# scan item prologue de-serialised (all constant and fragment loads in flight at once); sign flips folded into cvt neg modifiers; dead zero-inits before full-row DPP rotations removed in GEMM1 epilogue
# speedup vs baseline: 1.0071x; 1.0036x over previous
.LBB0_100:
	s_and_b32 s48, s82, 0x7ffffffc
	v_lshl_add_u32 v136, s82, 8, v184
	s_cmp_eq_u32 s48, 28
	v_mov_b32_e32 v137, v3
	s_mov_b64 s[48:49], -1
	s_cbranch_scc1 .LBB0_150
	v_readlane_b32 s48, v255, 15
	v_readlane_b32 s49, v255, 16
	s_load_dwordx2 s[48:49], s[48:49], 0x38


	s_waitcnt lgkmcnt(0)
	v_lshl_add_u64 v[138:139], v[136:137], 2, s[48:49]
	global_load_dwordx4 v[140:143], v[138:139], off
	global_load_dwordx4 v[132:135], v[138:139], off offset:16
	v_mov_b32_e32 v146, v3
	v_mov_b32_e32 v147, v3
	v_mov_b32_e32 v166, v3
	v_mov_b32_e32 v167, v3
	v_mov_b32_dpp v144, v112 row_ror:15 row_mask:0xf bank_mask:0xf
	v_mov_b32_dpp v145, v113 row_ror:15 row_mask:0xf bank_mask:0xf
	v_mov_b32_dpp v164, v114 row_ror:15 row_mask:0xf bank_mask:0xf
	v_mov_b32_dpp v165, v115 row_ror:15 row_mask:0xf bank_mask:0xf
	v_mov_b32_dpp v146, v128 row_shr:1 row_mask:0xf bank_mask:0xf
	v_mov_b32_dpp v147, v129 row_shr:1 row_mask:0xf bank_mask:0xf
	v_mov_b32_dpp v166, v130 row_shr:1 row_mask:0xf bank_mask:0xf
	v_mov_b32_dpp v167, v131 row_shr:1 row_mask:0xf bank_mask:0xf
	v_mov_b32_dpp v144, v128 row_shl:1 row_mask:0xf bank_mask:0xf
	v_mov_b32_dpp v145, v129 row_shl:1 row_mask:0xf bank_mask:0xf
	v_mov_b32_dpp v164, v130 row_shl:1 row_mask:0xf bank_mask:0xf
	v_mov_b32_dpp v165, v131 row_shl:1 row_mask:0xf bank_mask:0xf
	s_cmp_eq_u32 s82, 32
	v_pk_add_f32 v[146:147], v[146:147], v[144:145]
	v_pk_add_f32 v[166:167], v[166:167], v[164:165]
	s_cselect_b64 s[60:61], -1, 0
	s_and_b64 vcc, exec, s[60:61]
	s_waitcnt vmcnt(0)
	v_pk_mul_f32 v[168:169], v[142:143], 0.5 op_sel_hi:[1,0]
	v_pk_mul_f32 v[170:171], v[140:141], 0.5 op_sel_hi:[1,0]
	v_sub_f32_e32 v165, 1.0, v143
	v_sub_f32_e32 v164, 1.0, v142
	v_sub_f32_e32 v145, 1.0, v141
	v_sub_f32_e32 v144, 1.0, v140
	v_pk_mul_f32 v[140:141], v[168:169], v[166:167]
	v_pk_mul_f32 v[142:143], v[170:171], v[146:147]
	v_pk_fma_f32 v[172:173], v[130:131], v[164:165], v[140:141]
	v_pk_fma_f32 v[174:175], v[128:129], v[144:145], v[142:143]
	s_cbranch_vccz .LBB0_103
	v_mul_f32_e32 v2, 0x4038aa3b, v174
	v_exp_f32_e32 v2, v2
	v_mul_f32_e32 v140, 0x4038aa3b, v175
	v_mul_f32_e32 v141, 0x4038aa3b, v172
	v_exp_f32_e32 v142, v140
	v_add_f32_e32 v2, 1.0, v2
	v_rcp_f32_e32 v140, v2
	v_exp_f32_e32 v2, v141
	v_mul_f32_e32 v141, 0x4038aa3b, v173
	v_exp_f32_e32 v141, v141
	v_add_f32_e32 v146, 1.0, v142
	v_add_f32_e32 v2, 1.0, v2
	v_rcp_f32_e32 v142, v2
	v_add_f32_e32 v2, 1.0, v141
	v_rcp_f32_e32 v143, v2
	v_rcp_f32_e32 v141, v146
	v_pk_fma_f32 v[172:173], v[142:143], -2.0, 1.0 op_sel_hi:[1,0,0]
	v_pk_fma_f32 v[174:175], v[140:141], -2.0, 1.0 op_sel_hi:[1,0,0]
.LBB0_103:


	v_mov_b32_dpp v176, v84 row_ror:15 row_mask:0xf bank_mask:0xf
	v_mov_b32_e32 v178, v3
	v_mov_b32_dpp v177, v85 row_ror:15 row_mask:0xf bank_mask:0xf
	v_mov_b32_e32 v179, v3
	v_mov_b32_dpp v180, v86 row_ror:15 row_mask:0xf bank_mask:0xf
	v_mov_b32_e32 v186, v3
	v_mov_b32_dpp v181, v87 row_ror:15 row_mask:0xf bank_mask:0xf
	v_mov_b32_e32 v187, v3
	v_mov_b32_dpp v178, v120 row_shr:1 row_mask:0xf bank_mask:0xf
	v_mov_b32_dpp v176, v120 row_shl:1 row_mask:0xf bank_mask:0xf
	v_mov_b32_dpp v179, v121 row_shr:1 row_mask:0xf bank_mask:0xf
	v_mov_b32_dpp v177, v121 row_shl:1 row_mask:0xf bank_mask:0xf
	v_mov_b32_dpp v186, v122 row_shr:1 row_mask:0xf bank_mask:0xf
	v_mov_b32_dpp v180, v122 row_shl:1 row_mask:0xf bank_mask:0xf
	v_mov_b32_dpp v187, v123 row_shr:1 row_mask:0xf bank_mask:0xf
	v_mov_b32_dpp v181, v123 row_shl:1 row_mask:0xf bank_mask:0xf
	v_sub_f32_e32 v143, 1.0, v135
	v_sub_f32_e32 v142, 1.0, v134
	v_sub_f32_e32 v141, 1.0, v133
	v_sub_f32_e32 v140, 1.0, v132
	v_pk_mul_f32 v[146:147], v[134:135], 0.5 op_sel_hi:[1,0]
	v_pk_mul_f32 v[166:167], v[132:133], 0.5 op_sel_hi:[1,0]
	v_pk_add_f32 v[132:133], v[186:187], v[180:181]
	v_pk_add_f32 v[134:135], v[178:179], v[176:177]
	v_pk_mul_f32 v[132:133], v[146:147], v[132:133]
	v_pk_mul_f32 v[134:135], v[166:167], v[134:135]
	v_cndmask_b32_e64 v2, 0, 1, s[60:61]
	v_pk_fma_f32 v[132:133], v[122:123], v[142:143], v[132:133]
	v_cmp_ne_u32_e64 s[48:49], 1, v2
	s_andn2_b64 vcc, exec, s[60:61]
	v_pk_fma_f32 v[134:135], v[120:121], v[140:141], v[134:135]
	s_cbranch_vccnz .LBB0_105
	v_mul_f32_e32 v2, 0x4038aa3b, v134
	v_exp_f32_e32 v2, v2
	v_mul_f32_e32 v134, 0x4038aa3b, v135
	v_mul_f32_e32 v132, 0x4038aa3b, v132
	v_exp_f32_e32 v135, v134
	v_add_f32_e32 v2, 1.0, v2
	v_rcp_f32_e32 v134, v2
	v_exp_f32_e32 v2, v132
	v_mul_f32_e32 v132, 0x4038aa3b, v133
	v_exp_f32_e32 v133, v132
	v_add_f32_e32 v135, 1.0, v135
	v_add_f32_e32 v2, 1.0, v2
	v_rcp_f32_e32 v132, v2
	v_add_f32_e32 v2, 1.0, v133
	v_rcp_f32_e32 v133, v2
	v_rcp_f32_e32 v135, v135
	v_pk_fma_f32 v[132:133], v[132:133], -2.0, 1.0 op_sel_hi:[1,0,0]
	v_pk_fma_f32 v[134:135], v[134:135], -2.0, 1.0 op_sel_hi:[1,0,0]

.LBB0_109:


	v_mov_b32_dpp v174, v120 row_ror:1 row_mask:0xf bank_mask:0xf
	v_mov_b32_dpp v176, v72 row_ror:15 row_mask:0xf bank_mask:0xf
	v_mov_b32_dpp v175, v121 row_ror:1 row_mask:0xf bank_mask:0xf
	v_mov_b32_dpp v177, v73 row_ror:15 row_mask:0xf bank_mask:0xf
	v_mov_b32_dpp v178, v122 row_ror:1 row_mask:0xf bank_mask:0xf
	v_mov_b32_dpp v180, v74 row_ror:15 row_mask:0xf bank_mask:0xf
	v_mov_b32_dpp v179, v123 row_ror:1 row_mask:0xf bank_mask:0xf
	v_mov_b32_dpp v181, v75 row_ror:15 row_mask:0xf bank_mask:0xf
	v_mov_b32_dpp v174, v84 row_shr:1 row_mask:0xf bank_mask:0xf
	v_mov_b32_dpp v176, v84 row_shl:1 row_mask:0xf bank_mask:0xf
	v_mov_b32_dpp v175, v85 row_shr:1 row_mask:0xf bank_mask:0xf
	v_mov_b32_dpp v177, v85 row_shl:1 row_mask:0xf bank_mask:0xf
	v_mov_b32_dpp v178, v86 row_shr:1 row_mask:0xf bank_mask:0xf
	v_mov_b32_dpp v180, v86 row_shl:1 row_mask:0xf bank_mask:0xf
	v_mov_b32_dpp v179, v87 row_shr:1 row_mask:0xf bank_mask:0xf
	v_mov_b32_dpp v181, v87 row_shl:1 row_mask:0xf bank_mask:0xf
	v_pk_add_f32 v[178:179], v[178:179], v[180:181]
	v_pk_add_f32 v[174:175], v[174:175], v[176:177]
	s_and_b64 vcc, exec, s[48:49]
	v_pk_mul_f32 v[176:177], v[166:167], v[174:175]
	v_pk_mul_f32 v[174:175], v[146:147], v[178:179]
	v_pk_fma_f32 v[176:177], v[84:85], v[140:141], v[176:177]
	v_pk_fma_f32 v[174:175], v[86:87], v[142:143], v[174:175]
	s_cbranch_vccnz .LBB0_111
	v_mul_f32_e32 v2, 0x4038aa3b, v176
	v_exp_f32_e32 v2, v2
	v_mul_f32_e32 v176, 0x4038aa3b, v177
	v_mul_f32_e32 v174, 0x4038aa3b, v174
	v_exp_f32_e32 v177, v176
	v_add_f32_e32 v2, 1.0, v2
	v_rcp_f32_e32 v176, v2
	v_exp_f32_e32 v2, v174
	v_mul_f32_e32 v174, 0x4038aa3b, v175
	v_exp_f32_e32 v175, v174
	v_add_f32_e32 v177, 1.0, v177
	v_add_f32_e32 v2, 1.0, v2
	v_rcp_f32_e32 v174, v2
	v_add_f32_e32 v2, 1.0, v175
	v_rcp_f32_e32 v175, v2
	v_rcp_f32_e32 v177, v177
	v_pk_fma_f32 v[174:175], v[174:175], -2.0, 1.0 op_sel_hi:[1,0,0]
	v_pk_fma_f32 v[176:177], v[176:177], -2.0, 1.0 op_sel_hi:[1,0,0]
.LBB0_111:
	v_cvt_pk_bf16_f32 v179, v134, v135
	v_or_b32_e32 v2, 16, v162
	v_mov_b64_e32 v[134:135], s[50:51]
	v_mad_i64_i32 v[134:135], s[84:85], v2, s62, v[134:135]
	v_lshl_add_u64 v[134:135], v[134:135], 0, s[14:15]
	v_cvt_pk_bf16_f32 v178, v172, v173
	v_cvt_pk_bf16_f32 v180, v176, v177
	v_cvt_pk_bf16_f32 v181, v174, v175
	v_lshl_add_u64 v[172:173], v[136:137], 1, v[134:135]
	global_store_dwordx4 v[172:173], v[178:181], off


	s_nop 0
	v_mov_b32_dpp v172, v112 row_ror:1 row_mask:0xf bank_mask:0xf
	v_mov_b32_dpp v174, v96 row_ror:15 row_mask:0xf bank_mask:0xf
	v_mov_b32_dpp v173, v113 row_ror:1 row_mask:0xf bank_mask:0xf
	v_mov_b32_dpp v175, v97 row_ror:15 row_mask:0xf bank_mask:0xf
	v_mov_b32_dpp v176, v114 row_ror:1 row_mask:0xf bank_mask:0xf
	v_mov_b32_dpp v178, v98 row_ror:15 row_mask:0xf bank_mask:0xf
	v_mov_b32_dpp v177, v115 row_ror:1 row_mask:0xf bank_mask:0xf
	v_mov_b32_dpp v179, v99 row_ror:15 row_mask:0xf bank_mask:0xf
	v_mov_b32_dpp v172, v104 row_shr:1 row_mask:0xf bank_mask:0xf
	v_mov_b32_dpp v174, v104 row_shl:1 row_mask:0xf bank_mask:0xf
	v_mov_b32_dpp v173, v105 row_shr:1 row_mask:0xf bank_mask:0xf
	v_mov_b32_dpp v175, v105 row_shl:1 row_mask:0xf bank_mask:0xf
	v_mov_b32_dpp v176, v106 row_shr:1 row_mask:0xf bank_mask:0xf
	v_mov_b32_dpp v178, v106 row_shl:1 row_mask:0xf bank_mask:0xf
	v_mov_b32_dpp v177, v107 row_shr:1 row_mask:0xf bank_mask:0xf
	v_mov_b32_dpp v179, v107 row_shl:1 row_mask:0xf bank_mask:0xf
	v_pk_add_f32 v[176:177], v[176:177], v[178:179]
	v_pk_add_f32 v[172:173], v[172:173], v[174:175]
	s_and_b64 vcc, exec, s[48:49]
	v_pk_mul_f32 v[174:175], v[170:171], v[172:173]
	v_pk_mul_f32 v[172:173], v[168:169], v[176:177]
	v_pk_fma_f32 v[174:175], v[104:105], v[144:145], v[174:175]
	v_pk_fma_f32 v[172:173], v[106:107], v[164:165], v[172:173]
	s_cbranch_vccnz .LBB0_113
	v_mul_f32_e32 v2, 0x4038aa3b, v174
	v_exp_f32_e32 v2, v2
	v_mul_f32_e32 v174, 0x4038aa3b, v175
	v_mul_f32_e32 v172, 0x4038aa3b, v172
	v_exp_f32_e32 v175, v174
	v_add_f32_e32 v2, 1.0, v2
	v_rcp_f32_e32 v174, v2
	v_exp_f32_e32 v2, v172
	v_mul_f32_e32 v172, 0x4038aa3b, v173
	v_exp_f32_e32 v173, v172
	v_add_f32_e32 v175, 1.0, v175
	v_add_f32_e32 v2, 1.0, v2
	v_rcp_f32_e32 v172, v2
	v_add_f32_e32 v2, 1.0, v173
	v_rcp_f32_e32 v173, v2
	v_rcp_f32_e32 v175, v175
	v_pk_fma_f32 v[172:173], v[172:173], -2.0, 1.0 op_sel_hi:[1,0,0]
	v_pk_fma_f32 v[174:175], v[174:175], -2.0, 1.0 op_sel_hi:[1,0,0]
.LBB0_113:


	v_mov_b32_dpp v176, v84 row_ror:1 row_mask:0xf bank_mask:0xf
	v_mov_b32_dpp v178, v88 row_ror:15 row_mask:0xf bank_mask:0xf
	v_mov_b32_dpp v177, v85 row_ror:1 row_mask:0xf bank_mask:0xf
	v_mov_b32_dpp v179, v89 row_ror:15 row_mask:0xf bank_mask:0xf
	v_mov_b32_dpp v180, v86 row_ror:1 row_mask:0xf bank_mask:0xf
	v_mov_b32_dpp v186, v90 row_ror:15 row_mask:0xf bank_mask:0xf
	v_mov_b32_dpp v181, v87 row_ror:1 row_mask:0xf bank_mask:0xf
	v_mov_b32_dpp v187, v91 row_ror:15 row_mask:0xf bank_mask:0xf
	v_mov_b32_dpp v176, v72 row_shr:1 row_mask:0xf bank_mask:0xf
	v_mov_b32_dpp v178, v72 row_shl:1 row_mask:0xf bank_mask:0xf
	v_mov_b32_dpp v177, v73 row_shr:1 row_mask:0xf bank_mask:0xf
	v_mov_b32_dpp v179, v73 row_shl:1 row_mask:0xf bank_mask:0xf
	v_mov_b32_dpp v180, v74 row_shr:1 row_mask:0xf bank_mask:0xf
	v_mov_b32_dpp v186, v74 row_shl:1 row_mask:0xf bank_mask:0xf
	v_mov_b32_dpp v181, v75 row_shr:1 row_mask:0xf bank_mask:0xf
	v_mov_b32_dpp v187, v75 row_shl:1 row_mask:0xf bank_mask:0xf
	v_pk_add_f32 v[180:181], v[180:181], v[186:187]
	v_pk_add_f32 v[176:177], v[176:177], v[178:179]
	s_and_b64 vcc, exec, s[48:49]
	v_pk_mul_f32 v[178:179], v[166:167], v[176:177]
	v_pk_mul_f32 v[176:177], v[146:147], v[180:181]
	v_pk_fma_f32 v[178:179], v[72:73], v[140:141], v[178:179]
	v_pk_fma_f32 v[176:177], v[74:75], v[142:143], v[176:177]
	s_cbranch_vccnz .LBB0_115
	v_mul_f32_e32 v2, 0x4038aa3b, v178
	v_exp_f32_e32 v2, v2
	v_mul_f32_e32 v178, 0x4038aa3b, v179
	v_mul_f32_e32 v176, 0x4038aa3b, v176
	v_exp_f32_e32 v179, v178
	v_add_f32_e32 v2, 1.0, v2
	v_rcp_f32_e32 v178, v2
	v_exp_f32_e32 v2, v176
	v_mul_f32_e32 v176, 0x4038aa3b, v177
	v_exp_f32_e32 v177, v176
	v_add_f32_e32 v179, 1.0, v179
	v_add_f32_e32 v2, 1.0, v2
	v_rcp_f32_e32 v176, v2
	v_add_f32_e32 v2, 1.0, v177
	v_rcp_f32_e32 v177, v2
	v_rcp_f32_e32 v179, v179
	v_pk_fma_f32 v[176:177], v[176:177], -2.0, 1.0 op_sel_hi:[1,0,0]
	v_pk_fma_f32 v[178:179], v[178:179], -2.0, 1.0 op_sel_hi:[1,0,0]
.LBB0_115:
	v_cvt_pk_bf16_f32 v187, v172, v173
	v_or_b32_e32 v2, 32, v162
	v_mov_b64_e32 v[172:173], s[50:51]
	v_mad_i64_i32 v[172:173], s[84:85], v2, s62, v[172:173]
	v_lshl_add_u64 v[172:173], v[172:173], 0, s[14:15]
	v_cvt_pk_bf16_f32 v186, v174, v175
	v_cvt_pk_bf16_f32 v188, v178, v179
	v_cvt_pk_bf16_f32 v189, v176, v177
	v_lshl_add_u64 v[174:175], v[136:137], 1, v[172:173]
	global_store_dwordx4 v[174:175], v[186:189], off


	s_nop 0
	v_mov_b32_dpp v174, v104 row_ror:1 row_mask:0xf bank_mask:0xf
	v_mov_b32_e32 v176, v3
	v_mov_b32_dpp v175, v105 row_ror:1 row_mask:0xf bank_mask:0xf
	v_mov_b32_e32 v177, v3
	v_mov_b32_dpp v178, v106 row_ror:1 row_mask:0xf bank_mask:0xf
	v_mov_b32_e32 v180, v3
	v_mov_b32_dpp v179, v107 row_ror:1 row_mask:0xf bank_mask:0xf
	v_mov_b32_e32 v181, v3
	v_mov_b32_dpp v174, v96 row_shr:1 row_mask:0xf bank_mask:0xf
	v_mov_b32_dpp v176, v96 row_shl:1 row_mask:0xf bank_mask:0xf
	v_mov_b32_dpp v175, v97 row_shr:1 row_mask:0xf bank_mask:0xf
	v_mov_b32_dpp v177, v97 row_shl:1 row_mask:0xf bank_mask:0xf
	v_mov_b32_dpp v178, v98 row_shr:1 row_mask:0xf bank_mask:0xf
	v_mov_b32_dpp v180, v98 row_shl:1 row_mask:0xf bank_mask:0xf
	v_mov_b32_dpp v179, v99 row_shr:1 row_mask:0xf bank_mask:0xf
	v_mov_b32_dpp v181, v99 row_shl:1 row_mask:0xf bank_mask:0xf
	v_pk_add_f32 v[178:179], v[178:179], v[180:181]
	v_pk_add_f32 v[174:175], v[174:175], v[176:177]
	v_pk_mul_f32 v[168:169], v[168:169], v[178:179]
	v_pk_mul_f32 v[170:171], v[170:171], v[174:175]
	v_pk_fma_f32 v[164:165], v[98:99], v[164:165], v[168:169]
	s_and_b64 vcc, exec, s[48:49]
	v_pk_fma_f32 v[144:145], v[96:97], v[144:145], v[170:171]
	s_cbranch_vccnz .LBB0_117
	v_mul_f32_e32 v2, 0x4038aa3b, v144
	v_exp_f32_e32 v2, v2
	v_mul_f32_e32 v144, 0x4038aa3b, v145
	v_mul_f32_e32 v145, 0x4038aa3b, v164
	v_exp_f32_e32 v164, v144
	v_add_f32_e32 v2, 1.0, v2
	v_rcp_f32_e32 v144, v2
	v_exp_f32_e32 v2, v145
	v_mul_f32_e32 v145, 0x4038aa3b, v165
	v_exp_f32_e32 v145, v145
	v_add_f32_e32 v168, 1.0, v164
	v_add_f32_e32 v2, 1.0, v2
	v_rcp_f32_e32 v164, v2
	v_add_f32_e32 v2, 1.0, v145
	v_rcp_f32_e32 v165, v2
	v_rcp_f32_e32 v145, v168
	v_pk_fma_f32 v[164:165], v[164:165], -2.0, 1.0 op_sel_hi:[1,0,0]
	v_pk_fma_f32 v[144:145], v[144:145], -2.0, 1.0 op_sel_hi:[1,0,0]
.LBB0_117:


	v_mov_b32_dpp v168, v72 row_ror:1 row_mask:0xf bank_mask:0xf
	v_mov_b32_e32 v170, v3
	v_mov_b32_dpp v169, v73 row_ror:1 row_mask:0xf bank_mask:0xf
	v_mov_b32_e32 v171, v3
	v_mov_b32_dpp v174, v74 row_ror:1 row_mask:0xf bank_mask:0xf
	v_mov_b32_e32 v176, v3
	v_mov_b32_dpp v175, v75 row_ror:1 row_mask:0xf bank_mask:0xf
	v_mov_b32_e32 v177, v3
	v_mov_b32_dpp v168, v88 row_shr:1 row_mask:0xf bank_mask:0xf
	v_mov_b32_dpp v170, v88 row_shl:1 row_mask:0xf bank_mask:0xf
	v_mov_b32_dpp v169, v89 row_shr:1 row_mask:0xf bank_mask:0xf
	v_mov_b32_dpp v171, v89 row_shl:1 row_mask:0xf bank_mask:0xf
	v_mov_b32_dpp v174, v90 row_shr:1 row_mask:0xf bank_mask:0xf
	v_mov_b32_dpp v176, v90 row_shl:1 row_mask:0xf bank_mask:0xf
	v_mov_b32_dpp v175, v91 row_shr:1 row_mask:0xf bank_mask:0xf
	v_mov_b32_dpp v177, v91 row_shl:1 row_mask:0xf bank_mask:0xf
	v_pk_add_f32 v[174:175], v[174:175], v[176:177]
	v_pk_add_f32 v[168:169], v[168:169], v[170:171]
	v_pk_mul_f32 v[146:147], v[146:147], v[174:175]
	v_pk_mul_f32 v[166:167], v[166:167], v[168:169]
	v_pk_fma_f32 v[142:143], v[90:91], v[142:143], v[146:147]
	s_and_b64 vcc, exec, s[48:49]
	v_pk_fma_f32 v[140:141], v[88:89], v[140:141], v[166:167]
	s_cbranch_vccnz .LBB0_119
	v_mul_f32_e32 v2, 0x4038aa3b, v140
	v_exp_f32_e32 v2, v2
	v_mul_f32_e32 v140, 0x4038aa3b, v141
	v_mul_f32_e32 v141, 0x4038aa3b, v142
	v_exp_f32_e32 v142, v140
	v_add_f32_e32 v2, 1.0, v2
	v_rcp_f32_e32 v140, v2
	v_exp_f32_e32 v2, v141
	v_mul_f32_e32 v141, 0x4038aa3b, v143
	v_exp_f32_e32 v141, v141
	v_add_f32_e32 v146, 1.0, v142
	v_add_f32_e32 v2, 1.0, v2
	v_rcp_f32_e32 v142, v2
	v_add_f32_e32 v2, 1.0, v141
	v_rcp_f32_e32 v143, v2
	v_rcp_f32_e32 v141, v146
	v_pk_fma_f32 v[142:143], v[142:143], -2.0, 1.0 op_sel_hi:[1,0,0]
	v_pk_fma_f32 v[140:141], v[140:141], -2.0, 1.0 op_sel_hi:[1,0,0]

.LBB0_123:
	s_or_b64 exec, exec, vcc
	v_mov_b32_e32 v132, v3
	v_mov_b32_e32 v140, v3
	v_mov_b32_e32 v133, v3
	v_mov_b32_e32 v141, v3
	v_mov_b32_e32 v180, v3
	v_mov_b32_e32 v186, v3
	v_mov_b32_e32 v181, v3
	v_mov_b32_e32 v187, v3
	v_mov_b32_dpp v132, v124 row_ror:1 row_mask:0xf bank_mask:0xf
	v_mov_b32_dpp v140, v100 row_ror:15 row_mask:0xf bank_mask:0xf
	v_mov_b32_dpp v133, v125 row_ror:1 row_mask:0xf bank_mask:0xf
	v_mov_b32_dpp v141, v101 row_ror:15 row_mask:0xf bank_mask:0xf
	v_mov_b32_dpp v180, v126 row_ror:1 row_mask:0xf bank_mask:0xf
	v_mov_b32_dpp v186, v102 row_ror:15 row_mask:0xf bank_mask:0xf
	v_mov_b32_dpp v181, v127 row_ror:1 row_mask:0xf bank_mask:0xf
	v_mov_b32_dpp v187, v103 row_ror:15 row_mask:0xf bank_mask:0xf
	v_mov_b32_dpp v132, v108 row_shr:1 row_mask:0xf bank_mask:0xf
	v_mov_b32_dpp v140, v108 row_shl:1 row_mask:0xf bank_mask:0xf
	v_mov_b32_dpp v133, v109 row_shr:1 row_mask:0xf bank_mask:0xf
	v_mov_b32_dpp v141, v109 row_shl:1 row_mask:0xf bank_mask:0xf
	v_mov_b32_dpp v180, v110 row_shr:1 row_mask:0xf bank_mask:0xf
	v_mov_b32_dpp v186, v110 row_shl:1 row_mask:0xf bank_mask:0xf
	v_mov_b32_dpp v181, v111 row_shr:1 row_mask:0xf bank_mask:0xf
	v_mov_b32_dpp v187, v111 row_shl:1 row_mask:0xf bank_mask:0xf
	v_pk_add_f32 v[180:181], v[180:181], v[186:187]
	v_pk_add_f32 v[132:133], v[132:133], v[140:141]
	v_pk_mul_f32 v[140:141], v[176:177], v[180:181]
	v_pk_mul_f32 v[132:133], v[178:179], v[132:133]
	v_pk_fma_f32 v[140:141], v[110:111], v[170:171], v[140:141]
	v_pk_fma_f32 v[132:133], v[108:109], v[174:175], v[132:133]


	v_cvt_pk_bf16_f32 v186, v132, v133
	v_cvt_pk_bf16_f32 v187, v140, v141


	v_mov_b32_dpp v180, v118 row_ror:1 row_mask:0xf bank_mask:0xf
	v_mov_b32_dpp v188, v70 row_ror:15 row_mask:0xf bank_mask:0xf
	v_mov_b32_dpp v181, v119 row_ror:1 row_mask:0xf bank_mask:0xf
	v_mov_b32_dpp v189, v71 row_ror:15 row_mask:0xf bank_mask:0xf
	v_mov_b32_dpp v132, v116 row_ror:1 row_mask:0xf bank_mask:0xf
	v_mov_b32_dpp v140, v68 row_ror:15 row_mask:0xf bank_mask:0xf
	v_mov_b32_dpp v133, v117 row_ror:1 row_mask:0xf bank_mask:0xf
	v_mov_b32_dpp v141, v69 row_ror:15 row_mask:0xf bank_mask:0xf
	v_mov_b32_dpp v180, v78 row_shr:1 row_mask:0xf bank_mask:0xf
	v_mov_b32_dpp v188, v78 row_shl:1 row_mask:0xf bank_mask:0xf
	v_mov_b32_dpp v181, v79 row_shr:1 row_mask:0xf bank_mask:0xf
	v_mov_b32_dpp v189, v79 row_shl:1 row_mask:0xf bank_mask:0xf
	v_mov_b32_dpp v132, v76 row_shr:1 row_mask:0xf bank_mask:0xf
	v_mov_b32_dpp v140, v76 row_shl:1 row_mask:0xf bank_mask:0xf
	v_mov_b32_dpp v133, v77 row_shr:1 row_mask:0xf bank_mask:0xf
	v_mov_b32_dpp v141, v77 row_shl:1 row_mask:0xf bank_mask:0xf
	v_pk_add_f32 v[180:181], v[180:181], v[188:189]
	v_pk_add_f32 v[132:133], v[132:133], v[140:141]
	v_pk_mul_f32 v[140:141], v[166:167], v[180:181]
	v_pk_mul_f32 v[132:133], v[168:169], v[132:133]
	v_pk_fma_f32 v[140:141], v[78:79], v[146:147], v[140:141]
	v_pk_fma_f32 v[132:133], v[76:77], v[164:165], v[132:133]
	v_cvt_pk_bf16_f32 v189, v140, v141
	v_lshlrev_b64 v[140:141], 1, v[2:3]
	v_cvt_pk_bf16_f32 v188, v132, v133
	v_lshl_add_u64 v[132:133], v[134:135], 0, v[140:141]
	global_store_dwordx4 v[132:133], v[186:189], off


	s_nop 0
	v_mov_b32_dpp v132, v108 row_ror:1 row_mask:0xf bank_mask:0xf
	v_mov_b32_dpp v134, v92 row_ror:15 row_mask:0xf bank_mask:0xf
	v_mov_b32_dpp v133, v109 row_ror:1 row_mask:0xf bank_mask:0xf
	v_mov_b32_dpp v135, v93 row_ror:15 row_mask:0xf bank_mask:0xf
	v_mov_b32_dpp v180, v110 row_ror:1 row_mask:0xf bank_mask:0xf
	v_mov_b32_dpp v186, v94 row_ror:15 row_mask:0xf bank_mask:0xf
	v_mov_b32_dpp v181, v111 row_ror:1 row_mask:0xf bank_mask:0xf
	v_mov_b32_dpp v187, v95 row_ror:15 row_mask:0xf bank_mask:0xf
	v_mov_b32_dpp v132, v100 row_shr:1 row_mask:0xf bank_mask:0xf
	v_mov_b32_dpp v134, v100 row_shl:1 row_mask:0xf bank_mask:0xf
	v_mov_b32_dpp v133, v101 row_shr:1 row_mask:0xf bank_mask:0xf
	v_mov_b32_dpp v135, v101 row_shl:1 row_mask:0xf bank_mask:0xf
	v_mov_b32_dpp v180, v102 row_shr:1 row_mask:0xf bank_mask:0xf
	v_mov_b32_dpp v186, v102 row_shl:1 row_mask:0xf bank_mask:0xf
	v_mov_b32_dpp v181, v103 row_shr:1 row_mask:0xf bank_mask:0xf
	v_mov_b32_dpp v187, v103 row_shl:1 row_mask:0xf bank_mask:0xf
	v_pk_add_f32 v[180:181], v[180:181], v[186:187]
	v_pk_add_f32 v[132:133], v[132:133], v[134:135]
	v_pk_mul_f32 v[134:135], v[176:177], v[180:181]
	v_pk_mul_f32 v[132:133], v[178:179], v[132:133]
	v_pk_fma_f32 v[134:135], v[102:103], v[170:171], v[134:135]
	v_pk_fma_f32 v[132:133], v[100:101], v[174:175], v[132:133]

	v_cvt_pk_bf16_f32 v132, v132, v133
	v_cvt_pk_bf16_f32 v133, v134, v135


	v_mov_b32_dpp v134, v76 row_ror:1 row_mask:0xf bank_mask:0xf
	v_mov_b32_dpp v180, v80 row_ror:15 row_mask:0xf bank_mask:0xf
	v_mov_b32_dpp v135, v77 row_ror:1 row_mask:0xf bank_mask:0xf
	v_mov_b32_dpp v181, v81 row_ror:15 row_mask:0xf bank_mask:0xf
	v_mov_b32_dpp v186, v78 row_ror:1 row_mask:0xf bank_mask:0xf
	v_mov_b32_dpp v188, v82 row_ror:15 row_mask:0xf bank_mask:0xf
	v_mov_b32_dpp v187, v79 row_ror:1 row_mask:0xf bank_mask:0xf
	v_mov_b32_dpp v189, v83 row_ror:15 row_mask:0xf bank_mask:0xf
	v_mov_b32_dpp v134, v68 row_shr:1 row_mask:0xf bank_mask:0xf
	v_mov_b32_dpp v180, v68 row_shl:1 row_mask:0xf bank_mask:0xf
	v_mov_b32_dpp v135, v69 row_shr:1 row_mask:0xf bank_mask:0xf
	v_mov_b32_dpp v181, v69 row_shl:1 row_mask:0xf bank_mask:0xf
	v_mov_b32_dpp v186, v70 row_shr:1 row_mask:0xf bank_mask:0xf
	v_mov_b32_dpp v188, v70 row_shl:1 row_mask:0xf bank_mask:0xf
	v_mov_b32_dpp v187, v71 row_shr:1 row_mask:0xf bank_mask:0xf
	v_mov_b32_dpp v189, v71 row_shl:1 row_mask:0xf bank_mask:0xf
	v_pk_add_f32 v[186:187], v[186:187], v[188:189]
	v_pk_add_f32 v[134:135], v[134:135], v[180:181]
	v_pk_mul_f32 v[180:181], v[166:167], v[186:187]
	v_pk_mul_f32 v[134:135], v[168:169], v[134:135]
	v_pk_fma_f32 v[180:181], v[70:71], v[146:147], v[180:181]
	v_pk_fma_f32 v[134:135], v[68:69], v[164:165], v[134:135]
	v_lshl_add_u64 v[172:173], v[172:173], 0, v[140:141]
	v_cvt_pk_bf16_f32 v134, v134, v135
	v_cvt_pk_bf16_f32 v135, v180, v181
	global_store_dwordx4 v[172:173], v[132:135], off


	s_nop 1
	v_mov_b32_e32 v134, v3
	v_mov_b32_dpp v132, v100 row_ror:1 row_mask:0xf bank_mask:0xf
	v_mov_b32_dpp v133, v101 row_ror:1 row_mask:0xf bank_mask:0xf
	v_mov_b32_e32 v135, v3
	v_mov_b32_dpp v172, v102 row_ror:1 row_mask:0xf bank_mask:0xf
	v_mov_b32_e32 v180, v3
	v_mov_b32_dpp v173, v103 row_ror:1 row_mask:0xf bank_mask:0xf
	v_mov_b32_e32 v181, v3
	v_mov_b32_dpp v132, v92 row_shr:1 row_mask:0xf bank_mask:0xf
	v_mov_b32_dpp v134, v92 row_shl:1 row_mask:0xf bank_mask:0xf
	v_mov_b32_dpp v133, v93 row_shr:1 row_mask:0xf bank_mask:0xf
	v_mov_b32_dpp v135, v93 row_shl:1 row_mask:0xf bank_mask:0xf
	v_mov_b32_dpp v172, v94 row_shr:1 row_mask:0xf bank_mask:0xf
	v_mov_b32_dpp v180, v94 row_shl:1 row_mask:0xf bank_mask:0xf
	v_mov_b32_dpp v173, v95 row_shr:1 row_mask:0xf bank_mask:0xf
	v_mov_b32_dpp v181, v95 row_shl:1 row_mask:0xf bank_mask:0xf
	v_pk_add_f32 v[172:173], v[172:173], v[180:181]
	v_pk_add_f32 v[132:133], v[132:133], v[134:135]
	v_pk_mul_f32 v[134:135], v[176:177], v[172:173]
	v_pk_mul_f32 v[132:133], v[178:179], v[132:133]
	v_pk_fma_f32 v[134:135], v[94:95], v[170:171], v[134:135]
	v_pk_fma_f32 v[132:133], v[92:93], v[174:175], v[132:133]

	v_cvt_pk_bf16_f32 v132, v132, v133
	v_cvt_pk_bf16_f32 v133, v134, v135


	v_mov_b32_dpp v134, v68 row_ror:1 row_mask:0xf bank_mask:0xf
	v_mov_b32_e32 v170, v3
	v_mov_b32_dpp v135, v69 row_ror:1 row_mask:0xf bank_mask:0xf
	v_mov_b32_e32 v171, v3
	v_mov_b32_dpp v172, v70 row_ror:1 row_mask:0xf bank_mask:0xf
	v_mov_b32_e32 v174, v3
	v_mov_b32_dpp v173, v71 row_ror:1 row_mask:0xf bank_mask:0xf
	v_mov_b32_e32 v175, v3
	v_mov_b32_dpp v134, v80 row_shr:1 row_mask:0xf bank_mask:0xf
	v_mov_b32_dpp v170, v80 row_shl:1 row_mask:0xf bank_mask:0xf
	v_mov_b32_dpp v135, v81 row_shr:1 row_mask:0xf bank_mask:0xf
	v_mov_b32_dpp v171, v81 row_shl:1 row_mask:0xf bank_mask:0xf
	v_mov_b32_dpp v172, v82 row_shr:1 row_mask:0xf bank_mask:0xf
	v_mov_b32_dpp v174, v82 row_shl:1 row_mask:0xf bank_mask:0xf
	v_mov_b32_dpp v173, v83 row_shr:1 row_mask:0xf bank_mask:0xf
	v_mov_b32_dpp v175, v83 row_shl:1 row_mask:0xf bank_mask:0xf
	v_pk_add_f32 v[172:173], v[172:173], v[174:175]
	v_pk_add_f32 v[134:135], v[134:135], v[170:171]
	v_pk_mul_f32 v[166:167], v[166:167], v[172:173]
	v_pk_mul_f32 v[134:135], v[168:169], v[134:135]
	v_pk_fma_f32 v[146:147], v[82:83], v[146:147], v[166:167]
	v_pk_fma_f32 v[134:135], v[80:81], v[164:165], v[134:135]
	v_lshl_add_u64 v[144:145], v[144:145], 0, v[140:141]
	v_cvt_pk_bf16_f32 v134, v134, v135
	v_cvt_pk_bf16_f32 v135, v146, v147
	global_store_dwordx4 v[144:145], v[132:135], off
	s_and_saveexec_b64 s[60:61], s[40:41]
	s_cbranch_execz .LBB0_125
	v_mov_b64_e32 v[144:145], s[98:99]
	s_movk_i32 s29, 0x2200
	v_mad_u64_u32 v[144:145], s[84:85], v142, s29, v[144:145]
	v_mad_i32_i24 v145, v143, s29, v145
	v_cvt_pk_bf16_f32 v132, v92, v93
	v_cvt_pk_bf16_f32 v133, v94, v95
	v_cvt_pk_bf16_f32 v134, v80, v81
	v_cvt_pk_bf16_f32 v135, v82, v83
	v_lshl_add_u64 v[142:143], v[136:137], 1, v[144:145]
	global_store_dwordx4 v[142:143], v[132:135], off offset:256

.LBB0_127:


	v_mov_b32_dpp v178, v20 row_ror:15 row_mask:0xf bank_mask:0xf
	v_mov_b32_e32 v180, v3
	v_mov_b32_dpp v179, v21 row_ror:15 row_mask:0xf bank_mask:0xf
	v_mov_b32_e32 v181, v3
	v_mov_b32_dpp v186, v22 row_ror:15 row_mask:0xf bank_mask:0xf
	v_mov_b32_e32 v188, v3
	v_mov_b32_dpp v187, v23 row_ror:15 row_mask:0xf bank_mask:0xf
	v_mov_b32_e32 v189, v3
	v_mov_b32_dpp v180, v56 row_shr:1 row_mask:0xf bank_mask:0xf
	v_mov_b32_dpp v178, v56 row_shl:1 row_mask:0xf bank_mask:0xf
	v_mov_b32_dpp v181, v57 row_shr:1 row_mask:0xf bank_mask:0xf
	v_mov_b32_dpp v179, v57 row_shl:1 row_mask:0xf bank_mask:0xf
	v_mov_b32_dpp v188, v58 row_shr:1 row_mask:0xf bank_mask:0xf
	v_mov_b32_dpp v186, v58 row_shl:1 row_mask:0xf bank_mask:0xf
	v_mov_b32_dpp v189, v59 row_shr:1 row_mask:0xf bank_mask:0xf
	v_mov_b32_dpp v187, v59 row_shl:1 row_mask:0xf bank_mask:0xf
	s_waitcnt vmcnt(0)
	v_sub_f32_e32 v145, 1.0, v135
	v_sub_f32_e32 v144, 1.0, v134
	v_sub_f32_e32 v143, 1.0, v133
	v_sub_f32_e32 v142, 1.0, v132
	v_pk_mul_f32 v[146:147], v[134:135], 0.5 op_sel_hi:[1,0]
	v_pk_mul_f32 v[168:169], v[132:133], 0.5 op_sel_hi:[1,0]
	v_pk_add_f32 v[132:133], v[188:189], v[186:187]
	v_pk_add_f32 v[134:135], v[180:181], v[178:179]
	v_pk_mul_f32 v[132:133], v[146:147], v[132:133]
	v_pk_mul_f32 v[134:135], v[168:169], v[134:135]
	v_pk_fma_f32 v[132:133], v[58:59], v[144:145], v[132:133]
	s_and_b64 vcc, exec, s[48:49]
	v_pk_fma_f32 v[134:135], v[56:57], v[142:143], v[134:135]
	s_cbranch_vccnz .LBB0_129
	v_mul_f32_e32 v134, 0x4038aa3b, v134
	v_mul_f32_e32 v135, 0x4038aa3b, v135
	v_mul_f32_e32 v132, 0x4038aa3b, v132
	v_mul_f32_e32 v133, 0x4038aa3b, v133
	v_exp_f32_e32 v134, v134
	v_exp_f32_e32 v135, v135
	v_exp_f32_e32 v132, v132
	v_exp_f32_e32 v133, v133
	v_add_f32_e32 v134, 1.0, v134
	v_add_f32_e32 v135, 1.0, v135
	v_add_f32_e32 v132, 1.0, v132
	v_add_f32_e32 v133, 1.0, v133
	v_rcp_f32_e32 v134, v134
	v_rcp_f32_e32 v132, v132
	v_rcp_f32_e32 v133, v133
	v_rcp_f32_e32 v135, v135
	v_pk_fma_f32 v[132:133], v[132:133], -2.0, 1.0 op_sel_hi:[1,0,0]
	v_pk_fma_f32 v[134:135], v[134:135], -2.0, 1.0 op_sel_hi:[1,0,0]

.LBB0_133:


	v_mov_b32_dpp v176, v56 row_ror:1 row_mask:0xf bank_mask:0xf
	v_mov_b32_dpp v178, v8 row_ror:15 row_mask:0xf bank_mask:0xf
	v_mov_b32_dpp v177, v57 row_ror:1 row_mask:0xf bank_mask:0xf
	v_mov_b32_dpp v179, v9 row_ror:15 row_mask:0xf bank_mask:0xf
	v_mov_b32_dpp v180, v58 row_ror:1 row_mask:0xf bank_mask:0xf
	v_mov_b32_dpp v186, v10 row_ror:15 row_mask:0xf bank_mask:0xf
	v_mov_b32_dpp v181, v59 row_ror:1 row_mask:0xf bank_mask:0xf
	v_mov_b32_dpp v187, v11 row_ror:15 row_mask:0xf bank_mask:0xf
	v_mov_b32_dpp v176, v20 row_shr:1 row_mask:0xf bank_mask:0xf
	v_mov_b32_dpp v178, v20 row_shl:1 row_mask:0xf bank_mask:0xf
	v_mov_b32_dpp v177, v21 row_shr:1 row_mask:0xf bank_mask:0xf
	v_mov_b32_dpp v179, v21 row_shl:1 row_mask:0xf bank_mask:0xf
	v_mov_b32_dpp v180, v22 row_shr:1 row_mask:0xf bank_mask:0xf
	v_mov_b32_dpp v186, v22 row_shl:1 row_mask:0xf bank_mask:0xf
	v_mov_b32_dpp v181, v23 row_shr:1 row_mask:0xf bank_mask:0xf
	v_mov_b32_dpp v187, v23 row_shl:1 row_mask:0xf bank_mask:0xf
	v_pk_add_f32 v[180:181], v[180:181], v[186:187]
	v_pk_add_f32 v[176:177], v[176:177], v[178:179]
	s_and_b64 vcc, exec, s[48:49]
	v_pk_mul_f32 v[178:179], v[168:169], v[176:177]
	v_pk_mul_f32 v[176:177], v[146:147], v[180:181]
	v_pk_fma_f32 v[178:179], v[20:21], v[142:143], v[178:179]
	v_pk_fma_f32 v[176:177], v[22:23], v[144:145], v[176:177]
	s_cbranch_vccnz .LBB0_135
	v_mul_f32_e32 v178, 0x4038aa3b, v178
	v_mul_f32_e32 v179, 0x4038aa3b, v179
	v_mul_f32_e32 v176, 0x4038aa3b, v176
	v_mul_f32_e32 v177, 0x4038aa3b, v177
	v_exp_f32_e32 v178, v178
	v_exp_f32_e32 v179, v179
	v_exp_f32_e32 v176, v176
	v_exp_f32_e32 v177, v177
	v_add_f32_e32 v178, 1.0, v178
	v_add_f32_e32 v179, 1.0, v179
	v_add_f32_e32 v176, 1.0, v176
	v_add_f32_e32 v177, 1.0, v177
	v_rcp_f32_e32 v178, v178
	v_rcp_f32_e32 v176, v176
	v_rcp_f32_e32 v177, v177
	v_rcp_f32_e32 v179, v179
	v_pk_fma_f32 v[176:177], v[176:177], -2.0, 1.0 op_sel_hi:[1,0,0]
	v_pk_fma_f32 v[178:179], v[178:179], -2.0, 1.0 op_sel_hi:[1,0,0]
.LBB0_135:
	v_cvt_pk_bf16_f32 v186, v174, v175
	v_cvt_pk_bf16_f32 v187, v134, v135
	v_add_u32_e32 v174, 0x90, v162
	v_mov_b64_e32 v[134:135], s[50:51]
	v_mad_i64_i32 v[134:135], s[84:85], v174, s62, v[134:135]
	v_lshl_add_u64 v[134:135], v[134:135], 0, s[14:15]
	v_cvt_pk_bf16_f32 v188, v178, v179
	v_cvt_pk_bf16_f32 v189, v176, v177
	v_lshl_add_u64 v[174:175], v[136:137], 1, v[134:135]
	global_store_dwordx4 v[174:175], v[186:189], off


	s_nop 0
	v_mov_b32_dpp v174, v52 row_ror:1 row_mask:0xf bank_mask:0xf
	v_mov_b32_dpp v176, v32 row_ror:15 row_mask:0xf bank_mask:0xf
	v_mov_b32_dpp v175, v53 row_ror:1 row_mask:0xf bank_mask:0xf
	v_mov_b32_dpp v177, v33 row_ror:15 row_mask:0xf bank_mask:0xf
	v_mov_b32_dpp v178, v54 row_ror:1 row_mask:0xf bank_mask:0xf
	v_mov_b32_dpp v180, v34 row_ror:15 row_mask:0xf bank_mask:0xf
	v_mov_b32_dpp v179, v55 row_ror:1 row_mask:0xf bank_mask:0xf
	v_mov_b32_dpp v181, v35 row_ror:15 row_mask:0xf bank_mask:0xf
	v_mov_b32_dpp v174, v40 row_shr:1 row_mask:0xf bank_mask:0xf
	v_mov_b32_dpp v176, v40 row_shl:1 row_mask:0xf bank_mask:0xf
	v_mov_b32_dpp v175, v41 row_shr:1 row_mask:0xf bank_mask:0xf
	v_mov_b32_dpp v177, v41 row_shl:1 row_mask:0xf bank_mask:0xf
	v_mov_b32_dpp v178, v42 row_shr:1 row_mask:0xf bank_mask:0xf
	v_mov_b32_dpp v180, v42 row_shl:1 row_mask:0xf bank_mask:0xf
	v_mov_b32_dpp v179, v43 row_shr:1 row_mask:0xf bank_mask:0xf
	v_mov_b32_dpp v181, v43 row_shl:1 row_mask:0xf bank_mask:0xf
	v_pk_add_f32 v[178:179], v[178:179], v[180:181]
	v_pk_add_f32 v[174:175], v[174:175], v[176:177]
	s_and_b64 vcc, exec, s[48:49]
	v_pk_mul_f32 v[176:177], v[172:173], v[174:175]
	v_pk_mul_f32 v[174:175], v[170:171], v[178:179]
	v_pk_fma_f32 v[176:177], v[40:41], v[164:165], v[176:177]
	v_pk_fma_f32 v[174:175], v[42:43], v[166:167], v[174:175]
	s_cbranch_vccnz .LBB0_137
	v_mul_f32_e32 v176, 0x4038aa3b, v176
	v_mul_f32_e32 v177, 0x4038aa3b, v177
	v_mul_f32_e32 v174, 0x4038aa3b, v174
	v_mul_f32_e32 v175, 0x4038aa3b, v175
	v_exp_f32_e32 v176, v176
	v_exp_f32_e32 v177, v177
	v_exp_f32_e32 v174, v174
	v_exp_f32_e32 v175, v175
	v_add_f32_e32 v176, 1.0, v176
	v_add_f32_e32 v177, 1.0, v177
	v_add_f32_e32 v174, 1.0, v174
	v_add_f32_e32 v175, 1.0, v175
	v_rcp_f32_e32 v176, v176
	v_rcp_f32_e32 v174, v174
	v_rcp_f32_e32 v175, v175
	v_rcp_f32_e32 v177, v177
	v_pk_fma_f32 v[174:175], v[174:175], -2.0, 1.0 op_sel_hi:[1,0,0]
	v_pk_fma_f32 v[176:177], v[176:177], -2.0, 1.0 op_sel_hi:[1,0,0]
.LBB0_137:


	v_mov_b32_dpp v178, v20 row_ror:1 row_mask:0xf bank_mask:0xf
	v_mov_b32_dpp v180, v24 row_ror:15 row_mask:0xf bank_mask:0xf
	v_mov_b32_dpp v179, v21 row_ror:1 row_mask:0xf bank_mask:0xf
	v_mov_b32_dpp v181, v25 row_ror:15 row_mask:0xf bank_mask:0xf
	v_mov_b32_dpp v186, v22 row_ror:1 row_mask:0xf bank_mask:0xf
	v_mov_b32_dpp v188, v26 row_ror:15 row_mask:0xf bank_mask:0xf
	v_mov_b32_dpp v187, v23 row_ror:1 row_mask:0xf bank_mask:0xf
	v_mov_b32_dpp v189, v27 row_ror:15 row_mask:0xf bank_mask:0xf
	v_mov_b32_dpp v178, v8 row_shr:1 row_mask:0xf bank_mask:0xf
	v_mov_b32_dpp v180, v8 row_shl:1 row_mask:0xf bank_mask:0xf
	v_mov_b32_dpp v179, v9 row_shr:1 row_mask:0xf bank_mask:0xf
	v_mov_b32_dpp v181, v9 row_shl:1 row_mask:0xf bank_mask:0xf
	v_mov_b32_dpp v186, v10 row_shr:1 row_mask:0xf bank_mask:0xf
	v_mov_b32_dpp v188, v10 row_shl:1 row_mask:0xf bank_mask:0xf
	v_mov_b32_dpp v187, v11 row_shr:1 row_mask:0xf bank_mask:0xf
	v_mov_b32_dpp v189, v11 row_shl:1 row_mask:0xf bank_mask:0xf
	v_pk_add_f32 v[186:187], v[186:187], v[188:189]
	v_pk_add_f32 v[178:179], v[178:179], v[180:181]
	s_and_b64 vcc, exec, s[48:49]
	v_pk_mul_f32 v[180:181], v[168:169], v[178:179]
	v_pk_mul_f32 v[178:179], v[146:147], v[186:187]
	v_pk_fma_f32 v[180:181], v[8:9], v[142:143], v[180:181]
	v_pk_fma_f32 v[178:179], v[10:11], v[144:145], v[178:179]
	s_cbranch_vccnz .LBB0_139
	v_mul_f32_e32 v180, 0x4038aa3b, v180
	v_mul_f32_e32 v181, 0x4038aa3b, v181
	v_mul_f32_e32 v178, 0x4038aa3b, v178
	v_mul_f32_e32 v179, 0x4038aa3b, v179
	v_exp_f32_e32 v180, v180
	v_exp_f32_e32 v181, v181
	v_exp_f32_e32 v178, v178
	v_exp_f32_e32 v179, v179
	v_add_f32_e32 v180, 1.0, v180
	v_add_f32_e32 v181, 1.0, v181
	v_add_f32_e32 v178, 1.0, v178
	v_add_f32_e32 v179, 1.0, v179
	v_rcp_f32_e32 v180, v180
	v_rcp_f32_e32 v178, v178
	v_rcp_f32_e32 v179, v179
	v_rcp_f32_e32 v181, v181
	v_pk_fma_f32 v[178:179], v[178:179], -2.0, 1.0 op_sel_hi:[1,0,0]
	v_pk_fma_f32 v[180:181], v[180:181], -2.0, 1.0 op_sel_hi:[1,0,0]
.LBB0_139:
	v_cvt_pk_bf16_f32 v186, v176, v177
	v_cvt_pk_bf16_f32 v187, v174, v175
	v_add_u32_e32 v176, 0xa0, v162
	v_mov_b64_e32 v[174:175], s[50:51]
	v_mad_i64_i32 v[174:175], s[84:85], v176, s62, v[174:175]
	v_lshl_add_u64 v[174:175], v[174:175], 0, s[14:15]
	v_cvt_pk_bf16_f32 v188, v180, v181
	v_cvt_pk_bf16_f32 v189, v178, v179
	v_lshl_add_u64 v[176:177], v[136:137], 1, v[174:175]
	global_store_dwordx4 v[176:177], v[186:189], off


	s_nop 0
	v_mov_b32_dpp v176, v40 row_ror:1 row_mask:0xf bank_mask:0xf
	v_mov_b32_e32 v178, v3
	v_mov_b32_dpp v177, v41 row_ror:1 row_mask:0xf bank_mask:0xf
	v_mov_b32_e32 v179, v3
	v_mov_b32_dpp v180, v42 row_ror:1 row_mask:0xf bank_mask:0xf
	v_mov_b32_e32 v186, v3
	v_mov_b32_dpp v181, v43 row_ror:1 row_mask:0xf bank_mask:0xf
	v_mov_b32_e32 v187, v3
	v_mov_b32_dpp v176, v32 row_shr:1 row_mask:0xf bank_mask:0xf
	v_mov_b32_dpp v178, v32 row_shl:1 row_mask:0xf bank_mask:0xf
	v_mov_b32_dpp v177, v33 row_shr:1 row_mask:0xf bank_mask:0xf
	v_mov_b32_dpp v179, v33 row_shl:1 row_mask:0xf bank_mask:0xf
	v_mov_b32_dpp v180, v34 row_shr:1 row_mask:0xf bank_mask:0xf
	v_mov_b32_dpp v186, v34 row_shl:1 row_mask:0xf bank_mask:0xf
	v_mov_b32_dpp v181, v35 row_shr:1 row_mask:0xf bank_mask:0xf
	v_mov_b32_dpp v187, v35 row_shl:1 row_mask:0xf bank_mask:0xf
	v_pk_add_f32 v[180:181], v[180:181], v[186:187]
	v_pk_add_f32 v[176:177], v[176:177], v[178:179]
	v_pk_mul_f32 v[170:171], v[170:171], v[180:181]
	v_pk_mul_f32 v[172:173], v[172:173], v[176:177]
	v_pk_fma_f32 v[166:167], v[34:35], v[166:167], v[170:171]
	s_and_b64 vcc, exec, s[48:49]
	v_pk_fma_f32 v[164:165], v[32:33], v[164:165], v[172:173]
	s_cbranch_vccnz .LBB0_141
	v_mul_f32_e32 v164, 0x4038aa3b, v164
	v_mul_f32_e32 v165, 0x4038aa3b, v165
	v_mul_f32_e32 v166, 0x4038aa3b, v166
	v_mul_f32_e32 v167, 0x4038aa3b, v167
	v_exp_f32_e32 v164, v164
	v_exp_f32_e32 v165, v165
	v_exp_f32_e32 v166, v166
	v_exp_f32_e32 v167, v167
	v_add_f32_e32 v164, 1.0, v164
	v_add_f32_e32 v165, 1.0, v165
	v_add_f32_e32 v166, 1.0, v166
	v_add_f32_e32 v167, 1.0, v167
	v_rcp_f32_e32 v164, v164
	v_rcp_f32_e32 v166, v166
	v_rcp_f32_e32 v167, v167
	v_rcp_f32_e32 v165, v165
	v_pk_fma_f32 v[166:167], v[166:167], -2.0, 1.0 op_sel_hi:[1,0,0]
	v_pk_fma_f32 v[164:165], v[164:165], -2.0, 1.0 op_sel_hi:[1,0,0]
.LBB0_141:


	v_mov_b32_dpp v170, v8 row_ror:1 row_mask:0xf bank_mask:0xf
	v_mov_b32_e32 v172, v3
	v_mov_b32_dpp v171, v9 row_ror:1 row_mask:0xf bank_mask:0xf
	v_mov_b32_e32 v173, v3
	v_mov_b32_dpp v176, v10 row_ror:1 row_mask:0xf bank_mask:0xf
	v_mov_b32_e32 v178, v3
	v_mov_b32_dpp v177, v11 row_ror:1 row_mask:0xf bank_mask:0xf
	v_mov_b32_e32 v179, v3
	v_mov_b32_dpp v170, v24 row_shr:1 row_mask:0xf bank_mask:0xf
	v_mov_b32_dpp v172, v24 row_shl:1 row_mask:0xf bank_mask:0xf
	v_mov_b32_dpp v171, v25 row_shr:1 row_mask:0xf bank_mask:0xf
	v_mov_b32_dpp v173, v25 row_shl:1 row_mask:0xf bank_mask:0xf
	v_mov_b32_dpp v176, v26 row_shr:1 row_mask:0xf bank_mask:0xf
	v_mov_b32_dpp v178, v26 row_shl:1 row_mask:0xf bank_mask:0xf
	v_mov_b32_dpp v177, v27 row_shr:1 row_mask:0xf bank_mask:0xf
	v_mov_b32_dpp v179, v27 row_shl:1 row_mask:0xf bank_mask:0xf
	v_pk_add_f32 v[176:177], v[176:177], v[178:179]
	v_pk_add_f32 v[170:171], v[170:171], v[172:173]
	v_pk_mul_f32 v[146:147], v[146:147], v[176:177]
	v_pk_mul_f32 v[168:169], v[168:169], v[170:171]
	v_pk_fma_f32 v[144:145], v[26:27], v[144:145], v[146:147]
	s_and_b64 vcc, exec, s[48:49]
	v_pk_fma_f32 v[142:143], v[24:25], v[142:143], v[168:169]
	s_cbranch_vccnz .LBB0_143
	v_mul_f32_e32 v142, 0x4038aa3b, v142
	v_mul_f32_e32 v143, 0x4038aa3b, v143
	v_mul_f32_e32 v144, 0x4038aa3b, v144
	v_mul_f32_e32 v145, 0x4038aa3b, v145
	v_exp_f32_e32 v142, v142
	v_exp_f32_e32 v143, v143
	v_exp_f32_e32 v144, v144
	v_exp_f32_e32 v145, v145
	v_add_f32_e32 v142, 1.0, v142
	v_add_f32_e32 v143, 1.0, v143
	v_add_f32_e32 v144, 1.0, v144
	v_add_f32_e32 v145, 1.0, v145
	v_rcp_f32_e32 v142, v142
	v_rcp_f32_e32 v144, v144
	v_rcp_f32_e32 v145, v145
	v_rcp_f32_e32 v143, v143
	v_pk_fma_f32 v[144:145], v[144:145], -2.0, 1.0 op_sel_hi:[1,0,0]
	v_pk_fma_f32 v[142:143], v[142:143], -2.0, 1.0 op_sel_hi:[1,0,0]

.LBB0_147:
	s_or_b64 exec, exec, s[48:49]
	v_mov_b32_e32 v132, v3
	v_mov_b32_e32 v178, v3
	v_mov_b32_e32 v133, v3
	v_mov_b32_e32 v179, v3
	v_mov_b32_e32 v180, v3
	v_mov_b32_e32 v186, v3
	v_mov_b32_e32 v181, v3
	v_mov_b32_e32 v187, v3
	v_mov_b32_dpp v132, v60 row_ror:1 row_mask:0xf bank_mask:0xf
	v_mov_b32_dpp v178, v36 row_ror:15 row_mask:0xf bank_mask:0xf
	v_mov_b32_dpp v133, v61 row_ror:1 row_mask:0xf bank_mask:0xf
	v_mov_b32_dpp v179, v37 row_ror:15 row_mask:0xf bank_mask:0xf
	v_mov_b32_dpp v180, v62 row_ror:1 row_mask:0xf bank_mask:0xf
	v_mov_b32_dpp v186, v38 row_ror:15 row_mask:0xf bank_mask:0xf
	v_mov_b32_dpp v181, v63 row_ror:1 row_mask:0xf bank_mask:0xf
	v_mov_b32_dpp v187, v39 row_ror:15 row_mask:0xf bank_mask:0xf
	v_mov_b32_dpp v132, v44 row_shr:1 row_mask:0xf bank_mask:0xf
	v_mov_b32_dpp v178, v44 row_shl:1 row_mask:0xf bank_mask:0xf
	v_mov_b32_dpp v133, v45 row_shr:1 row_mask:0xf bank_mask:0xf
	v_mov_b32_dpp v179, v45 row_shl:1 row_mask:0xf bank_mask:0xf
	v_mov_b32_dpp v180, v46 row_shr:1 row_mask:0xf bank_mask:0xf
	v_mov_b32_dpp v186, v46 row_shl:1 row_mask:0xf bank_mask:0xf
	v_mov_b32_dpp v181, v47 row_shr:1 row_mask:0xf bank_mask:0xf
	v_mov_b32_dpp v187, v47 row_shl:1 row_mask:0xf bank_mask:0xf
	v_pk_add_f32 v[180:181], v[180:181], v[186:187]
	v_pk_add_f32 v[132:133], v[132:133], v[178:179]
	v_pk_mul_f32 v[178:179], v[172:173], v[180:181]
	v_pk_mul_f32 v[132:133], v[176:177], v[132:133]
	v_pk_fma_f32 v[180:181], v[46:47], v[168:169], v[178:179]
	v_pk_fma_f32 v[132:133], v[44:45], v[170:171], v[132:133]
	v_cvt_pk_bf16_f32 v179, v180, v181
	v_cvt_pk_bf16_f32 v178, v132, v133


	v_mov_b32_dpp v132, v48 row_ror:1 row_mask:0xf bank_mask:0xf
	v_mov_b32_dpp v180, v4 row_ror:15 row_mask:0xf bank_mask:0xf
	v_mov_b32_dpp v133, v49 row_ror:1 row_mask:0xf bank_mask:0xf
	v_mov_b32_dpp v181, v5 row_ror:15 row_mask:0xf bank_mask:0xf
	v_mov_b32_dpp v186, v50 row_ror:1 row_mask:0xf bank_mask:0xf
	v_mov_b32_dpp v188, v6 row_ror:15 row_mask:0xf bank_mask:0xf
	v_mov_b32_dpp v187, v51 row_ror:1 row_mask:0xf bank_mask:0xf
	v_mov_b32_dpp v189, v7 row_ror:15 row_mask:0xf bank_mask:0xf
	v_mov_b32_dpp v132, v12 row_shr:1 row_mask:0xf bank_mask:0xf
	v_mov_b32_dpp v180, v12 row_shl:1 row_mask:0xf bank_mask:0xf
	v_mov_b32_dpp v133, v13 row_shr:1 row_mask:0xf bank_mask:0xf
	v_mov_b32_dpp v181, v13 row_shl:1 row_mask:0xf bank_mask:0xf
	v_mov_b32_dpp v186, v14 row_shr:1 row_mask:0xf bank_mask:0xf
	v_mov_b32_dpp v188, v14 row_shl:1 row_mask:0xf bank_mask:0xf
	v_mov_b32_dpp v187, v15 row_shr:1 row_mask:0xf bank_mask:0xf
	v_mov_b32_dpp v189, v15 row_shl:1 row_mask:0xf bank_mask:0xf
	v_pk_add_f32 v[186:187], v[186:187], v[188:189]
	v_pk_add_f32 v[132:133], v[132:133], v[180:181]
	v_pk_mul_f32 v[180:181], v[164:165], v[186:187]
	v_pk_mul_f32 v[132:133], v[166:167], v[132:133]
	v_pk_fma_f32 v[186:187], v[14:15], v[138:139], v[180:181]
	v_pk_fma_f32 v[132:133], v[12:13], v[146:147], v[132:133]
	v_cvt_pk_bf16_f32 v181, v186, v187
	v_cvt_pk_bf16_f32 v180, v132, v133
	v_lshl_add_u64 v[132:133], v[134:135], 0, v[140:141]
	global_store_dwordx4 v[132:133], v[178:181], off


	s_nop 0
	v_mov_b32_dpp v132, v44 row_ror:1 row_mask:0xf bank_mask:0xf
	v_mov_b32_dpp v134, v28 row_ror:15 row_mask:0xf bank_mask:0xf
	v_mov_b32_dpp v133, v45 row_ror:1 row_mask:0xf bank_mask:0xf
	v_mov_b32_dpp v135, v29 row_ror:15 row_mask:0xf bank_mask:0xf
	v_mov_b32_dpp v178, v46 row_ror:1 row_mask:0xf bank_mask:0xf
	v_mov_b32_dpp v180, v30 row_ror:15 row_mask:0xf bank_mask:0xf
	v_mov_b32_dpp v179, v47 row_ror:1 row_mask:0xf bank_mask:0xf
	v_mov_b32_dpp v181, v31 row_ror:15 row_mask:0xf bank_mask:0xf
	v_mov_b32_dpp v132, v36 row_shr:1 row_mask:0xf bank_mask:0xf
	v_mov_b32_dpp v134, v36 row_shl:1 row_mask:0xf bank_mask:0xf
	v_mov_b32_dpp v133, v37 row_shr:1 row_mask:0xf bank_mask:0xf
	v_mov_b32_dpp v135, v37 row_shl:1 row_mask:0xf bank_mask:0xf
	v_mov_b32_dpp v178, v38 row_shr:1 row_mask:0xf bank_mask:0xf
	v_mov_b32_dpp v180, v38 row_shl:1 row_mask:0xf bank_mask:0xf
	v_mov_b32_dpp v179, v39 row_shr:1 row_mask:0xf bank_mask:0xf
	v_mov_b32_dpp v181, v39 row_shl:1 row_mask:0xf bank_mask:0xf
	v_pk_add_f32 v[178:179], v[178:179], v[180:181]
	v_pk_add_f32 v[132:133], v[132:133], v[134:135]
	v_pk_mul_f32 v[134:135], v[172:173], v[178:179]
	v_pk_mul_f32 v[132:133], v[176:177], v[132:133]
	v_pk_fma_f32 v[134:135], v[38:39], v[168:169], v[134:135]
	v_pk_fma_f32 v[132:133], v[36:37], v[170:171], v[132:133]

	v_cvt_pk_bf16_f32 v132, v132, v133
	v_cvt_pk_bf16_f32 v133, v134, v135


	v_mov_b32_dpp v134, v12 row_ror:1 row_mask:0xf bank_mask:0xf
	v_mov_b32_dpp v178, v16 row_ror:15 row_mask:0xf bank_mask:0xf
	v_mov_b32_dpp v135, v13 row_ror:1 row_mask:0xf bank_mask:0xf
	v_mov_b32_dpp v179, v17 row_ror:15 row_mask:0xf bank_mask:0xf
	v_mov_b32_dpp v180, v14 row_ror:1 row_mask:0xf bank_mask:0xf
	v_mov_b32_dpp v186, v18 row_ror:15 row_mask:0xf bank_mask:0xf
	v_mov_b32_dpp v181, v15 row_ror:1 row_mask:0xf bank_mask:0xf
	v_mov_b32_dpp v187, v19 row_ror:15 row_mask:0xf bank_mask:0xf
	v_mov_b32_dpp v134, v4 row_shr:1 row_mask:0xf bank_mask:0xf
	v_mov_b32_dpp v178, v4 row_shl:1 row_mask:0xf bank_mask:0xf
	v_mov_b32_dpp v135, v5 row_shr:1 row_mask:0xf bank_mask:0xf
	v_mov_b32_dpp v179, v5 row_shl:1 row_mask:0xf bank_mask:0xf
	v_mov_b32_dpp v180, v6 row_shr:1 row_mask:0xf bank_mask:0xf
	v_mov_b32_dpp v186, v6 row_shl:1 row_mask:0xf bank_mask:0xf
	v_mov_b32_dpp v181, v7 row_shr:1 row_mask:0xf bank_mask:0xf
	v_mov_b32_dpp v187, v7 row_shl:1 row_mask:0xf bank_mask:0xf
	v_pk_add_f32 v[180:181], v[180:181], v[186:187]
	v_pk_add_f32 v[134:135], v[134:135], v[178:179]
	v_pk_mul_f32 v[178:179], v[164:165], v[180:181]
	v_pk_mul_f32 v[134:135], v[166:167], v[134:135]
	v_pk_fma_f32 v[178:179], v[6:7], v[138:139], v[178:179]
	v_pk_fma_f32 v[134:135], v[4:5], v[146:147], v[134:135]
	v_lshl_add_u64 v[174:175], v[174:175], 0, v[140:141]
	v_cvt_pk_bf16_f32 v134, v134, v135
	v_cvt_pk_bf16_f32 v135, v178, v179
	global_store_dwordx4 v[174:175], v[132:135], off


	s_nop 1
	v_mov_b32_e32 v134, v3
	v_mov_b32_dpp v132, v36 row_ror:1 row_mask:0xf bank_mask:0xf
	v_mov_b32_dpp v133, v37 row_ror:1 row_mask:0xf bank_mask:0xf
	v_mov_b32_e32 v135, v3
	v_mov_b32_dpp v174, v38 row_ror:1 row_mask:0xf bank_mask:0xf
	v_mov_b32_e32 v178, v3
	v_mov_b32_dpp v175, v39 row_ror:1 row_mask:0xf bank_mask:0xf
	v_mov_b32_e32 v179, v3
	v_mov_b32_dpp v132, v28 row_shr:1 row_mask:0xf bank_mask:0xf
	v_mov_b32_dpp v134, v28 row_shl:1 row_mask:0xf bank_mask:0xf
	v_mov_b32_dpp v133, v29 row_shr:1 row_mask:0xf bank_mask:0xf
	v_mov_b32_dpp v135, v29 row_shl:1 row_mask:0xf bank_mask:0xf
	v_mov_b32_dpp v174, v30 row_shr:1 row_mask:0xf bank_mask:0xf
	v_mov_b32_dpp v178, v30 row_shl:1 row_mask:0xf bank_mask:0xf
	v_mov_b32_dpp v175, v31 row_shr:1 row_mask:0xf bank_mask:0xf
	v_mov_b32_dpp v179, v31 row_shl:1 row_mask:0xf bank_mask:0xf
	v_pk_add_f32 v[174:175], v[174:175], v[178:179]
	v_pk_add_f32 v[132:133], v[132:133], v[134:135]
	v_pk_mul_f32 v[134:135], v[172:173], v[174:175]
	v_pk_mul_f32 v[132:133], v[176:177], v[132:133]
	v_pk_fma_f32 v[134:135], v[30:31], v[168:169], v[134:135]
	v_pk_fma_f32 v[132:133], v[28:29], v[170:171], v[132:133]

	v_cvt_pk_bf16_f32 v132, v132, v133
	v_cvt_pk_bf16_f32 v133, v134, v135


	v_mov_b32_dpp v134, v4 row_ror:1 row_mask:0xf bank_mask:0xf
	v_mov_b32_e32 v168, v3
	v_mov_b32_dpp v135, v5 row_ror:1 row_mask:0xf bank_mask:0xf
	v_mov_b32_e32 v169, v3
	v_mov_b32_dpp v170, v6 row_ror:1 row_mask:0xf bank_mask:0xf
	v_mov_b32_e32 v172, v3
	v_mov_b32_dpp v171, v7 row_ror:1 row_mask:0xf bank_mask:0xf
	v_mov_b32_e32 v173, v3
	v_mov_b32_dpp v134, v16 row_shr:1 row_mask:0xf bank_mask:0xf
	v_mov_b32_dpp v168, v16 row_shl:1 row_mask:0xf bank_mask:0xf
	v_mov_b32_dpp v135, v17 row_shr:1 row_mask:0xf bank_mask:0xf
	v_mov_b32_dpp v169, v17 row_shl:1 row_mask:0xf bank_mask:0xf
	v_mov_b32_dpp v170, v18 row_shr:1 row_mask:0xf bank_mask:0xf
	v_mov_b32_dpp v172, v18 row_shl:1 row_mask:0xf bank_mask:0xf
	v_mov_b32_dpp v171, v19 row_shr:1 row_mask:0xf bank_mask:0xf
	v_mov_b32_dpp v173, v19 row_shl:1 row_mask:0xf bank_mask:0xf
	v_pk_add_f32 v[170:171], v[170:171], v[172:173]
	v_pk_add_f32 v[134:135], v[134:135], v[168:169]
	v_pk_mul_f32 v[164:165], v[164:165], v[170:171]
	v_pk_mul_f32 v[134:135], v[166:167], v[134:135]
	v_pk_fma_f32 v[138:139], v[18:19], v[138:139], v[164:165]
	v_pk_fma_f32 v[134:135], v[16:17], v[146:147], v[134:135]
	s_nop 0
	v_cvt_pk_bf16_f32 v134, v134, v135
	v_cvt_pk_bf16_f32 v135, v138, v139
	v_lshl_add_u64 v[138:139], v[144:145], 0, v[140:141]
	global_store_dwordx4 v[138:139], v[132:135], off
	s_and_saveexec_b64 s[48:49], s[40:41]
	s_cbranch_execz .LBB0_149
	v_mov_b64_e32 v[138:139], s[98:99]
	s_movk_i32 s29, 0x2200
	v_mad_u64_u32 v[138:139], s[60:61], v142, s29, v[138:139]
	v_mad_i32_i24 v139, v143, s29, v139
	v_cvt_pk_bf16_f32 v132, v28, v29
	v_cvt_pk_bf16_f32 v133, v30, v31
	v_cvt_pk_bf16_f32 v134, v16, v17
	v_cvt_pk_bf16_f32 v135, v18, v19
	v_lshl_add_u64 v[138:139], v[136:137], 1, v[138:139]
	global_store_dwordx4 v[138:139], v[132:135], off offset:256

.LBB0_153:
	v_lshl_or_b32 v164, s82, 6, v183
	v_ashrrev_i32_e32 v165, 31, v164
	v_lshlrev_b64 v[136:137], 2, v[164:165]
	v_lshl_add_u64 v[132:133], s[52:53], 0, v[136:137]
	global_load_dwordx4 v[140:143], v[132:133], off
	v_lshl_add_u64 v[132:133], s[8:9], 0, v[136:137]
	global_load_dwordx4 v[144:147], v[132:133], off
	v_lshl_add_u64 v[132:133], s[4:5], 0, v[136:137]
	global_load_dwordx4 v[132:135], v[132:133], off
	v_lshl_add_u64 v[136:137], s[54:55], 0, v[136:137]
	global_load_dwordx4 v[136:139], v[136:137], off
	v_mul_f32_e32 v2, 0xbfb8aa3b, v116
	v_exp_f32_e32 v2, v2
	v_pk_mul_f32 v[124:125], v[128:129], v[124:125]
	v_pk_mul_f32 v[126:127], v[130:131], v[126:127]
	v_pk_mul_f32 v[110:111], v[114:115], v[110:111]
	v_add_f32_e32 v2, 1.0, v2
	v_rcp_f32_e32 v128, v2
	v_mul_f32_e32 v2, 0xbfb8aa3b, v117
	v_exp_f32_e32 v2, v2
	v_mov_b32_e32 v114, v3
	v_mov_b32_e32 v115, v3
	v_pk_mul_f32 v[108:109], v[112:113], v[108:109]
	v_add_f32_e32 v2, 1.0, v2
	v_rcp_f32_e32 v129, v2
	v_mul_f32_e32 v2, 0xbfb8aa3b, v118
	v_exp_f32_e32 v2, v2

	v_pk_mul_f32 v[116:117], v[116:117], v[128:129]
	v_mov_b32_dpp v114, v124 row_shr:1 row_mask:0xf bank_mask:0xf
	v_add_f32_e32 v2, 1.0, v2
	v_pk_mul_f32 v[116:117], v[120:121], v[116:117]
	v_rcp_f32_e32 v120, v2
	v_mul_f32_e32 v2, 0xbfb8aa3b, v119
	v_exp_f32_e32 v2, v2

	v_mov_b32_dpp v115, v125 row_shr:1 row_mask:0xf bank_mask:0xf
	v_mov_b32_dpp v112, v108 row_ror:15 row_mask:0xf bank_mask:0xf
	v_add_f32_e32 v2, 1.0, v2
	v_rcp_f32_e32 v121, v2
	v_mov_b32_dpp v113, v109 row_ror:15 row_mask:0xf bank_mask:0xf
	v_mov_b32_dpp v112, v124 row_shl:1 row_mask:0xf bank_mask:0xf
	v_ashrrev_i32_e32 v163, 31, v162
	v_pk_mul_f32 v[118:119], v[118:119], v[120:121]

	v_pk_mul_f32 v[118:119], v[122:123], v[118:119]
	v_mov_b32_e32 v122, v3
	v_mov_b32_e32 v123, v3

	s_nop 0
	v_mov_b32_dpp v122, v126 row_shr:1 row_mask:0xf bank_mask:0xf
	v_mov_b32_dpp v123, v127 row_shr:1 row_mask:0xf bank_mask:0xf
	v_mov_b32_dpp v120, v110 row_ror:15 row_mask:0xf bank_mask:0xf
	v_mov_b32_dpp v121, v111 row_ror:15 row_mask:0xf bank_mask:0xf
	v_mov_b32_dpp v113, v125 row_shl:1 row_mask:0xf bank_mask:0xf
	v_mov_b32_dpp v120, v126 row_shl:1 row_mask:0xf bank_mask:0xf
	v_mov_b32_dpp v121, v127 row_shl:1 row_mask:0xf bank_mask:0xf
	s_lshl_b32 s59, s81, 2
	s_add_i32 s81, s59, s71
	s_mul_hi_i32 s49, s81, 6
	s_mul_i32 s48, s81, 6
	s_waitcnt vmcnt(0)
	v_pk_mul_f32 v[122:123], v[142:143], v[122:123]
	v_pk_mul_f32 v[114:115], v[140:141], v[114:115]
	v_pk_fma_f32 v[122:123], v[126:127], v[146:147], v[122:123]
	v_pk_fma_f32 v[114:115], v[124:125], v[144:145], v[114:115]
	v_pk_fma_f32 v[120:121], v[134:135], v[120:121], v[122:123]
	v_pk_fma_f32 v[112:113], v[132:133], v[112:113], v[114:115]
	v_pk_add_f32 v[114:115], v[138:139], v[120:121]
	v_pk_add_f32 v[112:113], v[136:137], v[112:113]
	v_pk_mul_f32 v[114:115], v[118:119], v[114:115]
	v_pk_mul_f32 v[112:113], v[116:117], v[112:113]
	s_nop 0
	v_cvt_pk_bf16_f32 v112, v112, v113
	v_cvt_pk_bf16_f32 v113, v114, v115
	v_lshlrev_b64 v[114:115], 12, v[162:163]
	v_lshl_add_u64 v[114:115], s[10:11], 0, v[114:115]
	v_lshl_add_u64 v[114:115], v[164:165], 1, v[114:115]
	global_store_dwordx2 v[114:115], v[112:113], off
	s_and_saveexec_b64 s[60:61], s[38:39]
	s_cbranch_execz .LBB0_156
	v_mov_b32_e32 v115, s49
	v_or_b32_e32 v114, s48, v154
	v_lshlrev_b64 v[114:115], 11, v[114:115]
	v_lshl_add_u64 v[114:115], s[36:37], 0, v[114:115]
	v_cvt_pk_bf16_f32 v112, v124, v125
	v_cvt_pk_bf16_f32 v113, v126, v127
	v_lshl_add_u64 v[114:115], v[164:165], 1, v[114:115]
	global_store_dwordx2 v[114:115], v[112:113], off
	s_and_b64 exec, exec, s[42:43]
	s_cbranch_execz .LBB0_156
	s_mul_i32 s82, s81, 0x3000
	s_mul_hi_i32 s83, s81, 0x3000
	s_add_u32 s82, s36, s82
	s_addc_u32 s83, s37, s83
	v_lshl_add_u64 v[114:115], v[164:165], 1, s[82:83]
	v_add_co_u32_e32 v114, vcc, 0x2000, v114
	v_cvt_pk_bf16_f32 v112, v116, v117
	v_cvt_pk_bf16_f32 v113, v118, v119
	v_addc_co_u32_e32 v115, vcc, 0, v115, vcc
	global_store_dwordx2 v[114:115], v[112:113], off
.LBB0_156:
	s_or_b64 exec, exec, s[60:61]
	v_mul_f32_e32 v2, 0xbfb8aa3b, v76
	v_exp_f32_e32 v2, v2
	v_pk_mul_f32 v[100:101], v[104:105], v[100:101]
	v_pk_mul_f32 v[102:103], v[106:107], v[102:103]
	v_pk_mul_f32 v[92:93], v[96:97], v[92:93]
	v_add_f32_e32 v2, 1.0, v2
	v_rcp_f32_e32 v112, v2
	v_mul_f32_e32 v2, 0xbfb8aa3b, v77
	v_exp_f32_e32 v2, v2
	v_pk_mul_f32 v[94:95], v[98:99], v[94:95]
	v_mov_b32_e32 v98, v3
	v_mov_b32_e32 v99, v3
	v_add_f32_e32 v2, 1.0, v2
	v_rcp_f32_e32 v113, v2
	v_mul_f32_e32 v2, 0xbfb8aa3b, v78
	v_exp_f32_e32 v2, v2
	v_mov_b32_dpp v98, v102 row_ror:15 row_mask:0xf bank_mask:0xf
	v_pk_mul_f32 v[76:77], v[76:77], v[112:113]
	v_mov_b32_dpp v99, v103 row_ror:15 row_mask:0xf bank_mask:0xf
	v_add_f32_e32 v2, 1.0, v2
	v_rcp_f32_e32 v114, v2
	v_mul_f32_e32 v2, 0xbfb8aa3b, v79
	v_exp_f32_e32 v2, v2
	v_pk_mul_f32 v[76:77], v[84:85], v[76:77]
	v_mov_b32_dpp v98, v110 row_shl:1 row_mask:0xf bank_mask:0xf
	v_mov_b32_dpp v99, v111 row_shl:1 row_mask:0xf bank_mask:0xf
	v_add_f32_e32 v2, 1.0, v2
	v_rcp_f32_e32 v115, v2
	v_mul_f32_e32 v2, 0xbfb8aa3b, v68
	v_exp_f32_e32 v2, v2
	v_pk_mul_f32 v[78:79], v[78:79], v[114:115]
	s_nop 0
	v_pk_mul_f32 v[78:79], v[86:87], v[78:79]
	v_add_f32_e32 v2, 1.0, v2
	v_rcp_f32_e32 v104, v2
	v_mul_f32_e32 v2, 0xbfb8aa3b, v69
	v_exp_f32_e32 v2, v2
	s_nop 0
	v_add_f32_e32 v2, 1.0, v2
	v_rcp_f32_e32 v105, v2
	v_mul_f32_e32 v2, 0xbfb8aa3b, v70
	v_exp_f32_e32 v2, v2
	v_pk_mul_f32 v[68:69], v[68:69], v[104:105]
	s_nop 0
	v_pk_mul_f32 v[68:69], v[72:73], v[68:69]
	v_add_f32_e32 v2, 1.0, v2
	v_rcp_f32_e32 v106, v2
	v_mul_f32_e32 v2, 0xbfb8aa3b, v71
	v_exp_f32_e32 v2, v2
	s_nop 0
	v_add_f32_e32 v2, 1.0, v2
	v_rcp_f32_e32 v107, v2
	v_mul_f32_e32 v2, 0xbfb8aa3b, v80
	v_exp_f32_e32 v2, v2
	v_pk_mul_f32 v[70:71], v[70:71], v[106:107]
	s_nop 0
	v_pk_mul_f32 v[70:71], v[74:75], v[70:71]
	v_add_f32_e32 v2, 1.0, v2
	v_rcp_f32_e32 v96, v2
	v_mul_f32_e32 v2, 0xbfb8aa3b, v81
	v_exp_f32_e32 v2, v2
	s_nop 0
	v_add_f32_e32 v2, 1.0, v2
	v_rcp_f32_e32 v97, v2
	v_mul_f32_e32 v2, 0xbfb8aa3b, v82
	v_exp_f32_e32 v2, v2
	v_pk_mul_f32 v[80:81], v[80:81], v[96:97]
	s_nop 0
	v_pk_mul_f32 v[80:81], v[88:89], v[80:81]
	v_add_f32_e32 v2, 1.0, v2
	v_rcp_f32_e32 v88, v2
	v_mul_f32_e32 v2, 0xbfb8aa3b, v83
	v_exp_f32_e32 v2, v2


	s_nop 0
	v_add_f32_e32 v2, 1.0, v2
	v_rcp_f32_e32 v89, v2
	v_mov_b32_dpp v96, v126 row_ror:1 row_mask:0xf bank_mask:0xf
	v_mov_b32_dpp v97, v127 row_ror:1 row_mask:0xf bank_mask:0xf
	v_pk_mul_f32 v[82:83], v[82:83], v[88:89]


	v_pk_mul_f32 v[82:83], v[90:91], v[82:83]
	v_mov_b32_dpp v88, v124 row_ror:1 row_mask:0xf bank_mask:0xf
	v_mov_b32_dpp v89, v125 row_ror:1 row_mask:0xf bank_mask:0xf

	s_nop 0
	v_mov_b32_dpp v88, v108 row_shr:1 row_mask:0xf bank_mask:0xf

	v_mov_b32_dpp v89, v109 row_shr:1 row_mask:0xf bank_mask:0xf
	v_mov_b32_dpp v96, v110 row_shr:1 row_mask:0xf bank_mask:0xf
	v_mov_b32_dpp v97, v111 row_shr:1 row_mask:0xf bank_mask:0xf
	v_mov_b32_dpp v90, v100 row_ror:15 row_mask:0xf bank_mask:0xf
	v_mov_b32_dpp v91, v101 row_ror:15 row_mask:0xf bank_mask:0xf
	v_pk_mul_f32 v[84:85], v[142:143], v[96:97]
	v_pk_mul_f32 v[86:87], v[140:141], v[88:89]
	v_mov_b32_dpp v90, v108 row_shl:1 row_mask:0xf bank_mask:0xf
	v_mov_b32_dpp v91, v109 row_shl:1 row_mask:0xf bank_mask:0xf
	v_pk_fma_f32 v[86:87], v[108:109], v[144:145], v[86:87]
	v_pk_fma_f32 v[84:85], v[110:111], v[146:147], v[84:85]
	v_pk_fma_f32 v[86:87], v[132:133], v[90:91], v[86:87]
	v_pk_fma_f32 v[84:85], v[134:135], v[98:99], v[84:85]
	v_pk_add_f32 v[86:87], v[136:137], v[86:87]
	v_pk_add_f32 v[84:85], v[138:139], v[84:85]
	v_pk_mul_f32 v[76:77], v[76:77], v[86:87]
	v_pk_mul_f32 v[78:79], v[78:79], v[84:85]
	v_cvt_pk_bf16_f32 v76, v76, v77
	v_cvt_pk_bf16_f32 v77, v78, v79
	v_or_b32_e32 v78, 16, v162
	v_ashrrev_i32_e32 v79, 31, v78
	v_lshlrev_b64 v[78:79], 12, v[78:79]
	v_lshl_add_u64 v[78:79], s[10:11], 0, v[78:79]
	v_lshlrev_b64 v[84:85], 1, v[164:165]
	v_lshl_add_u64 v[78:79], v[78:79], 0, v[84:85]
	global_store_dwordx2 v[78:79], v[76:77], off


	v_mov_b32_dpp v76, v108 row_ror:1 row_mask:0xf bank_mask:0xf
	v_mov_b32_dpp v77, v109 row_ror:1 row_mask:0xf bank_mask:0xf
	v_mov_b32_dpp v86, v110 row_ror:1 row_mask:0xf bank_mask:0xf
	v_mov_b32_dpp v87, v111 row_ror:1 row_mask:0xf bank_mask:0xf

	v_mov_b32_dpp v76, v100 row_shr:1 row_mask:0xf bank_mask:0xf

	v_mov_b32_dpp v77, v101 row_shr:1 row_mask:0xf bank_mask:0xf

	v_mov_b32_dpp v86, v102 row_shr:1 row_mask:0xf bank_mask:0xf

	v_mov_b32_dpp v87, v103 row_shr:1 row_mask:0xf bank_mask:0xf
	v_mov_b32_dpp v78, v92 row_ror:15 row_mask:0xf bank_mask:0xf
	v_mov_b32_dpp v79, v93 row_ror:15 row_mask:0xf bank_mask:0xf
	v_mov_b32_dpp v88, v94 row_ror:15 row_mask:0xf bank_mask:0xf
	v_mov_b32_dpp v89, v95 row_ror:15 row_mask:0xf bank_mask:0xf
	v_pk_mul_f32 v[72:73], v[142:143], v[86:87]
	v_pk_mul_f32 v[74:75], v[140:141], v[76:77]
	v_mov_b32_dpp v78, v100 row_shl:1 row_mask:0xf bank_mask:0xf
	v_mov_b32_dpp v79, v101 row_shl:1 row_mask:0xf bank_mask:0xf
	v_mov_b32_dpp v88, v102 row_shl:1 row_mask:0xf bank_mask:0xf
	v_mov_b32_dpp v89, v103 row_shl:1 row_mask:0xf bank_mask:0xf
	v_pk_fma_f32 v[74:75], v[100:101], v[144:145], v[74:75]
	v_pk_fma_f32 v[72:73], v[102:103], v[146:147], v[72:73]
	v_pk_fma_f32 v[74:75], v[132:133], v[78:79], v[74:75]
	v_pk_fma_f32 v[72:73], v[134:135], v[88:89], v[72:73]
	v_pk_add_f32 v[74:75], v[136:137], v[74:75]
	v_pk_add_f32 v[72:73], v[138:139], v[72:73]
	v_pk_mul_f32 v[68:69], v[68:69], v[74:75]
	v_pk_mul_f32 v[70:71], v[70:71], v[72:73]
	v_cvt_pk_bf16_f32 v68, v68, v69
	v_cvt_pk_bf16_f32 v69, v70, v71
	v_or_b32_e32 v70, 32, v162
	v_ashrrev_i32_e32 v71, 31, v70
	v_lshlrev_b64 v[70:71], 12, v[70:71]
	v_lshl_add_u64 v[70:71], s[10:11], 0, v[70:71]
	v_lshl_add_u64 v[70:71], v[70:71], 0, v[84:85]
	global_store_dwordx2 v[70:71], v[68:69], off


	v_mov_b32_dpp v68, v100 row_ror:1 row_mask:0xf bank_mask:0xf
	v_mov_b32_dpp v69, v101 row_ror:1 row_mask:0xf bank_mask:0xf
	v_mov_b32_dpp v72, v102 row_ror:1 row_mask:0xf bank_mask:0xf
	v_mov_b32_dpp v73, v103 row_ror:1 row_mask:0xf bank_mask:0xf
	v_mov_b32_dpp v68, v92 row_shr:1 row_mask:0xf bank_mask:0xf
	v_mov_b32_dpp v69, v93 row_shr:1 row_mask:0xf bank_mask:0xf
	v_mov_b32_dpp v72, v94 row_shr:1 row_mask:0xf bank_mask:0xf
	v_mov_b32_dpp v73, v95 row_shr:1 row_mask:0xf bank_mask:0xf
	v_mov_b32_e32 v70, v3
	v_mov_b32_e32 v71, v3
	v_mov_b32_e32 v74, v3
	v_mov_b32_e32 v75, v3
	v_pk_mul_f32 v[72:73], v[142:143], v[72:73]
	v_pk_mul_f32 v[68:69], v[140:141], v[68:69]
	v_mov_b32_dpp v70, v92 row_shl:1 row_mask:0xf bank_mask:0xf
	v_mov_b32_dpp v71, v93 row_shl:1 row_mask:0xf bank_mask:0xf
	v_mov_b32_dpp v74, v94 row_shl:1 row_mask:0xf bank_mask:0xf
	v_mov_b32_dpp v75, v95 row_shl:1 row_mask:0xf bank_mask:0xf
	v_pk_fma_f32 v[72:73], v[94:95], v[146:147], v[72:73]
	v_pk_fma_f32 v[68:69], v[92:93], v[144:145], v[68:69]
	v_pk_fma_f32 v[72:73], v[134:135], v[74:75], v[72:73]
	v_pk_fma_f32 v[68:69], v[132:133], v[70:71], v[68:69]
	v_pk_add_f32 v[70:71], v[138:139], v[72:73]
	v_pk_add_f32 v[68:69], v[136:137], v[68:69]
	v_pk_mul_f32 v[70:71], v[82:83], v[70:71]
	v_pk_mul_f32 v[68:69], v[80:81], v[68:69]
	s_nop 0
	v_cvt_pk_bf16_f32 v68, v68, v69
	v_cvt_pk_bf16_f32 v69, v70, v71
	v_or_b32_e32 v70, 48, v162
	v_ashrrev_i32_e32 v71, 31, v70
	v_lshlrev_b64 v[70:71], 12, v[70:71]
	v_lshl_add_u64 v[70:71], s[10:11], 0, v[70:71]
	v_lshl_add_u64 v[70:71], v[70:71], 0, v[84:85]
	global_store_dwordx2 v[70:71], v[68:69], off
	s_and_saveexec_b64 s[60:61], s[40:41]
	s_cbranch_execz .LBB0_159
	v_lshl_add_u64 v[70:71], s[48:49], 0, v[156:157]
	v_lshlrev_b64 v[70:71], 11, v[70:71]
	v_lshl_add_u64 v[70:71], s[36:37], 0, v[70:71]
	v_cvt_pk_bf16_f32 v68, v92, v93
	v_cvt_pk_bf16_f32 v69, v94, v95
	v_lshl_add_u64 v[70:71], v[164:165], 1, v[70:71]
	global_store_dwordx2 v[70:71], v[68:69], off
	s_and_b64 exec, exec, s[44:45]
	s_cbranch_execz .LBB0_159
	s_mul_hi_i32 s49, s81, 0x3000
	s_mulk_i32 s81, 0x3000
	s_add_u32 s48, s36, s81
	s_addc_u32 s49, s37, s49
	v_lshl_add_u64 v[70:71], v[164:165], 1, s[48:49]
	v_add_co_u32_e32 v70, vcc, 0x2000, v70
	v_cvt_pk_bf16_f32 v68, v80, v81
	v_cvt_pk_bf16_f32 v69, v82, v83
	v_addc_co_u32_e32 v71, vcc, 0, v71, vcc
	global_store_dwordx2 v[70:71], v[68:69], off offset:2048
.LBB0_159:
	s_or_b64 exec, exec, s[60:61]
	v_mul_f32_e32 v2, 0xbfb8aa3b, v48
	v_exp_f32_e32 v2, v2
	v_pk_mul_f32 v[60:61], v[64:65], v[60:61]
	v_pk_mul_f32 v[62:63], v[66:67], v[62:63]
	v_pk_mul_f32 v[46:47], v[54:55], v[46:47]
	v_add_f32_e32 v2, 1.0, v2
	v_rcp_f32_e32 v64, v2
	v_mul_f32_e32 v2, 0xbfb8aa3b, v49
	v_exp_f32_e32 v2, v2
	v_mov_b32_e32 v54, v3
	v_mov_b32_e32 v55, v3
	s_add_i32 s59, s59, s79
	v_add_f32_e32 v2, 1.0, v2
	v_rcp_f32_e32 v65, v2
	v_mul_f32_e32 v2, 0xbfb8aa3b, v50
	v_exp_f32_e32 v2, v2
	v_mov_b32_dpp v54, v46 row_ror:15 row_mask:0xf bank_mask:0xf
	v_pk_mul_f32 v[48:49], v[48:49], v[64:65]
	v_mov_b32_dpp v55, v47 row_ror:15 row_mask:0xf bank_mask:0xf
	v_add_f32_e32 v2, 1.0, v2
	v_pk_mul_f32 v[56:57], v[56:57], v[48:49]
	v_rcp_f32_e32 v48, v2
	v_mul_f32_e32 v2, 0xbfb8aa3b, v51
	v_exp_f32_e32 v2, v2
	v_mov_b32_dpp v54, v62 row_shl:1 row_mask:0xf bank_mask:0xf
	v_mov_b32_dpp v55, v63 row_shl:1 row_mask:0xf bank_mask:0xf
	s_mul_hi_i32 s49, s59, 6
	v_add_f32_e32 v2, 1.0, v2
	v_rcp_f32_e32 v49, v2
	s_mul_i32 s48, s59, 6
	v_pk_mul_f32 v[48:49], v[50:51], v[48:49]
	s_nop 0
	v_pk_mul_f32 v[50:51], v[58:59], v[48:49]
	v_pk_mul_f32 v[48:49], v[52:53], v[44:45]
	v_mov_b32_e32 v52, v3
	v_mov_b32_e32 v53, v3

	s_nop 0
	v_mov_b32_dpp v52, v60 row_shr:1 row_mask:0xf bank_mask:0xf

	v_mov_b32_dpp v53, v61 row_shr:1 row_mask:0xf bank_mask:0xf
	v_mov_b32_dpp v44, v48 row_ror:15 row_mask:0xf bank_mask:0xf
	v_mov_b32_dpp v45, v49 row_ror:15 row_mask:0xf bank_mask:0xf
	v_mov_b32_e32 v58, v3
	v_mov_b32_e32 v59, v3
	v_pk_mul_f32 v[52:53], v[140:141], v[52:53]
	v_mov_b32_dpp v44, v60 row_shl:1 row_mask:0xf bank_mask:0xf
	v_mov_b32_dpp v45, v61 row_shl:1 row_mask:0xf bank_mask:0xf
	v_mov_b32_dpp v58, v62 row_shr:1 row_mask:0xf bank_mask:0xf
	v_mov_b32_dpp v59, v63 row_shr:1 row_mask:0xf bank_mask:0xf
	v_pk_fma_f32 v[52:53], v[60:61], v[144:145], v[52:53]
	v_pk_mul_f32 v[58:59], v[142:143], v[58:59]
	v_pk_fma_f32 v[44:45], v[132:133], v[44:45], v[52:53]
	v_pk_fma_f32 v[58:59], v[62:63], v[146:147], v[58:59]
	v_pk_add_f32 v[44:45], v[136:137], v[44:45]
	v_pk_fma_f32 v[54:55], v[134:135], v[54:55], v[58:59]
	v_pk_mul_f32 v[44:45], v[56:57], v[44:45]
	v_pk_add_f32 v[52:53], v[138:139], v[54:55]
	v_cvt_pk_bf16_f32 v54, v44, v45
	v_lshlrev_b64 v[44:45], 12, v[162:163]
	v_lshl_add_u64 v[44:45], s[10:11], 0, v[44:45]
	v_pk_mul_f32 v[52:53], v[50:51], v[52:53]
	v_lshl_add_u64 v[44:45], v[164:165], 1, v[44:45]
	v_cvt_pk_bf16_f32 v55, v52, v53
	v_add_co_u32_e32 v52, vcc, 0x80000, v44
	s_nop 1
	v_addc_co_u32_e32 v53, vcc, 0, v45, vcc
	global_store_dwordx2 v[52:53], v[54:55], off
	s_and_saveexec_b64 s[60:61], s[38:39]
	s_cbranch_execz .LBB0_162
	v_mov_b32_e32 v55, s49
	v_or_b32_e32 v54, s48, v154
	v_lshlrev_b64 v[54:55], 11, v[54:55]
	v_lshl_add_u64 v[54:55], s[36:37], 0, v[54:55]
	v_cvt_pk_bf16_f32 v52, v60, v61
	v_cvt_pk_bf16_f32 v53, v62, v63
	v_lshl_add_u64 v[54:55], v[164:165], 1, v[54:55]
	global_store_dwordx2 v[54:55], v[52:53], off
	s_and_b64 exec, exec, s[42:43]
	s_cbranch_execz .LBB0_162
	s_mul_i32 s82, s59, 0x3000
	s_mul_hi_i32 s81, s59, 0x3000
	s_add_u32 s82, s36, s82
	s_addc_u32 s83, s37, s81
	v_cvt_pk_bf16_f32 v53, v50, v51
	v_lshl_add_u64 v[50:51], v[164:165], 1, s[82:83]
	v_add_co_u32_e32 v50, vcc, 0x2000, v50
	v_cvt_pk_bf16_f32 v52, v56, v57
	s_nop 0
	v_addc_co_u32_e32 v51, vcc, 0, v51, vcc
	global_store_dwordx2 v[50:51], v[52:53], off
.LBB0_162:
	s_or_b64 exec, exec, s[60:61]
	v_mul_f32_e32 v2, 0xbfb8aa3b, v12
	v_exp_f32_e32 v2, v2
	v_pk_mul_f32 v[36:37], v[40:41], v[36:37]
	v_pk_mul_f32 v[38:39], v[42:43], v[38:39]
	v_pk_mul_f32 v[28:29], v[32:33], v[28:29]
	v_add_f32_e32 v2, 1.0, v2
	v_rcp_f32_e32 v50, v2
	v_mul_f32_e32 v2, 0xbfb8aa3b, v13
	v_exp_f32_e32 v2, v2
	v_pk_mul_f32 v[30:31], v[34:35], v[30:31]
	v_mov_b32_e32 v34, v3
	v_mov_b32_e32 v35, v3
	v_add_f32_e32 v2, 1.0, v2
	v_rcp_f32_e32 v51, v2
	v_mul_f32_e32 v2, 0xbfb8aa3b, v14
	v_exp_f32_e32 v2, v2
	v_mov_b32_dpp v34, v38 row_ror:15 row_mask:0xf bank_mask:0xf
	v_pk_mul_f32 v[12:13], v[12:13], v[50:51]
	v_mov_b32_dpp v35, v39 row_ror:15 row_mask:0xf bank_mask:0xf
	v_add_f32_e32 v2, 1.0, v2
	v_rcp_f32_e32 v52, v2
	v_mul_f32_e32 v2, 0xbfb8aa3b, v15
	v_exp_f32_e32 v2, v2
	v_pk_mul_f32 v[12:13], v[20:21], v[12:13]
	v_mov_b32_dpp v34, v46 row_shl:1 row_mask:0xf bank_mask:0xf
	v_mov_b32_dpp v35, v47 row_shl:1 row_mask:0xf bank_mask:0xf
	v_add_f32_e32 v2, 1.0, v2
	v_rcp_f32_e32 v53, v2
	v_mul_f32_e32 v2, 0xbfb8aa3b, v4
	v_exp_f32_e32 v2, v2
	s_mov_b32 s60, 0x90000
	v_pk_mul_f32 v[14:15], v[14:15], v[52:53]
	v_add_f32_e32 v2, 1.0, v2
	v_rcp_f32_e32 v40, v2
	v_mul_f32_e32 v2, 0xbfb8aa3b, v5
	v_exp_f32_e32 v2, v2
	v_pk_mul_f32 v[14:15], v[22:23], v[14:15]
	v_add_f32_e32 v2, 1.0, v2
	v_rcp_f32_e32 v41, v2
	v_mul_f32_e32 v2, 0xbfb8aa3b, v6
	v_exp_f32_e32 v2, v2
	v_pk_mul_f32 v[4:5], v[4:5], v[40:41]
	s_nop 0
	v_pk_mul_f32 v[4:5], v[8:9], v[4:5]
	v_add_f32_e32 v2, 1.0, v2
	v_rcp_f32_e32 v42, v2
	v_mul_f32_e32 v2, 0xbfb8aa3b, v7
	v_exp_f32_e32 v2, v2
	s_nop 0
	v_add_f32_e32 v2, 1.0, v2
	v_rcp_f32_e32 v43, v2
	v_mul_f32_e32 v2, 0xbfb8aa3b, v16
	v_exp_f32_e32 v2, v2
	v_pk_mul_f32 v[6:7], v[6:7], v[42:43]
	s_nop 0
	v_pk_mul_f32 v[6:7], v[10:11], v[6:7]
	v_add_f32_e32 v2, 1.0, v2
	v_rcp_f32_e32 v32, v2
	v_mul_f32_e32 v2, 0xbfb8aa3b, v17
	v_exp_f32_e32 v2, v2
	s_nop 0
	v_add_f32_e32 v2, 1.0, v2
	v_rcp_f32_e32 v33, v2
	v_mul_f32_e32 v2, 0xbfb8aa3b, v18
	v_exp_f32_e32 v2, v2
	v_pk_mul_f32 v[16:17], v[16:17], v[32:33]
	s_nop 0
	v_pk_mul_f32 v[16:17], v[24:25], v[16:17]
	v_add_f32_e32 v2, 1.0, v2
	v_rcp_f32_e32 v24, v2
	v_mul_f32_e32 v2, 0xbfb8aa3b, v19
	v_exp_f32_e32 v2, v2


	s_nop 0
	v_add_f32_e32 v2, 1.0, v2
	v_rcp_f32_e32 v25, v2
	v_mov_b32_dpp v32, v62 row_ror:1 row_mask:0xf bank_mask:0xf
	v_mov_b32_dpp v33, v63 row_ror:1 row_mask:0xf bank_mask:0xf
	v_pk_mul_f32 v[18:19], v[18:19], v[24:25]


	v_pk_mul_f32 v[18:19], v[26:27], v[18:19]
	v_mov_b32_dpp v24, v60 row_ror:1 row_mask:0xf bank_mask:0xf
	v_mov_b32_dpp v25, v61 row_ror:1 row_mask:0xf bank_mask:0xf

	s_nop 0
	v_mov_b32_dpp v24, v48 row_shr:1 row_mask:0xf bank_mask:0xf

	v_mov_b32_dpp v25, v49 row_shr:1 row_mask:0xf bank_mask:0xf
	v_mov_b32_dpp v32, v46 row_shr:1 row_mask:0xf bank_mask:0xf
	v_mov_b32_dpp v33, v47 row_shr:1 row_mask:0xf bank_mask:0xf
	v_mov_b32_dpp v26, v36 row_ror:15 row_mask:0xf bank_mask:0xf
	v_mov_b32_dpp v27, v37 row_ror:15 row_mask:0xf bank_mask:0xf
	v_pk_mul_f32 v[20:21], v[142:143], v[32:33]
	v_pk_mul_f32 v[22:23], v[140:141], v[24:25]
	v_mov_b32_dpp v26, v48 row_shl:1 row_mask:0xf bank_mask:0xf
	v_mov_b32_dpp v27, v49 row_shl:1 row_mask:0xf bank_mask:0xf
	v_pk_fma_f32 v[22:23], v[48:49], v[144:145], v[22:23]
	v_pk_fma_f32 v[20:21], v[46:47], v[146:147], v[20:21]
	v_pk_fma_f32 v[22:23], v[132:133], v[26:27], v[22:23]
	v_pk_fma_f32 v[20:21], v[134:135], v[34:35], v[20:21]
	v_pk_add_f32 v[22:23], v[136:137], v[22:23]
	v_pk_add_f32 v[20:21], v[138:139], v[20:21]
	v_pk_mul_f32 v[12:13], v[12:13], v[22:23]
	v_pk_mul_f32 v[14:15], v[14:15], v[20:21]
	v_cvt_pk_bf16_f32 v12, v12, v13
	v_cvt_pk_bf16_f32 v13, v14, v15
	v_add_co_u32_e32 v14, vcc, s60, v44

	s_nop 0
	s_nop 0
	v_addc_co_u32_e32 v15, vcc, 0, v45, vcc
	global_store_dwordx2 v[14:15], v[12:13], off


	v_mov_b32_dpp v12, v48 row_ror:1 row_mask:0xf bank_mask:0xf
	v_mov_b32_dpp v13, v49 row_ror:1 row_mask:0xf bank_mask:0xf
	v_mov_b32_dpp v20, v46 row_ror:1 row_mask:0xf bank_mask:0xf
	v_mov_b32_dpp v21, v47 row_ror:1 row_mask:0xf bank_mask:0xf

	v_mov_b32_dpp v12, v36 row_shr:1 row_mask:0xf bank_mask:0xf

	v_mov_b32_dpp v13, v37 row_shr:1 row_mask:0xf bank_mask:0xf

	v_mov_b32_dpp v20, v38 row_shr:1 row_mask:0xf bank_mask:0xf

	v_mov_b32_dpp v21, v39 row_shr:1 row_mask:0xf bank_mask:0xf
	v_mov_b32_dpp v14, v28 row_ror:15 row_mask:0xf bank_mask:0xf
	v_mov_b32_dpp v15, v29 row_ror:15 row_mask:0xf bank_mask:0xf
	v_mov_b32_dpp v22, v30 row_ror:15 row_mask:0xf bank_mask:0xf
	v_mov_b32_dpp v23, v31 row_ror:15 row_mask:0xf bank_mask:0xf
	v_pk_mul_f32 v[8:9], v[142:143], v[20:21]
	v_pk_mul_f32 v[10:11], v[140:141], v[12:13]
	v_mov_b32_dpp v14, v36 row_shl:1 row_mask:0xf bank_mask:0xf
	v_mov_b32_dpp v15, v37 row_shl:1 row_mask:0xf bank_mask:0xf
	v_mov_b32_dpp v22, v38 row_shl:1 row_mask:0xf bank_mask:0xf
	v_mov_b32_dpp v23, v39 row_shl:1 row_mask:0xf bank_mask:0xf
	v_pk_fma_f32 v[10:11], v[36:37], v[144:145], v[10:11]
	v_pk_fma_f32 v[8:9], v[38:39], v[146:147], v[8:9]
	v_pk_fma_f32 v[10:11], v[132:133], v[14:15], v[10:11]
	v_pk_fma_f32 v[8:9], v[134:135], v[22:23], v[8:9]
	v_pk_add_f32 v[10:11], v[136:137], v[10:11]
	v_pk_add_f32 v[8:9], v[138:139], v[8:9]
	v_pk_mul_f32 v[4:5], v[4:5], v[10:11]
	v_pk_mul_f32 v[6:7], v[6:7], v[8:9]
	s_mov_b32 s60, 0xa0000
	v_cvt_pk_bf16_f32 v4, v4, v5
	v_cvt_pk_bf16_f32 v5, v6, v7
	v_add_co_u32_e32 v6, vcc, s60, v44

	s_nop 0
	s_nop 0
	v_addc_co_u32_e32 v7, vcc, 0, v45, vcc
	global_store_dwordx2 v[6:7], v[4:5], off


	v_mov_b32_dpp v4, v36 row_ror:1 row_mask:0xf bank_mask:0xf
	v_mov_b32_dpp v5, v37 row_ror:1 row_mask:0xf bank_mask:0xf
	v_mov_b32_dpp v8, v38 row_ror:1 row_mask:0xf bank_mask:0xf
	v_mov_b32_dpp v9, v39 row_ror:1 row_mask:0xf bank_mask:0xf
	v_mov_b32_dpp v4, v28 row_shr:1 row_mask:0xf bank_mask:0xf
	v_mov_b32_dpp v5, v29 row_shr:1 row_mask:0xf bank_mask:0xf
	v_mov_b32_dpp v8, v30 row_shr:1 row_mask:0xf bank_mask:0xf
	v_mov_b32_dpp v9, v31 row_shr:1 row_mask:0xf bank_mask:0xf
	v_mov_b32_e32 v6, v3
	v_mov_b32_e32 v7, v3
	v_mov_b32_e32 v10, v3
	v_mov_b32_e32 v11, v3
	v_pk_mul_f32 v[8:9], v[142:143], v[8:9]
	v_pk_mul_f32 v[4:5], v[140:141], v[4:5]
	v_mov_b32_dpp v6, v28 row_shl:1 row_mask:0xf bank_mask:0xf
	v_mov_b32_dpp v7, v29 row_shl:1 row_mask:0xf bank_mask:0xf
	v_mov_b32_dpp v10, v30 row_shl:1 row_mask:0xf bank_mask:0xf
	v_mov_b32_dpp v11, v31 row_shl:1 row_mask:0xf bank_mask:0xf
	v_pk_fma_f32 v[8:9], v[30:31], v[146:147], v[8:9]
	v_pk_fma_f32 v[4:5], v[28:29], v[144:145], v[4:5]
	v_pk_fma_f32 v[8:9], v[134:135], v[10:11], v[8:9]
	v_pk_fma_f32 v[4:5], v[132:133], v[6:7], v[4:5]
	v_pk_add_f32 v[6:7], v[138:139], v[8:9]
	v_pk_add_f32 v[4:5], v[136:137], v[4:5]
	v_pk_mul_f32 v[6:7], v[18:19], v[6:7]
	v_pk_mul_f32 v[4:5], v[16:17], v[4:5]
	s_nop 0
	v_cvt_pk_bf16_f32 v4, v4, v5
	v_cvt_pk_bf16_f32 v5, v6, v7
	v_add_co_u32_e32 v6, vcc, 0xb0000, v44
	s_nop 1
	v_addc_co_u32_e32 v7, vcc, 0, v45, vcc
	global_store_dwordx2 v[6:7], v[4:5], off
	s_and_saveexec_b64 s[60:61], s[40:41]
	s_cbranch_execz .LBB0_165
	v_lshl_add_u64 v[6:7], s[48:49], 0, v[156:157]
	v_lshlrev_b64 v[6:7], 11, v[6:7]
	v_lshl_add_u64 v[6:7], s[36:37], 0, v[6:7]
	v_cvt_pk_bf16_f32 v4, v28, v29
	v_cvt_pk_bf16_f32 v5, v30, v31
	v_lshl_add_u64 v[6:7], v[164:165], 1, v[6:7]
	global_store_dwordx2 v[6:7], v[4:5], off
	s_and_b64 exec, exec, s[44:45]
	s_cbranch_execz .LBB0_165
	s_mul_hi_i32 s49, s59, 0x3000
	s_mulk_i32 s59, 0x3000
	s_add_u32 s48, s36, s59
	s_addc_u32 s49, s37, s49
	v_lshl_add_u64 v[6:7], v[164:165], 1, s[48:49]
	v_add_co_u32_e32 v6, vcc, 0x2000, v6
	v_cvt_pk_bf16_f32 v4, v16, v17
	v_cvt_pk_bf16_f32 v5, v18, v19
	v_addc_co_u32_e32 v7, vcc, 0, v7, vcc
	global_store_dwordx2 v[6:7], v[4:5], off offset:2048

.LBB0_318:
	s_lshl_b32 s6, s36, 3
	s_add_i32 s6, s6, s87
	s_ashr_i32 s7, s6, s59
	v_mbcnt_lo_u32_b32 v1, -1, 0
	v_mbcnt_hi_u32_b32 v1, -1, v1
	s_and_b32 s10, s7, 15
	v_add_u32_e32 v6, s29, v1
	s_bfe_u32 s37, s7, 0x10004
	v_cmp_gt_i32_e32 vcc, 64, v6
	s_barrier


	s_waitcnt vmcnt(0)
	s_load_dwordx2 s[40:41], s[0:1], 0x48
	s_load_dwordx2 s[42:43], s[0:1], 0x58
	v_lshlrev_b32_e32 v4, 9, v6
	v_and_b32_e32 v4, 0xe000, v4
	s_lshl_b32 s11, s37, 16
	v_or_b32_e32 v4, s11, v4
	v_lshlrev_b32_e32 v4, 2, v4
	v_lshrrev_b32_e32 v5, 1, v6
	v_and_b32_e32 v5, 0xc0, v5
	v_and_b32_e32 v0, 15, v1
	v_lshl_add_u32 v5, v0, 2, v5
	s_lshl_b32 s96, s10, 8
	v_add3_u32 v4, v4, v5, s96
	v_mov_b32_e32 v5, 0
	v_lshlrev_b32_e32 v7, 4, v6
	s_waitcnt lgkmcnt(0)
	v_lshl_add_u64 v[8:9], s[40:41], 0, v[4:5]
	v_lshl_add_u64 v[10:11], s[42:43], 0, v[4:5]
	v_lshl_add_u64 v[8:9], v[8:9], 0, s[14:15]
	global_load_dword v12, v[8:9], off offset:-4096
	global_load_dword v13, v[8:9], off
	v_lshl_add_u64 v[8:9], v[8:9], 0, s[16:17]
	global_load_dword v14, v[8:9], off offset:-4096
	global_load_dword v15, v[8:9], off
	v_lshl_add_u64 v[8:9], v[8:9], 0, s[16:17]
	global_load_dword v16, v[8:9], off offset:-4096
	global_load_dword v17, v[8:9], off
	v_lshl_add_u64 v[8:9], v[8:9], 0, s[16:17]
	global_load_dword v18, v[8:9], off offset:-4096
	global_load_dword v19, v[8:9], off
	v_lshl_add_u64 v[10:11], v[10:11], 0, s[14:15]
	global_load_dword v20, v[10:11], off offset:-4096
	global_load_dword v21, v[10:11], off
	v_lshl_add_u64 v[10:11], v[10:11], 0, s[16:17]
	global_load_dword v22, v[10:11], off offset:-4096
	global_load_dword v23, v[10:11], off
	v_lshl_add_u64 v[10:11], v[10:11], 0, s[16:17]
	global_load_dword v24, v[10:11], off offset:-4096
	global_load_dword v25, v[10:11], off
	v_lshl_add_u64 v[10:11], v[10:11], 0, s[16:17]
	global_load_dword v26, v[10:11], off offset:-4096
	global_load_dword v27, v[10:11], off
	s_and_saveexec_b64 s[8:9], vcc
	s_cbranch_execz .Lp1_cdone
	s_load_dwordx4 s[40:43], s[0:1], 0x38
	s_load_dwordx2 s[20:21], s[0:1], 0x50
	s_load_dwordx4 s[44:47], s[0:1], 0x60
	s_load_dwordx2 s[38:39], s[0:1], 0x70
	s_add_i32 s11, s10, s87
	v_lshl_add_u32 v28, s11, 6, v1
	v_lshl_add_u32 v29, s37, 10, v28
	v_lshl_add_u32 v30, s37, 6, v6
	v_lshlrev_b32_e32 v28, 2, v28
	v_lshlrev_b32_e32 v29, 2, v29
	v_lshlrev_b32_e32 v30, 2, v30
	v_add_u32_e32 v31, 0x2000, v28
	v_add_u32_e32 v30, 0x4000, v30
	v_lshlrev_b32_e32 v2, 2, v6
	s_waitcnt lgkmcnt(0)
	global_load_dword v32, v28, s[40:41]
	global_load_dword v33, v31, s[40:41] offset:-4096
	global_load_dword v34, v31, s[40:41]
	global_load_dword v35, v29, s[42:43]
	global_load_dword v36, v29, s[20:21]
	global_load_dword v37, v28, s[44:45]
	global_load_dword v38, v28, s[46:47]
	global_load_dword v39, v28, s[38:39]
	global_load_dword v40, v30, s[40:41]
	global_load_dword v41, v30, s[40:41] offset:512
	s_waitcnt vmcnt(0)
	v_mul_f32_e32 v35, 0xbfb8aa3b, v35
	v_mul_f32_e32 v36, 0xbfb8aa3b, v36
	ds_write2st64_b32 v2, v32, v33 offset0:64 offset1:65
	ds_write2st64_b32 v2, v34, v35 offset0:66 offset1:67
	ds_write2st64_b32 v2, v36, v37 offset0:68 offset1:69
	ds_write2st64_b32 v2, v38, v39 offset0:70 offset1:71
	ds_write2st64_b32 v2, v40, v41 offset0:72 offset1:73
.Lp1_cdone:
	s_or_b64 exec, exec, s[8:9]
	s_waitcnt vmcnt(0)
	v_mul_f32_e32 v12, 0xbfb8aa3b, v12
	v_mul_f32_e32 v13, 0xbfb8aa3b, v13
	v_mul_f32_e32 v14, 0xbfb8aa3b, v14
	v_mul_f32_e32 v15, 0xbfb8aa3b, v15
	v_mul_f32_e32 v16, 0xbfb8aa3b, v16
	v_mul_f32_e32 v17, 0xbfb8aa3b, v17
	v_mul_f32_e32 v18, 0xbfb8aa3b, v18
	v_mul_f32_e32 v19, 0xbfb8aa3b, v19
	v_mul_f32_e32 v20, 0xbfb8aa3b, v20
	v_mul_f32_e32 v21, 0xbfb8aa3b, v21
	v_mul_f32_e32 v22, 0xbfb8aa3b, v22
	v_mul_f32_e32 v23, 0xbfb8aa3b, v23
	v_mul_f32_e32 v24, 0xbfb8aa3b, v24
	v_mul_f32_e32 v25, 0xbfb8aa3b, v25
	v_mul_f32_e32 v26, 0xbfb8aa3b, v26
	v_mul_f32_e32 v27, 0xbfb8aa3b, v27
	v_cvt_pk_bf16_f32 v12, v12, v13
	v_cvt_pk_bf16_f32 v13, v14, v15
	v_cvt_pk_bf16_f32 v14, v16, v17
	v_cvt_pk_bf16_f32 v15, v18, v19
	v_cvt_pk_bf16_f32 v20, v20, v21
	v_cvt_pk_bf16_f32 v21, v22, v23
	v_cvt_pk_bf16_f32 v22, v24, v25
	v_cvt_pk_bf16_f32 v23, v26, v27
	ds_write_b128 v7, v[12:15]
	ds_write_b128 v7, v[20:23] offset:8192
	s_lshl_b32 s96, s10, 6
	v_mov_b64_e32 v[208:209], s[96:97]
	v_and_b32_e32 v2, 63, v1
	v_bfe_u32 v8, v1, 4, 2
	s_waitcnt lgkmcnt(0)
	s_barrier
	s_and_b32 s8, s6, s61
	v_lshlrev_b32_e32 v2, 2, v8
	v_cmp_eq_u32_e32 vcc, v2, v0
	v_or_b32_e32 v4, 1, v2
	s_ashr_i32 s9, s7, 5
	v_cndmask_b32_e64 v24, 0, 1.0, vcc
	v_cmp_eq_u32_e32 vcc, v4, v0
	v_or_b32_e32 v4, 2, v2
	v_or_b32_e32 v2, 3, v2
	v_cndmask_b32_e64 v25, 0, 1.0, vcc
	v_cmp_eq_u32_e32 vcc, v4, v0
	s_lshl_b32 s7, s8, 8
	s_cmp_eq_u32 s37, 0
	v_cndmask_b32_e64 v26, 0, 1.0, vcc
	v_cmp_eq_u32_e32 vcc, v2, v0
	v_or_b32_e32 v0, s7, v0
	v_xad_u32 v2, v0, -1, s58
	s_cselect_b64 s[38:39], -1, 0
	v_cndmask_b32_e64 v0, v2, v0, s[38:39]
	s_lshl_b32 s10, s9, s92
	v_add_u32_e32 v0, s10, v0
	v_mov_b64_e32 v[4:5], s[4:5]
	v_mad_i64_i32 v[4:5], s[8:9], v0, s62, v[4:5]
	v_lshl_add_u64 v[6:7], v[208:209], 1, v[4:5]
	v_lshlrev_b32_e32 v2, 3, v8
	v_lshl_add_u64 v[6:7], v[6:7], 0, v[2:3]
	s_lshl_b32 s96, s37, 7
	v_cndmask_b32_e64 v27, 0, 1.0, vcc
	v_lshl_add_u64 v[8:9], v[6:7], 0, s[22:23]
	v_add_co_u32_e32 v6, vcc, s31, v6
	v_lshl_add_u64 v[4:5], v[4:5], 0, s[96:97]
	v_and_b32_e32 v2, 48, v1
	v_addc_co_u32_e32 v7, vcc, 0, v7, vcc
	v_lshl_add_u64 v[0:1], v[4:5], 0, v[2:3]
	v_lshl_add_u64 v[4:5], v[0:1], 0, s[24:25]
	v_add_co_u32_e32 v0, vcc, 0x3000, v0
	global_load_dwordx2 v[210:211], v[6:7], off offset:2048
	global_load_dwordx2 v[212:213], v[8:9], off offset:32
	global_load_dwordx2 v[214:215], v[8:9], off offset:64
	global_load_dwordx2 v[216:217], v[8:9], off offset:96
	v_addc_co_u32_e32 v1, vcc, 0, v1, vcc
	global_load_dwordx4 v[132:135], v[4:5], off offset:256
	global_load_dwordx4 v[140:143], v[4:5], off offset:64
	global_load_dwordx4 v[144:147], v[0:1], off
	global_load_dwordx4 v[136:139], v[4:5], off offset:320
	global_load_dwordx2 v[202:203], v[8:9], off offset:2048
	global_load_dwordx2 v[240:241], v[8:9], off offset:2080
	global_load_dwordx2 v[242:243], v[8:9], off offset:2112
	global_load_dwordx2 v[244:245], v[8:9], off offset:2144
	s_movk_i32 s100, 0x260
	v_mov_b32_e32 v12, 0
	s_lshl_b32 s8, s37, 6
	s_mov_b32 s20, 0
	s_sub_i32 s11, s50, s7
	s_lshl_b32 s96, s8, 1
	v_mov_b32_e32 v13, v12
	v_mov_b32_e32 v14, v12
	v_mov_b32_e32 v15, v12
	v_mov_b32_e32 v96, v12
	v_mov_b32_e32 v97, v12
	v_mov_b32_e32 v98, v12
	v_mov_b32_e32 v99, v12
	v_mov_b32_e32 v108, v12
	v_mov_b32_e32 v109, v12
	v_mov_b32_e32 v110, v12
	v_mov_b32_e32 v111, v12
	v_mov_b32_e32 v68, v12
	v_mov_b32_e32 v69, v12
	v_mov_b32_e32 v70, v12
	v_mov_b32_e32 v71, v12
	v_mov_b32_e32 v72, v24
	v_mov_b32_e32 v73, v25
	v_mov_b32_e32 v74, v26
	v_mov_b32_e32 v75, v27
	v_mov_b32_e32 v36, v12
	v_mov_b32_e32 v37, v12
	v_mov_b32_e32 v38, v12
	v_mov_b32_e32 v39, v12
	v_mov_b32_e32 v32, v12
	v_mov_b32_e32 v33, v12
	v_mov_b32_e32 v34, v12
	v_mov_b32_e32 v35, v12
	v_mov_b32_e32 v116, v12
	v_mov_b32_e32 v117, v12
	v_mov_b32_e32 v118, v12
	v_mov_b32_e32 v119, v12
	v_mov_b32_e32 v124, v12
	v_mov_b32_e32 v125, v12
	v_mov_b32_e32 v126, v12
	v_mov_b32_e32 v127, v12
	v_mov_b32_e32 v16, v24
	v_mov_b32_e32 v17, v25
	v_mov_b32_e32 v18, v26
	v_mov_b32_e32 v19, v27
	v_mov_b32_e32 v20, v12
	v_mov_b32_e32 v21, v12
	v_mov_b32_e32 v22, v12
	v_mov_b32_e32 v23, v12
	v_mov_b32_e32 v56, v12
	v_mov_b32_e32 v57, v12
	v_mov_b32_e32 v58, v12
	v_mov_b32_e32 v59, v12
	v_mov_b32_e32 v44, v12
	v_mov_b32_e32 v45, v12
	v_mov_b32_e32 v46, v12
	v_mov_b32_e32 v47, v12
	v_mov_b32_e32 v28, v12
	v_mov_b32_e32 v29, v12
	v_mov_b32_e32 v30, v12
	v_mov_b32_e32 v31, v12
	v_mov_b32_e32 v4, v24
	v_mov_b32_e32 v5, v25
	v_mov_b32_e32 v6, v26
	v_mov_b32_e32 v7, v27
	v_mov_b32_e32 v104, v12
	v_mov_b32_e32 v105, v12
	v_mov_b32_e32 v106, v12
	v_mov_b32_e32 v107, v12
	v_mov_b32_e32 v88, v12
	v_mov_b32_e32 v89, v12
	v_mov_b32_e32 v90, v12
	v_mov_b32_e32 v91, v12
	v_mov_b32_e32 v40, v12
	v_mov_b32_e32 v41, v12
	v_mov_b32_e32 v42, v12
	v_mov_b32_e32 v43, v12
	v_mov_b32_e32 v8, v12
	v_mov_b32_e32 v9, v12
	v_mov_b32_e32 v10, v12
	v_mov_b32_e32 v11, v12
	v_mov_b32_e32 v92, v12
	v_mov_b32_e32 v93, v12
	v_mov_b32_e32 v94, v12
	v_mov_b32_e32 v95, v12
	v_mov_b32_e32 v80, v12
	v_mov_b32_e32 v81, v12
	v_mov_b32_e32 v82, v12
	v_mov_b32_e32 v83, v12
	v_mov_b32_e32 v64, v12
	v_mov_b32_e32 v65, v12
	v_mov_b32_e32 v66, v12
	v_mov_b32_e32 v67, v12
	v_mov_b32_e32 v52, v12
	v_mov_b32_e32 v53, v12
	v_mov_b32_e32 v54, v12
	v_mov_b32_e32 v55, v12
	v_mov_b32_e32 v128, v12
	v_mov_b32_e32 v129, v12
	v_mov_b32_e32 v130, v12
	v_mov_b32_e32 v131, v12
	v_mov_b32_e32 v84, v12
	v_mov_b32_e32 v85, v12
	v_mov_b32_e32 v86, v12
	v_mov_b32_e32 v87, v12
	v_mov_b32_e32 v100, v12
	v_mov_b32_e32 v101, v12
	v_mov_b32_e32 v102, v12
	v_mov_b32_e32 v103, v12
	v_mov_b32_e32 v60, v12
	v_mov_b32_e32 v61, v12
	v_mov_b32_e32 v62, v12
	v_mov_b32_e32 v63, v12
	v_mov_b32_e32 v120, v12
	v_mov_b32_e32 v121, v12
	v_mov_b32_e32 v122, v12
	v_mov_b32_e32 v123, v12
	v_mov_b32_e32 v112, v12
	v_mov_b32_e32 v113, v12
	v_mov_b32_e32 v114, v12
	v_mov_b32_e32 v115, v12
	v_mov_b32_e32 v76, v12
	v_mov_b32_e32 v77, v12
	v_mov_b32_e32 v78, v12
	v_mov_b32_e32 v79, v12
	v_mov_b32_e32 v48, v12
	v_mov_b32_e32 v49, v12
	v_mov_b32_e32 v50, v12
	v_mov_b32_e32 v51, v12
	s_branch .LBB0_328
.LBB0_327:
	s_or_b64 exec, exec, s[8:9]
	s_waitcnt lgkmcnt(2)
	v_add_f32_e32 v150, v150, v182
	v_add_f32_e32 v151, v151, v183
	v_add_f32_e32 v152, v152, v184
	v_add_f32_e32 v153, v153, v185
	v_exp_f32_e32 v150, v150
	v_exp_f32_e32 v151, v151
	v_exp_f32_e32 v152, v152
	v_exp_f32_e32 v153, v153
	v_add_f32_e32 v150, 1.0, v150
	v_add_f32_e32 v151, 1.0, v151
	v_add_f32_e32 v152, 1.0, v152
	v_add_f32_e32 v153, 1.0, v153
	v_rcp_f32_e32 v150, v150
	v_rcp_f32_e32 v151, v151
	v_rcp_f32_e32 v152, v152
	v_rcp_f32_e32 v153, v153
	v_mul_f32_e32 v164, v186, v194
	v_mul_f32_e32 v165, v187, v195
	v_mul_f32_e32 v148, v170, v192
	v_mul_f32_e32 v149, v171, v193
	v_rcp_f32_e32 v166, v236
	v_cvt_pk_bf16_f32 v148, v148, v149
	v_cvt_pk_bf16_f32 v149, v164, v165
	v_rcp_f32_e32 v164, v232
	v_rcp_f32_e32 v165, v233
	v_rcp_f32_e32 v167, v237
	s_waitcnt lgkmcnt(1)
	v_mul_f32_e32 v170, v180, v198
	v_mul_f32_e32 v171, v181, v199
	v_mov_b32_e32 v180, v230
	v_mov_b32_e32 v181, v230
	v_mul_f32_e32 v170, v180, v170
	v_mul_f32_e32 v171, v181, v171
	v_add_f32_e32 v180, -1.0, v150
	v_add_f32_e32 v181, -1.0, v151
	v_add_f32_e32 v182, -1.0, v152
	v_add_f32_e32 v183, -1.0, v153
	s_waitcnt lgkmcnt(0)
	v_fma_f32 v174, v174, v180, 1.0
	v_fma_f32 v175, v175, v181, 1.0
	v_fma_f32 v176, v176, v182, 1.0
	v_fma_f32 v177, v177, v183, 1.0
	v_mul_f32_e32 v174, v174, v196
	v_mul_f32_e32 v175, v175, v197
	v_mul_f32_e32 v176, v176, v198
	v_mul_f32_e32 v177, v177, v199
	v_mul_f32_e32 v184, v170, v152
	v_mul_f32_e32 v185, v171, v153
	v_mul_f32_e32 v152, v190, v234
	v_mul_f32_e32 v153, v191, v235
	v_mul_f32_e32 v154, v188, v154
	v_mul_f32_e32 v155, v189, v155
	v_mul_f32_e32 v180, v170, v224
	v_mul_f32_e32 v181, v171, v225
	v_mul_f32_e32 v176, v176, v166
	v_mul_f32_e32 v177, v177, v167
	v_mul_f32_e32 v170, v174, v164
	v_mul_f32_e32 v171, v175, v165
	v_cvt_pk_bf16_f32 v154, v154, v155
	v_cvt_pk_bf16_f32 v155, v152, v153
	v_mul_f32_e32 v174, v228, v220
	v_mul_f32_e32 v175, v229, v221
	v_mul_f32_e32 v152, v226, v218
	v_mul_f32_e32 v153, v227, v219
	v_cvt_pk_bf16_f32 v170, v170, v171
	v_cvt_pk_bf16_f32 v152, v152, v153
	v_cvt_pk_bf16_f32 v153, v174, v175
	v_cvt_pk_bf16_f32 v171, v176, v177
	v_mul_f32_e32 v178, v178, v196
	v_mul_f32_e32 v179, v179, v197
	v_mfma_f32_16x16x32_bf16 v[160:163], v[160:163], v[152:155], 0
	v_mul_f32_e64 v178, v230, v178
	v_mul_f32_e64 v179, v231, v179
	v_lshlrev_b32_e32 v200, 2, v249
	v_mul_f32_e32 v182, v178, v222
	v_mul_f32_e32 v183, v179, v223
	v_mul_f32_e32 v174, v178, v150
	v_mul_f32_e32 v175, v179, v151
	v_cvt_pk_bf16_f32 v150, v182, v183
	v_cvt_pk_bf16_f32 v151, v180, v181
	v_mul_f32_e32 v174, v174, v164
	v_mul_f32_e32 v175, v175, v165
	v_cmp_lt_u32_e64 s[40:41], v246, v200
	v_mfma_f32_16x16x32_bf16 v[160:163], v[168:171], v[148:151], v[160:163]
	v_mul_f32_e64 v168, v184, v166
	v_mul_f32_e64 v169, v185, v167
	v_cvt_pk_bf16_f32 v174, v174, v175
	v_cvt_pk_bf16_f32 v175, v168, v169
	v_mfma_f32_16x16x32_bf16 v[164:167], v[152:155], v[156:159], 0
	ds_write_b64 v2, v[170:171] offset:21344
	ds_write_b64 v2, v[174:175] offset:23648

	ds_write_b64 v2, v[0:1] offset:19040
	v_cmp_lt_u32_e32 vcc, v200, v246
	v_or_b32_e32 v180, 2, v200
	v_mfma_f32_16x16x32_bf16 v[156:159], v[156:159], v[152:155], 0
	v_or_b32_e32 v183, 3, v200
	v_lshlrev_b32_e32 v168, 3, v248
	v_and_b32_e32 v177, 24, v168
	v_mfma_f32_16x16x32_bf16 v[164:167], v[148:151], v[172:175], v[164:167]
	v_lshrrev_b32_e32 v176, 2, v246
	v_or_b32_e32 v176, v200, v176
	v_mul_u32_u24_e32 v176, 0x90, v176
	v_mfma_f32_16x16x32_bf16 v[156:159], v[172:175], v[148:151], v[156:159]
	v_or_b32_e32 v175, 1, v200
	s_nop 2
	v_cndmask_b32_e64 v0, 0, v164, s[40:41]
	v_cmp_eq_u32_e64 s[40:41], v200, v246
	v_cndmask_b32_e32 v172, 0, v160, vcc
	v_cndmask_b32_e64 v1, v165, 0, vcc
	v_cndmask_b32_e64 v174, 0, 1.0, s[40:41]
	v_cmp_lt_u32_e64 s[40:41], v175, v246
	v_cndmask_b32_e32 v173, 0, v156, vcc
	v_cmp_lt_u32_e32 vcc, v180, v246
	v_cndmask_b32_e64 v178, 0, v161, s[40:41]
	v_cndmask_b32_e64 v179, 0, v157, s[40:41]
	v_cmp_lt_u32_e64 s[40:41], v246, v180
	v_cndmask_b32_e32 v181, 0, v162, vcc
	v_cndmask_b32_e32 v182, 0, v158, vcc
	v_cndmask_b32_e64 v2, 0, v166, s[40:41]
	v_cmp_lt_u32_e32 vcc, v183, v246
	v_cmp_lt_u32_e64 s[40:41], v246, v183
	v_cvt_pk_bf16_f32 v0, v0, v1
	v_cndmask_b32_e32 v185, 0, v159, vcc
	v_cndmask_b32_e64 v156, 0, v167, s[40:41]
	v_cvt_pk_bf16_f32 v1, v2, v156
	v_mov_b32_e32 v2, v3
	v_cvt_pk_bf16_f32 v156, v173, v179
	v_cvt_pk_bf16_f32 v157, v182, v185
	v_mov_b32_e32 v158, v3
	v_mov_b32_e32 v159, v3
	v_cndmask_b32_e32 v184, 0, v163, vcc
	v_mov_b32_e32 v166, v3
	v_mfma_f32_16x16x32_bf16 v[160:163], v[0:3], v[156:159], 0
	v_mov_b32_e32 v167, v3
	v_cmp_eq_u32_e32 vcc, v175, v246
	v_cvt_pk_bf16_f32 v192, v172, v178
	v_mfma_f32_16x16x32_bf16 v[168:171], v[156:159], v[0:3], 0
	v_cndmask_b32_e64 v175, 0, 1.0, vcc
	s_nop 2
	v_cvt_pk_bf16_f32 v164, v160, v161
	v_cvt_pk_bf16_f32 v165, v162, v163
	v_cmp_eq_u32_e32 vcc, v180, v246
	v_cvt_pk_bf16_f32 v193, v181, v184
	v_cvt_pk_bf16_f32 v0, v168, v169
	v_cvt_pk_bf16_f32 v1, v170, v171
	v_cndmask_b32_e64 v180, 0, 1.0, vcc
	v_cmp_eq_u32_e32 vcc, v183, v246
	v_mfma_f32_16x16x32_bf16 v[168:171], v[164:167], v[0:3], 0
	v_sub_f32_e32 v172, v180, v182
	v_cndmask_b32_e64 v183, 0, 1.0, vcc
	v_mov_b32_e32 v194, v3
	v_mfma_f32_16x16x32_bf16 v[164:167], v[0:3], v[164:167], 0
	v_mov_b32_e32 v195, v3
	s_nop 2
	v_cvt_pk_bf16_f32 v168, v168, v169
	v_cvt_pk_bf16_f32 v169, v170, v171
	v_mfma_f32_16x16x32_bf16 v[156:159], v[0:3], v[156:159], 0
	v_mov_b32_e32 v170, v3
	v_cvt_pk_bf16_f32 v164, v164, v165
	v_cvt_pk_bf16_f32 v165, v166, v167
	v_mov_b32_e32 v166, v3
	v_mov_b32_e32 v167, v3
	v_mov_b32_e32 v171, v3
	v_sub_f32_e32 v1, v175, v179
	v_sub_f32_e32 v0, v174, v173
	v_mfma_f32_16x16x32_bf16 v[164:167], v[164:167], v[168:171], 0
	v_sub_f32_e32 v173, v183, v185
	v_add_f32_e32 v162, v162, v172
	v_add_f32_e32 v163, v163, v173
	v_add_f32_e32 v0, v160, v0
	v_add_f32_e32 v1, v161, v1
	v_sub_f32_e32 v159, v163, v159
	v_sub_f32_e32 v158, v162, v158
	v_sub_f32_e32 v157, v1, v157
	v_sub_f32_e32 v156, v0, v156
	v_cvt_pk_bf16_f32 v0, v156, v157
	v_cvt_pk_bf16_f32 v1, v158, v159
	v_mov_b32_e32 v162, v3
	v_mov_b32_e32 v163, v3
	v_mfma_f32_16x16x32_bf16 v[156:159], v[168:171], v[0:3], v[156:159]
	v_cvt_pk_bf16_f32 v0, v164, v165
	v_cvt_pk_bf16_f32 v1, v166, v167
	s_nop 5
	v_cvt_pk_bf16_f32 v160, v156, v157
	v_cvt_pk_bf16_f32 v161, v158, v159
	s_nop 1
	v_mfma_f32_16x16x32_bf16 v[170:173], v[0:3], v[160:163], v[156:159]
	v_add3_u32 v1, v176, v177, s33
	s_nop 6
	v_cvt_pk_bf16_f32 v0, v170, v171
	ds_read_b64_tr_b16 v[176:177], v1 offset:18944
	ds_read_b64_tr_b16 v[204:205], v1 offset:18976
	ds_read_b64_tr_b16 v[196:197], v1 offset:19008
	ds_read_b64_tr_b16 v[188:189], v1 offset:19040
	ds_read_b64_tr_b16 v[168:169], v1 offset:21248
	ds_read_b64_tr_b16 v[164:165], v1 offset:21280
	ds_read_b64_tr_b16 v[160:161], v1 offset:21312
	ds_read_b64_tr_b16 v[156:157], v1 offset:21344
	ds_read_b64_tr_b16 v[170:171], v1 offset:23552
	ds_read_b64_tr_b16 v[166:167], v1 offset:23584
	ds_read_b64_tr_b16 v[162:163], v1 offset:23616
	ds_read_b64_tr_b16 v[158:159], v1 offset:23648
	v_cvt_pk_bf16_f32 v1, v172, v173
	s_setprio 1
	v_cvt_pk_bf16_f32 v172, v104, v105
	v_cvt_pk_bf16_f32 v173, v106, v107
	v_cvt_pk_bf16_f32 v174, v92, v93
	v_cvt_pk_bf16_f32 v175, v94, v95
	v_cvt_pk_bf16_f32 v178, v128, v129
	v_cvt_pk_bf16_f32 v179, v130, v131
	v_mfma_f32_16x16x32_bf16 v[172:175], v[152:155], v[172:175], 0
	v_cvt_pk_bf16_f32 v180, v120, v121
	v_cvt_pk_bf16_f32 v181, v122, v123
	v_cvt_pk_bf16_f32 v182, v112, v113
	v_cvt_pk_bf16_f32 v183, v114, v115
	v_mfma_f32_16x16x32_bf16 v[172:175], v[148:151], v[178:181], v[172:175]
	v_mov_b32_e32 v178, v3
	v_mov_b32_e32 v179, v3
	v_cvt_pk_bf16_f32 v180, v84, v85
	v_cvt_pk_bf16_f32 v181, v86, v87
	s_waitcnt lgkmcnt(11)
	v_mfma_f32_16x16x32_bf16 v[172:175], v[192:195], v[176:179], v[172:175]
	v_mov_b32_e32 v206, v3
	v_mov_b32_e32 v207, v3
	v_cvt_pk_bf16_f32 v218, v100, v101
	v_cvt_pk_bf16_f32 v219, v102, v103
	v_cvt_pk_bf16_f32 v220, v76, v77
	s_nop 2
	v_cvt_pk_bf16_f32 v172, v172, v173
	v_cvt_pk_bf16_f32 v173, v174, v175
	v_mov_b32_e32 v174, v3
	v_mov_b32_e32 v175, v3
	v_cvt_pk_bf16_f32 v221, v78, v79
	v_mov_b32_e32 v198, v3
	v_mfma_f32_16x16x32_bf16 v[172:175], v[0:3], v[172:175], 0
	v_mov_b32_e32 v199, v3
	ds_read_b128 v[184:187], v247 offset:26048
	s_nop 5


	v_cvt_pk_bf16_f32 v178, -v172, -v173


	v_cvt_pk_bf16_f32 v179, -v174, -v175
	v_cvt_pk_bf16_f32 v172, v88, v89
	v_cvt_pk_bf16_f32 v173, v90, v91
	v_cvt_pk_bf16_f32 v174, v80, v81
	v_cvt_pk_bf16_f32 v175, v82, v83
	s_waitcnt lgkmcnt(4)
	v_mfma_f32_16x16x32_bf16 v[104:107], v[168:171], v[176:179], v[104:107]
	v_mfma_f32_16x16x32_bf16 v[172:175], v[152:155], v[172:175], 0
	v_mfma_f32_16x16x32_bf16 v[172:175], v[148:151], v[180:183], v[172:175]
	v_mfma_f32_16x16x32_bf16 v[180:183], v[192:195], v[204:207], v[172:175]
	s_waitcnt lgkmcnt(3)
	v_mfma_f32_16x16x32_bf16 v[92:95], v[164:167], v[176:179], v[92:95]
	s_nop 4
	ds_read_b128 v[172:175], v247 offset:25856
	v_cvt_pk_bf16_f32 v180, v180, v181
	v_cvt_pk_bf16_f32 v181, v182, v183
	v_mov_b32_e32 v182, v3
	v_mov_b32_e32 v183, v3
	s_waitcnt lgkmcnt(3)
	v_mfma_f32_16x16x32_bf16 v[128:131], v[160:163], v[176:179], v[128:131]
	s_waitcnt lgkmcnt(2)
	v_mfma_f32_16x16x32_bf16 v[120:123], v[156:159], v[176:179], v[120:123]
	v_mfma_f32_16x16x32_bf16 v[176:179], v[0:3], v[180:183], 0
	ds_read_b128 v[180:183], v247 offset:25984
	s_waitcnt lgkmcnt(2)
	s_nop 4
	v_mul_f32_e32 v122, v122, v186
	v_mul_f32_e32 v123, v123, v187
	v_mul_f32_e32 v120, v120, v184
	v_mul_f32_e32 v121, v121, v185
	s_waitcnt lgkmcnt(0)
	v_mul_f32_e32 v130, v130, v182
	v_mul_f32_e32 v131, v131, v183
	v_mul_f32_e32 v128, v128, v180
	v_mul_f32_e32 v129, v129, v181


	v_cvt_pk_bf16_f32 v206, -v176, -v177


	v_cvt_pk_bf16_f32 v207, -v178, -v179
	ds_read_b128 v[176:179], v247 offset:25920
	v_mul_f32_e32 v106, v106, v174
	v_mul_f32_e32 v107, v107, v175
	v_mfma_f32_16x16x32_bf16 v[88:91], v[168:171], v[204:207], v[88:91]
	v_mul_f32_e64 v104, v104, v172
	v_mul_f32_e64 v105, v105, v173
	s_waitcnt lgkmcnt(0)
	v_mul_f32_e32 v94, v94, v178
	v_mul_f32_e32 v95, v95, v179
	v_mfma_f32_16x16x32_bf16 v[80:83], v[164:167], v[204:207], v[80:83]
	v_mul_f32_e64 v92, v92, v176
	v_mul_f32_e64 v93, v93, v177

	v_mul_f32_e32 v90, v174, v90
	v_mul_f32_e32 v91, v175, v91
	v_mul_f32_e32 v88, v172, v88
	v_mul_f32_e32 v89, v173, v89
	v_mfma_f32_16x16x32_bf16 v[84:87], v[160:163], v[204:207], v[84:87]
	v_mfma_f32_16x16x32_bf16 v[112:115], v[156:159], v[204:207], v[112:115]
	v_cvt_pk_bf16_f32 v204, v40, v41
	v_cvt_pk_bf16_f32 v205, v42, v43
	v_cvt_pk_bf16_f32 v206, v64, v65
	v_cvt_pk_bf16_f32 v207, v66, v67
	v_mul_f32_e32 v82, v178, v82
	v_mul_f32_e32 v83, v179, v83
	v_mul_f32_e32 v80, v176, v80
	v_mul_f32_e32 v81, v177, v81
	v_mfma_f32_16x16x32_bf16 v[204:207], v[152:155], v[204:207], 0
	v_mul_f32_e64 v86, v182, v86
	v_mul_f32_e64 v87, v183, v87
	v_mul_f32_e32 v84, v180, v84
	v_mul_f32_e32 v85, v181, v85
	v_mul_f32_e32 v114, v186, v114
	v_mul_f32_e32 v115, v187, v115
	v_mfma_f32_16x16x32_bf16 v[204:207], v[148:151], v[218:221], v[204:207]
	v_mul_f32_e64 v112, v184, v112
	v_mul_f32_e64 v113, v185, v113
	v_mfma_f32_16x16x32_bf16 v[204:207], v[192:195], v[196:199], v[204:207]
	s_nop 7
	v_cvt_pk_bf16_f32 v204, v204, v205
	v_cvt_pk_bf16_f32 v205, v206, v207
	v_mov_b32_e32 v206, v3
	v_mov_b32_e32 v207, v3
	s_nop 1
	v_mfma_f32_16x16x32_bf16 v[204:207], v[0:3], v[204:207], 0
	s_nop 7


	v_cvt_pk_bf16_f32 v198, -v204, -v205


	v_cvt_pk_bf16_f32 v199, -v206, -v207
	v_cvt_pk_bf16_f32 v204, v60, v61
	v_cvt_pk_bf16_f32 v205, v62, v63
	v_mfma_f32_16x16x32_bf16 v[40:43], v[168:171], v[196:199], v[40:43]
	v_cvt_pk_bf16_f32 v206, v48, v49
	v_cvt_pk_bf16_f32 v207, v50, v51
	v_mov_b32_e32 v190, v3
	v_mfma_f32_16x16x32_bf16 v[64:67], v[164:167], v[196:199], v[64:67]
	v_mov_b32_e32 v191, v3
	s_nop 2
	v_mul_f32_e32 v42, v174, v42
	v_mul_f32_e32 v43, v175, v43
	v_mul_f32_e32 v40, v172, v40
	v_mul_f32_e32 v41, v173, v41
	v_mfma_f32_16x16x32_bf16 v[100:103], v[160:163], v[196:199], v[100:103]
	v_mfma_f32_16x16x32_bf16 v[76:79], v[156:159], v[196:199], v[76:79]
	v_cvt_pk_bf16_f32 v196, v8, v9
	v_cvt_pk_bf16_f32 v197, v10, v11
	v_cvt_pk_bf16_f32 v198, v52, v53
	v_cvt_pk_bf16_f32 v199, v54, v55
	v_mul_f32_e32 v66, v178, v66
	v_mul_f32_e32 v67, v179, v67
	v_mul_f32_e32 v64, v176, v64
	v_mul_f32_e32 v65, v177, v65
	v_mfma_f32_16x16x32_bf16 v[196:199], v[152:155], v[196:199], 0
	v_mul_f32_e64 v102, v182, v102
	v_mul_f32_e64 v103, v183, v103
	v_mul_f32_e32 v100, v180, v100
	v_mul_f32_e32 v101, v181, v101
	v_mul_f32_e32 v78, v186, v78
	v_mul_f32_e32 v79, v187, v79
	v_mfma_f32_16x16x32_bf16 v[196:199], v[148:151], v[204:207], v[196:199]
	v_mul_f32_e64 v76, v184, v76
	v_mul_f32_e64 v77, v185, v77
	v_mfma_f32_16x16x32_bf16 v[190:193], v[192:195], v[188:191], v[196:199]
	v_cvt_pk_bf16_f32 v194, v56, v57
	v_cvt_pk_bf16_f32 v195, v58, v59
	s_nop 5
	v_cvt_pk_bf16_f32 v190, v190, v191
	v_cvt_pk_bf16_f32 v191, v192, v193
	v_mov_b32_e32 v192, v3
	v_mov_b32_e32 v193, v3
	s_nop 1
	v_mfma_f32_16x16x32_bf16 v[190:193], v[0:3], v[190:193], 0
	s_nop 7


	v_cvt_pk_bf16_f32 v190, -v190, -v191


	v_cvt_pk_bf16_f32 v191, -v192, -v193
	v_cvt_pk_bf16_f32 v192, v116, v117
	v_cvt_pk_bf16_f32 v193, v118, v119
	v_mfma_f32_16x16x32_bf16 v[8:11], v[168:171], v[188:191], v[8:11]
	v_mfma_f32_16x16x32_bf16 v[52:55], v[164:167], v[188:191], v[52:55]
	v_mfma_f32_16x16x32_bf16 v[60:63], v[160:163], v[188:191], v[60:63]
	s_nop 5
	v_mul_f32_e64 v10, v174, v10
	v_mul_f32_e64 v11, v175, v11
	v_mul_f32_e32 v8, v172, v8
	v_mul_f32_e32 v9, v173, v9
	v_mul_f32_e32 v54, v178, v54
	v_mul_f32_e32 v55, v179, v55
	v_mfma_f32_16x16x32_bf16 v[48:51], v[156:159], v[188:191], v[48:51]
	v_cvt_pk_bf16_f32 v188, v24, v25
	v_cvt_pk_bf16_f32 v189, v26, v27
	v_cvt_pk_bf16_f32 v190, v68, v69
	v_cvt_pk_bf16_f32 v191, v70, v71
	v_mul_f32_e32 v52, v176, v52
	v_mul_f32_e32 v53, v177, v53
	v_mul_f32_e32 v62, v182, v62
	v_mul_f32_e32 v63, v183, v63
	v_mfma_f32_16x16x32_bf16 v[188:191], v[152:155], v[188:191], 0
	v_mul_f32_e64 v60, v180, v60
	v_mul_f32_e64 v61, v181, v61
	v_mul_f32_e32 v50, v186, v50
	v_mul_f32_e32 v51, v187, v51
	v_mul_f32_e32 v48, v184, v48
	v_mul_f32_e32 v49, v185, v49
	v_mfma_f32_16x16x32_bf16 v[188:191], v[148:151], v[192:195], v[188:191]
	v_cvt_pk_bf16_f32 v194, v44, v45
	v_cvt_pk_bf16_f32 v195, v46, v47
	s_nop 5
	v_cvt_pk_bf16_f32 v188, v188, v189
	v_cvt_pk_bf16_f32 v189, v190, v191
	v_mov_b32_e32 v190, v3
	v_mov_b32_e32 v191, v3
	s_nop 1
	v_mfma_f32_16x16x32_bf16 v[188:191], v[0:3], v[188:191], 0
	s_nop 7


	v_cvt_pk_bf16_f32 v192, -v188, -v189


	v_cvt_pk_bf16_f32 v193, -v190, -v191
	v_mov_b32_e32 v190, v3
	v_mov_b32_e32 v191, v3
	v_cvt_pk_bf16_f32 v188, v12, v13
	v_cvt_pk_bf16_f32 v189, v14, v15
	v_mfma_f32_16x16x32_bf16 v[24:27], v[168:171], v[190:193], v[24:27]
	v_mfma_f32_16x16x32_bf16 v[68:71], v[164:167], v[190:193], v[68:71]
	v_mfma_f32_16x16x32_bf16 v[116:119], v[160:163], v[190:193], v[116:119]
	s_nop 5
	v_mul_f32_e64 v26, v174, v26
	v_mul_f32_e64 v27, v175, v27
	v_mul_f32_e32 v24, v172, v24
	v_mul_f32_e32 v25, v173, v25
	v_mul_f32_e32 v70, v178, v70
	v_mul_f32_e32 v71, v179, v71
	v_mfma_f32_16x16x32_bf16 v[56:59], v[156:159], v[190:193], v[56:59]
	v_cvt_pk_bf16_f32 v190, v72, v73
	v_cvt_pk_bf16_f32 v191, v74, v75
	v_cvt_pk_bf16_f32 v192, v124, v125
	v_cvt_pk_bf16_f32 v193, v126, v127
	v_mfma_f32_16x16x32_bf16 v[188:191], v[152:155], v[188:191], 0
	v_mul_f32_e64 v68, v176, v68
	v_mul_f32_e64 v69, v177, v69
	v_mul_f32_e32 v118, v182, v118
	v_mul_f32_e32 v119, v183, v119
	v_mul_f32_e32 v116, v180, v116
	v_mul_f32_e32 v117, v181, v117
	v_mfma_f32_16x16x32_bf16 v[188:191], v[148:151], v[192:195], v[188:191]
	v_cvt_pk_bf16_f32 v194, v28, v29
	v_cvt_pk_bf16_f32 v195, v30, v31
	v_mul_f32_e32 v58, v186, v58
	v_mul_f32_e32 v59, v187, v59
	v_mul_f32_e32 v56, v184, v56
	v_mul_f32_e32 v57, v185, v57
	s_nop 1
	v_cvt_pk_bf16_f32 v188, v188, v189
	v_cvt_pk_bf16_f32 v189, v190, v191
	v_mov_b32_e32 v190, v3
	v_mov_b32_e32 v191, v3
	s_nop 1
	v_mfma_f32_16x16x32_bf16 v[188:191], v[0:3], v[188:191], 0
	s_nop 7


	v_cvt_pk_bf16_f32 v192, -v188, -v189


	v_cvt_pk_bf16_f32 v193, -v190, -v191
	v_mov_b32_e32 v190, v3
	v_mov_b32_e32 v191, v3
	v_cvt_pk_bf16_f32 v188, v96, v97
	v_cvt_pk_bf16_f32 v189, v98, v99
	v_mfma_f32_16x16x32_bf16 v[12:15], v[168:171], v[190:193], v[12:15]
	v_mfma_f32_16x16x32_bf16 v[72:75], v[164:167], v[190:193], v[72:75]
	v_mfma_f32_16x16x32_bf16 v[124:127], v[160:163], v[190:193], v[124:127]
	s_nop 5
	v_mul_f32_e64 v14, v174, v14
	v_mul_f32_e64 v15, v175, v15
	v_mul_f32_e32 v12, v172, v12
	v_mul_f32_e32 v13, v173, v13
	v_mul_f32_e32 v74, v178, v74
	v_mul_f32_e32 v75, v179, v75
	v_mfma_f32_16x16x32_bf16 v[44:47], v[156:159], v[190:193], v[44:47]
	v_cvt_pk_bf16_f32 v190, v36, v37
	v_cvt_pk_bf16_f32 v191, v38, v39
	v_cvt_pk_bf16_f32 v192, v16, v17
	v_cvt_pk_bf16_f32 v193, v18, v19
	v_mfma_f32_16x16x32_bf16 v[188:191], v[152:155], v[188:191], 0
	v_mul_f32_e64 v72, v176, v72
	v_mul_f32_e64 v73, v177, v73
	v_mul_f32_e32 v126, v182, v126
	v_mul_f32_e32 v127, v183, v127
	v_mul_f32_e32 v124, v180, v124
	v_mul_f32_e32 v125, v181, v125
	v_mfma_f32_16x16x32_bf16 v[188:191], v[148:151], v[192:195], v[188:191]
	v_cvt_pk_bf16_f32 v194, v4, v5
	v_cvt_pk_bf16_f32 v195, v6, v7
	v_mul_f32_e32 v46, v186, v46
	v_mul_f32_e32 v47, v187, v47
	v_mul_f32_e32 v44, v184, v44
	v_mul_f32_e32 v45, v185, v45
	s_nop 1
	v_cvt_pk_bf16_f32 v188, v188, v189
	v_cvt_pk_bf16_f32 v189, v190, v191
	v_mov_b32_e32 v190, v3
	v_mov_b32_e32 v191, v3
	s_nop 1
	v_mfma_f32_16x16x32_bf16 v[188:191], v[0:3], v[188:191], 0
	s_nop 7


	v_cvt_pk_bf16_f32 v192, -v188, -v189


	v_cvt_pk_bf16_f32 v193, -v190, -v191
	v_mov_b32_e32 v190, v3
	v_mov_b32_e32 v191, v3
	v_cvt_pk_bf16_f32 v188, v108, v109
	v_cvt_pk_bf16_f32 v189, v110, v111
	v_mfma_f32_16x16x32_bf16 v[96:99], v[168:171], v[190:193], v[96:99]
	v_mfma_f32_16x16x32_bf16 v[36:39], v[164:167], v[190:193], v[36:39]
	v_mfma_f32_16x16x32_bf16 v[16:19], v[160:163], v[190:193], v[16:19]
	s_nop 5
	v_mul_f32_e64 v98, v174, v98
	v_mul_f32_e64 v99, v175, v99
	v_mul_f32_e32 v96, v172, v96
	v_mul_f32_e32 v97, v173, v97
	v_mul_f32_e32 v38, v178, v38
	v_mul_f32_e32 v39, v179, v39
	v_mfma_f32_16x16x32_bf16 v[28:31], v[156:159], v[190:193], v[28:31]
	v_cvt_pk_bf16_f32 v190, v32, v33
	v_cvt_pk_bf16_f32 v191, v34, v35
	v_cvt_pk_bf16_f32 v192, v20, v21
	v_cvt_pk_bf16_f32 v193, v22, v23
	v_mfma_f32_16x16x32_bf16 v[152:155], v[152:155], v[188:191], 0
	v_mul_f32_e64 v36, v176, v36
	v_mul_f32_e64 v37, v177, v37
	v_mul_f32_e32 v18, v182, v18
	v_mul_f32_e32 v19, v183, v19
	v_mul_f32_e32 v16, v180, v16
	v_mul_f32_e32 v17, v181, v17
	v_mfma_f32_16x16x32_bf16 v[148:151], v[148:151], v[192:195], v[152:155]
	v_mul_f32_e64 v30, v186, v30
	v_mul_f32_e64 v31, v187, v31
	v_mul_f32_e32 v28, v184, v28
	v_mul_f32_e32 v29, v185, v29
	s_nop 3
	v_cvt_pk_bf16_f32 v148, v148, v149
	v_cvt_pk_bf16_f32 v149, v150, v151
	v_mov_b32_e32 v150, v3
	v_mov_b32_e32 v151, v3
	s_nop 1
	v_mfma_f32_16x16x32_bf16 v[148:151], v[0:3], v[148:151], 0
	s_nop 7


	v_cvt_pk_bf16_f32 v152, -v148, -v149


	v_cvt_pk_bf16_f32 v153, -v150, -v151
	v_mov_b32_e32 v150, v3
	v_mov_b32_e32 v151, v3
	s_nop 1
	v_mfma_f32_16x16x32_bf16 v[108:111], v[168:171], v[150:153], v[108:111]
	v_mfma_f32_16x16x32_bf16 v[32:35], v[164:167], v[150:153], v[32:35]
	v_mfma_f32_16x16x32_bf16 v[20:23], v[160:163], v[150:153], v[20:23]
	s_nop 5
	v_mul_f32_e64 v110, v174, v110
	v_mul_f32_e64 v111, v175, v111
	v_mul_f32_e32 v108, v172, v108
	v_mul_f32_e32 v109, v173, v109
	v_mul_f32_e32 v34, v178, v34
	v_mul_f32_e32 v35, v179, v35
	v_mfma_f32_16x16x32_bf16 v[4:7], v[156:159], v[150:153], v[4:7]
	v_mul_f32_e64 v32, v176, v32
	v_mul_f32_e64 v33, v177, v33
	v_mul_f32_e32 v22, v182, v22
	v_mul_f32_e32 v23, v183, v23
	v_mul_f32_e32 v20, v180, v20
	v_mul_f32_e32 v21, v181, v21
	s_nop 1
	v_mul_f32_e32 v6, v186, v6
	v_mul_f32_e32 v7, v187, v7
	v_mul_f32_e32 v4, v184, v4
	v_mul_f32_e32 v5, v185, v5
	s_setprio 0
	s_add_i32 s11, s11, -16
	s_cmpk_eq_i32 s20, 0x100
	s_cbranch_scc1 .LBB0_317

.LBB0_528:
	s_lshl_b32 s8, s51, 3
	s_add_i32 s8, s8, s87
	s_ashr_i32 s9, s8, s59
	v_mbcnt_lo_u32_b32 v68, -1, 0
	v_mbcnt_hi_u32_b32 v68, -1, v68
	s_and_b32 s54, s9, 15
	v_add_u32_e32 v1, s29, v68
	s_bfe_u32 s55, s9, 0x10004
	v_cmp_gt_i32_e32 vcc, 64, v1
	s_barrier


	s_waitcnt vmcnt(0)
	s_load_dwordx2 s[40:41], s[0:1], 0x48
	s_load_dwordx2 s[42:43], s[0:1], 0x58
	v_lshlrev_b32_e32 v4, 9, v1
	v_and_b32_e32 v4, 0xe000, v4
	s_lshl_b32 s38, s55, 16
	v_or_b32_e32 v4, s38, v4
	v_lshlrev_b32_e32 v4, 2, v4
	v_lshrrev_b32_e32 v5, 1, v1
	v_and_b32_e32 v5, 0xc0, v5
	v_and_b32_e32 v0, 15, v68
	v_lshl_add_u32 v5, v0, 2, v5
	s_lshl_b32 s96, s54, 8
	v_add3_u32 v4, v4, v5, s96
	v_mov_b32_e32 v5, 0
	v_lshlrev_b32_e32 v7, 4, v1
	s_waitcnt lgkmcnt(0)
	v_lshl_add_u64 v[8:9], s[40:41], 0, v[4:5]
	v_lshl_add_u64 v[10:11], s[42:43], 0, v[4:5]
	v_lshl_add_u64 v[8:9], v[8:9], 0, s[14:15]
	global_load_dword v12, v[8:9], off offset:-4096
	global_load_dword v13, v[8:9], off
	v_lshl_add_u64 v[8:9], v[8:9], 0, s[16:17]
	global_load_dword v14, v[8:9], off offset:-4096
	global_load_dword v15, v[8:9], off
	v_lshl_add_u64 v[8:9], v[8:9], 0, s[16:17]
	global_load_dword v16, v[8:9], off offset:-4096
	global_load_dword v17, v[8:9], off
	v_lshl_add_u64 v[8:9], v[8:9], 0, s[16:17]
	global_load_dword v18, v[8:9], off offset:-4096
	global_load_dword v19, v[8:9], off
	v_lshl_add_u64 v[10:11], v[10:11], 0, s[14:15]
	global_load_dword v20, v[10:11], off offset:-4096
	global_load_dword v21, v[10:11], off
	v_lshl_add_u64 v[10:11], v[10:11], 0, s[16:17]
	global_load_dword v22, v[10:11], off offset:-4096
	global_load_dword v23, v[10:11], off
	v_lshl_add_u64 v[10:11], v[10:11], 0, s[16:17]
	global_load_dword v24, v[10:11], off offset:-4096
	global_load_dword v25, v[10:11], off
	v_lshl_add_u64 v[10:11], v[10:11], 0, s[16:17]
	global_load_dword v26, v[10:11], off offset:-4096
	global_load_dword v27, v[10:11], off
	s_and_saveexec_b64 s[10:11], vcc
	s_cbranch_execz .Lp2_cdone
	s_load_dwordx4 s[40:43], s[0:1], 0x38
	s_load_dwordx2 s[20:21], s[0:1], 0x50
	s_load_dwordx4 s[44:47], s[0:1], 0x60
	s_load_dwordx2 s[34:35], s[0:1], 0x70
	s_add_i32 s38, s54, s87
	v_lshl_add_u32 v28, s38, 6, v68
	v_lshl_add_u32 v29, s55, 10, v28
	v_lshl_add_u32 v30, s55, 6, v1
	v_lshlrev_b32_e32 v28, 2, v28
	v_lshlrev_b32_e32 v29, 2, v29
	v_lshlrev_b32_e32 v30, 2, v30
	v_add_u32_e32 v31, 0x2000, v28
	v_add_u32_e32 v30, 0x4000, v30
	v_lshlrev_b32_e32 v2, 2, v1
	s_waitcnt lgkmcnt(0)
	global_load_dword v32, v28, s[40:41]
	global_load_dword v33, v31, s[40:41] offset:-4096
	global_load_dword v34, v31, s[40:41]
	global_load_dword v35, v29, s[42:43]
	global_load_dword v36, v29, s[20:21]
	global_load_dword v37, v28, s[44:45]
	global_load_dword v38, v28, s[46:47]
	global_load_dword v39, v28, s[34:35]
	global_load_dword v40, v30, s[40:41]
	global_load_dword v41, v30, s[40:41] offset:512
	s_waitcnt vmcnt(0)
	v_mul_f32_e32 v35, 0xbfb8aa3b, v35
	v_mul_f32_e32 v36, 0xbfb8aa3b, v36
	ds_write2st64_b32 v2, v32, v33 offset0:64 offset1:65
	ds_write2st64_b32 v2, v34, v35 offset0:66 offset1:67
	ds_write2st64_b32 v2, v36, v37 offset0:68 offset1:69
	ds_write2st64_b32 v2, v38, v39 offset0:70 offset1:71
	ds_write2st64_b32 v2, v40, v41 offset0:72 offset1:73
.Lp2_cdone:
	s_or_b64 exec, exec, s[10:11]
	s_waitcnt vmcnt(0)
	v_mul_f32_e32 v12, 0xbfb8aa3b, v12
	v_mul_f32_e32 v13, 0xbfb8aa3b, v13
	v_mul_f32_e32 v14, 0xbfb8aa3b, v14
	v_mul_f32_e32 v15, 0xbfb8aa3b, v15
	v_mul_f32_e32 v16, 0xbfb8aa3b, v16
	v_mul_f32_e32 v17, 0xbfb8aa3b, v17
	v_mul_f32_e32 v18, 0xbfb8aa3b, v18
	v_mul_f32_e32 v19, 0xbfb8aa3b, v19
	v_mul_f32_e32 v20, 0xbfb8aa3b, v20
	v_mul_f32_e32 v21, 0xbfb8aa3b, v21
	v_mul_f32_e32 v22, 0xbfb8aa3b, v22
	v_mul_f32_e32 v23, 0xbfb8aa3b, v23
	v_mul_f32_e32 v24, 0xbfb8aa3b, v24
	v_mul_f32_e32 v25, 0xbfb8aa3b, v25
	v_mul_f32_e32 v26, 0xbfb8aa3b, v26
	v_mul_f32_e32 v27, 0xbfb8aa3b, v27
	v_cvt_pk_bf16_f32 v12, v12, v13
	v_cvt_pk_bf16_f32 v13, v14, v15
	v_cvt_pk_bf16_f32 v14, v16, v17
	v_cvt_pk_bf16_f32 v15, v18, v19
	v_cvt_pk_bf16_f32 v20, v20, v21
	v_cvt_pk_bf16_f32 v21, v22, v23
	v_cvt_pk_bf16_f32 v22, v24, v25
	v_cvt_pk_bf16_f32 v23, v26, v27
	ds_write_b128 v7, v[12:15]
	ds_write_b128 v7, v[20:23] offset:8192
	s_lshl_b32 s96, s54, 6
	v_mov_b64_e32 v[152:153], s[96:97]
	s_ashr_i32 s11, s9, 5
	s_ashr_i32 s9, s8, 31
	s_and_b32 s10, s8, s61
	v_and_b32_e32 v1, 63, v68
	s_lshl_b64 s[8:9], s[8:9], 14
	s_waitcnt lgkmcnt(0)
	s_barrier
	s_add_u32 s8, s48, s8
	s_waitcnt vmcnt(11)
	v_lshlrev_b32_e32 v4, 2, v1
	s_addc_u32 s9, s49, s9
	v_ashrrev_i32_e32 v5, 31, v4
	s_lshl_b32 s52, s10, 8
	s_waitcnt vmcnt(4)
	v_lshl_add_u64 v[48:49], v[4:5], 2, s[8:9]
	s_cmp_eq_u32 s55, 0
	v_or_b32_e32 v0, s52, v0
	v_add_co_u32_e32 v50, vcc, s31, v48
	v_xad_u32 v1, v0, -1, s58
	s_cselect_b64 s[38:39], -1, 0
	v_addc_co_u32_e32 v51, vcc, 0, v49, vcc
	v_cndmask_b32_e64 v0, v1, v0, s[38:39]
	s_lshl_b32 s53, s11, s92
	s_waitcnt vmcnt(3)
	v_add_co_u32_e32 v44, vcc, s19, v48
	v_add_u32_e32 v2, s53, v0
	v_mov_b64_e32 v[0:1], s[4:5]
	v_addc_co_u32_e32 v45, vcc, 0, v49, vcc
	v_mad_i64_i32 v[70:71], s[8:9], v2, s62, v[0:1]
	v_lshlrev_b64 v[80:81], 1, v[152:153]
	v_lshrrev_b32_e32 v0, 1, v68
	v_add_co_u32_e32 v64, vcc, s64, v48
	v_and_b32_e32 v2, 24, v0
	v_lshl_add_u64 v[0:1], v[70:71], 0, v[80:81]
	v_addc_co_u32_e32 v65, vcc, 0, v49, vcc
	v_lshl_add_u64 v[0:1], v[0:1], 0, v[2:3]
	v_add_co_u32_e32 v66, vcc, s31, v0
	s_waitcnt vmcnt(2)
	v_lshl_add_u64 v[72:73], v[0:1], 0, s[22:23]
	v_addc_co_u32_e32 v67, vcc, 0, v1, vcc
	v_lshl_add_u64 v[74:75], v[0:1], 0, s[16:17]
	s_waitcnt vmcnt(1)
	v_lshl_add_u64 v[76:77], v[0:1], 0, s[14:15]
	v_add_co_u32_e32 v0, vcc, s19, v0
	global_load_dwordx4 v[16:19], v[48:49], off
	global_load_dwordx4 v[4:7], v[48:49], off offset:1024
	global_load_dwordx4 v[8:11], v[48:49], off offset:2048
	global_load_dwordx4 v[12:15], v[48:49], off offset:3072
	v_addc_co_u32_e32 v1, vcc, 0, v1, vcc
	global_load_dwordx4 v[20:23], v[50:51], off offset:1024
	global_load_dwordx4 v[24:27], v[50:51], off offset:2048
	global_load_dwordx4 v[28:31], v[44:45], off offset:-4096
	global_load_dwordx4 v[32:35], v[44:45], off
	global_load_dwordx4 v[36:39], v[44:45], off offset:1024
	global_load_dwordx4 v[40:43], v[44:45], off offset:2048
	s_nop 0
	global_load_dwordx4 v[44:47], v[44:45], off offset:3072
	s_nop 0
	global_load_dwordx4 v[60:63], v[50:51], off offset:3072
	global_load_dwordx4 v[56:59], v[64:65], off
	s_nop 0
	global_load_dwordx4 v[48:51], v[64:65], off offset:1024
	global_load_dwordx4 v[52:55], v[64:65], off offset:2048
	global_load_dwordx2 v[158:159], v[66:67], off offset:2048
	global_load_dwordx2 v[124:125], v[0:1], off
	global_load_dwordx2 v[138:139], v[66:67], off
	s_nop 0
	global_load_dwordx4 v[64:67], v[64:65], off offset:3072
	s_nop 0
	global_load_dwordx2 v[156:157], v[72:73], off offset:32
	global_load_dwordx2 v[182:183], v[74:75], off offset:32
	global_load_dwordx2 v[160:161], v[72:73], off offset:64
	global_load_dwordx2 v[140:141], v[74:75], off offset:64
	global_load_dwordx2 v[162:163], v[72:73], off offset:96
	global_load_dwordx2 v[136:137], v[76:77], off offset:32
	global_load_dwordx2 v[134:135], v[76:77], off offset:64
	global_load_dwordx2 v[132:133], v[76:77], off offset:96
	global_load_dwordx2 v[0:1], v[74:75], off offset:96
	s_lshl_b32 s96, s55, 7
	v_lshl_add_u64 v[70:71], v[70:71], 0, s[96:97]
	v_and_b32_e32 v2, 48, v68
	v_lshl_add_u64 v[68:69], v[70:71], 0, v[2:3]
	v_add_co_u32_e32 v76, vcc, s64, v68
	v_lshl_add_u64 v[82:83], v[68:69], 0, s[24:25]
	s_nop 0
	v_addc_co_u32_e32 v77, vcc, 0, v69, vcc
	global_load_dwordx4 v[68:71], v[82:83], off offset:256
	global_load_dwordx4 v[72:75], v[82:83], off offset:64
	s_nop 0
	global_load_dwordx4 v[76:79], v[76:77], off
	s_nop 0
	global_load_dwordx4 v[84:87], v[82:83], off offset:320
	s_lshl_b32 s34, s55, 6
	s_lshl_b32 s8, s55, 14
	s_lshl_b32 s10, s54, 2
	s_add_u32 s10, s36, s10
	s_addc_u32 s11, s37, 0
	s_ashr_i32 s21, s53, 31
	s_add_u32 s20, s8, s53
	s_mov_b32 s9, s97
	s_addc_u32 s21, 0, s21
	v_lshl_add_u64 v[154:155], s[6:7], 0, v[80:81]
	s_sub_i32 s54, s50, s52
	s_mov_b32 s55, 16
	s_lshl_b32 s96, s34, 1
	s_branch .LBB0_538
.LBB0_537:
	s_or_b64 exec, exec, s[34:35]
	v_mul_f32_e32 v84, v84, v198
	v_mul_f32_e32 v85, v85, v199
	v_mul_f32_e32 v0, v86, v232
	v_mul_f32_e32 v1, v87, v233
	v_lshlrev_b32_e32 v86, 3, v238
	v_cvt_pk_bf16_f32 v90, v84, v85
	v_mul_f32_e32 v84, v196, v88
	v_mul_f32_e32 v85, v197, v89
	v_and_b32_e32 v132, 24, v86
	v_cvt_pk_bf16_f32 v86, v84, v85
	v_mul_f32_e32 v84, v210, v208
	v_mul_f32_e32 v85, v211, v209
	v_mul_f32_e32 v88, v130, v192
	v_mul_f32_e32 v89, v131, v193
	v_cvt_pk_bf16_f32 v99, v84, v85
	v_cvt_pk_bf16_f32 v98, v88, v89
	v_mul_f32_e32 v84, v186, v148
	v_mul_f32_e32 v85, v187, v149
	v_mul_f32_e32 v88, v184, v146
	v_mul_f32_e32 v89, v185, v147
	v_cvt_pk_bf16_f32 v97, v84, v85
	v_cvt_pk_bf16_f32 v96, v88, v89
	s_waitcnt lgkmcnt(0)
	v_cvt_pk_bf16_f32 v91, v0, v1
	v_mul_f32_e32 v0, v230, v92
	v_mul_f32_e32 v1, v231, v93
	v_mfma_f32_16x16x32_bf16 v[92:95], v[104:107], v[96:99], 0
	v_cvt_pk_bf16_f32 v87, v0, v1
	v_mul_f32_e32 v0, v224, v222
	v_mul_f32_e32 v1, v225, v223
	v_mul_f32_e32 v84, v220, v216
	v_mul_f32_e32 v85, v221, v217
	v_cvt_pk_bf16_f32 v89, v0, v1
	v_cvt_pk_bf16_f32 v88, v84, v85
	v_mfma_f32_16x16x32_bf16 v[126:129], v[100:103], v[96:99], 0
	v_mul_f32_e64 v0, v218, v134
	v_mul_f32_e64 v1, v219, v135
	v_mul_f32_e32 v84, v182, v120
	v_mul_f32_e32 v85, v183, v121
	v_lshlrev_b32_e32 v150, 2, v246
	v_mfma_f32_16x16x32_bf16 v[122:125], v[116:119], v[88:91], v[92:95]
	v_lshrrev_b32_e32 v2, 2, v237
	v_cvt_pk_bf16_f32 v84, v84, v85
	v_cvt_pk_bf16_f32 v85, v0, v1
	v_mfma_f32_16x16x32_bf16 v[92:95], v[96:99], v[100:103], 0
	v_mul_f32_e64 v0, v190, v110
	v_mul_f32_e64 v1, v191, v111
	v_mul_f32_e32 v120, v188, v108
	v_mul_f32_e32 v121, v189, v109
	v_or_b32_e32 v2, v150, v2
	v_mfma_f32_16x16x32_bf16 v[108:111], v[88:91], v[112:115], v[92:95]
	v_mul_u32_u24_e32 v133, 0x90, v2
	v_cmp_eq_u32_e64 s[42:43], v150, v237
	v_or_b32_e32 v2, 1, v150
	v_mfma_f32_16x16x32_bf16 v[126:129], v[112:115], v[88:91], v[126:129]
	v_cvt_pk_bf16_f32 v95, v0, v1
	v_mul_f32_e32 v0, v144, v138
	v_mul_f32_e32 v1, v145, v139
	v_mul_f32_e32 v92, v142, v140
	v_mul_f32_e32 v93, v143, v141
	v_cmp_lt_u32_e64 s[40:41], v237, v150
	v_cndmask_b32_e64 v131, 0, 1.0, s[42:43]
	v_cmp_lt_u32_e64 s[42:43], v2, v237
	v_cvt_pk_bf16_f32 v94, v120, v121
	v_cvt_pk_bf16_f32 v92, v92, v93
	v_cvt_pk_bf16_f32 v93, v0, v1
	v_cndmask_b32_e64 v1, 0, v108, s[40:41]
	v_cndmask_b32_e64 v108, 0, v123, s[42:43]
	v_cndmask_b32_e64 v134, 0, v127, s[42:43]
	v_cmp_eq_u32_e64 s[42:43], v2, v237
	v_or_b32_e32 v2, 2, v150
	v_mfma_f32_16x16x32_bf16 v[100:103], v[100:103], v[92:95], 0
	v_cndmask_b32_e64 v135, 0, 1.0, s[42:43]
	v_cmp_lt_u32_e64 s[42:43], v2, v237
	v_cmp_lt_u32_e64 s[44:45], v237, v2
	v_cmp_lt_u32_e32 vcc, v150, v237
	v_cndmask_b32_e64 v121, 0, v124, s[42:43]
	v_cndmask_b32_e64 v136, 0, v128, s[42:43]
	v_cmp_eq_u32_e64 s[42:43], v2, v237
	v_or_b32_e32 v2, 3, v150
	v_cndmask_b32_e32 v130, 0, v126, vcc
	v_cndmask_b32_e64 v137, 0, 1.0, s[42:43]
	v_cmp_lt_u32_e64 s[42:43], v2, v237
	v_mfma_f32_16x16x32_bf16 v[100:103], v[112:115], v[84:87], v[100:103]
	v_cvt_pk_bf16_f32 v112, v130, v134
	v_cndmask_b32_e64 v138, 0, v129, s[42:43]
	v_cvt_pk_bf16_f32 v113, v136, v138
	v_mov_b32_e32 v114, v3
	v_mov_b32_e32 v115, v3
	v_cmp_lt_u32_e64 s[46:47], v237, v2
	v_cndmask_b32_e32 v0, 0, v122, vcc
	v_cndmask_b32_e64 v109, v109, 0, vcc
	v_cndmask_b32_e64 v110, 0, v110, s[44:45]
	v_cndmask_b32_e64 v111, 0, v111, s[46:47]
	v_cndmask_b32_e64 v122, 0, v125, s[42:43]
	v_cmp_eq_u32_e64 s[42:43], v2, v237
	v_cvt_pk_bf16_f32 v120, v0, v108
	v_cvt_pk_bf16_f32 v0, v1, v109
	v_cvt_pk_bf16_f32 v1, v110, v111
	v_mov_b32_e32 v2, v3
	v_mfma_f32_16x16x32_bf16 v[104:107], v[104:107], v[92:95], 0
	v_cvt_pk_bf16_f32 v121, v121, v122
	v_cndmask_b32_e64 v140, v100, 0, s[40:41]
	v_mov_b32_e32 v124, v3
	v_mfma_f32_16x16x32_bf16 v[108:111], v[112:115], v[0:3], 0
	v_mov_b32_e32 v125, v3
	v_cndmask_b32_e32 v141, 0, v101, vcc
	v_cndmask_b32_e64 v143, v102, 0, s[44:45]
	v_mfma_f32_16x16x32_bf16 v[104:107], v[116:119], v[84:87], v[104:107]
	v_cndmask_b32_e64 v139, 0, 1.0, s[42:43]
	v_mfma_f32_16x16x32_bf16 v[116:119], v[0:3], v[112:115], 0
	s_nop 1
	v_cvt_pk_bf16_f32 v0, v108, v109
	v_cvt_pk_bf16_f32 v1, v110, v111
	s_nop 1
	v_cndmask_b32_e64 v104, v104, 0, s[40:41]
	v_cndmask_b32_e32 v100, 0, v105, vcc
	v_cndmask_b32_e64 v111, v103, 0, s[46:47]
	v_cvt_pk_bf16_f32 v122, v116, v117
	v_cvt_pk_bf16_f32 v123, v118, v119
	v_cvt_pk_bf16_f32 v108, v104, v100
	v_mfma_f32_16x16x32_bf16 v[112:115], v[0:3], v[112:115], 0
	v_cndmask_b32_e64 v142, v106, 0, s[44:45]
	v_cndmask_b32_e64 v109, v107, 0, s[46:47]
	v_mov_b32_e32 v106, v3
	v_mfma_f32_16x16x32_bf16 v[100:103], v[0:3], v[122:125], 0
	v_mov_b32_e32 v107, v3
	v_cvt_pk_bf16_f32 v109, v142, v109
	v_cvt_pk_bf16_f32 v110, v140, v141
	v_mfma_f32_16x16x32_bf16 v[126:129], v[122:125], v[0:3], 0
	v_sub_f32_e32 v1, v135, v134
	s_nop 2
	v_cvt_pk_bf16_f32 v100, v100, v101
	v_cvt_pk_bf16_f32 v101, v102, v103
	v_mov_b32_e32 v102, v3
	v_mov_b32_e32 v103, v3
	v_cvt_pk_bf16_f32 v104, v126, v127
	v_cvt_pk_bf16_f32 v105, v128, v129
	v_sub_f32_e32 v0, v131, v130
	v_sub_f32_e32 v123, v139, v138
	v_mfma_f32_16x16x32_bf16 v[100:103], v[100:103], v[104:107], 0
	v_sub_f32_e32 v122, v137, v136
	v_add_f32_e32 v118, v118, v122
	v_add_f32_e32 v119, v119, v123
	v_add_f32_e32 v0, v116, v0
	v_add_f32_e32 v1, v117, v1
	v_sub_f32_e32 v115, v119, v115
	v_sub_f32_e32 v114, v118, v114
	v_sub_f32_e32 v113, v1, v113
	v_sub_f32_e32 v112, v0, v112
	v_cvt_pk_bf16_f32 v0, v112, v113
	v_cvt_pk_bf16_f32 v1, v114, v115
	v_cvt_pk_bf16_f32 v111, v143, v111
	v_mov_b32_e32 v122, v3
	v_mfma_f32_16x16x32_bf16 v[104:107], v[104:107], v[0:3], v[112:115]
	v_cvt_pk_bf16_f32 v0, v100, v101
	v_cvt_pk_bf16_f32 v1, v102, v103
	v_mov_b32_e32 v102, v3
	v_mov_b32_e32 v103, v3
	v_mov_b32_e32 v123, v3
	s_nop 2
	v_cvt_pk_bf16_f32 v100, v104, v105
	v_cvt_pk_bf16_f32 v101, v106, v107
	s_nop 1
	v_mfma_f32_16x16x32_bf16 v[100:103], v[0:3], v[100:103], v[104:107]
	v_add3_u32 v1, v133, v132, s33
	s_nop 6
	v_cvt_pk_bf16_f32 v0, v100, v101
	ds_read_b64_tr_b16 v[144:145], v1 offset:18944
	ds_read_b64_tr_b16 v[148:149], v1 offset:18976
	ds_read_b64_tr_b16 v[128:129], v1 offset:19008
	ds_read_b64_tr_b16 v[100:101], v1 offset:19040
	ds_read_b64_tr_b16 v[124:125], v1 offset:21248
	ds_read_b64_tr_b16 v[116:117], v1 offset:21280
	ds_read_b64_tr_b16 v[112:113], v1 offset:21312
	ds_read_b64_tr_b16 v[104:105], v1 offset:21344
	ds_read_b64_tr_b16 v[126:127], v1 offset:23552
	ds_read_b64_tr_b16 v[118:119], v1 offset:23584
	ds_read_b64_tr_b16 v[114:115], v1 offset:23616
	ds_read_b64_tr_b16 v[106:107], v1 offset:23648
	v_cvt_pk_bf16_f32 v1, v102, v103
	s_setprio 1
	v_cvt_pk_bf16_f32 v130, v16, v17
	v_cvt_pk_bf16_f32 v131, v18, v19
	v_cvt_pk_bf16_f32 v132, v28, v29
	v_cvt_pk_bf16_f32 v133, v30, v31
	v_cvt_pk_bf16_f32 v134, v32, v33
	v_cvt_pk_bf16_f32 v135, v34, v35
	v_mfma_f32_16x16x32_bf16 v[138:141], v[96:99], v[130:133], 0
	v_cvt_pk_bf16_f32 v136, v56, v57
	v_cvt_pk_bf16_f32 v137, v58, v59
	v_mov_b32_e32 v146, v3
	v_mov_b32_e32 v147, v3
	v_mfma_f32_16x16x32_bf16 v[138:141], v[88:91], v[134:137], v[138:141]
	v_add_u32_e32 v182, s70, v237
	v_sub_u32_e32 v183, s54, v237
	v_add_u32_e32 v182, -16, v182
	v_add_u32_e32 v183, 3, v183
	v_cndmask_b32_e64 v180, v183, v182, s[38:39]
	v_ashrrev_i32_e32 v181, 31, v180
	v_lshl_add_u64 v[180:181], s[20:21], 0, v[180:181]
	v_lshlrev_b64 v[180:181], 11, v[180:181]
	v_lshlrev_b32_e32 v182, 3, v246
	v_or_b32_e32 v180, v180, v182
	v_lshl_add_u64 v[180:181], v[154:155], 0, v[180:181]

	v_cvt_pk_bf16_f32 v188, v4, v5
	s_waitcnt lgkmcnt(11)
	v_mfma_f32_16x16x32_bf16 v[138:141], v[120:123], v[144:147], v[138:141]
	v_cvt_pk_bf16_f32 v189, v6, v7
	v_cvt_pk_bf16_f32 v190, v20, v21
	v_cvt_pk_bf16_f32 v191, v22, v23
	v_mfma_f32_16x16x32_bf16 v[130:133], v[130:133], v[92:95], 0

	s_nop 2
	s_nop 0
	v_cvt_pk_bf16_f32 v138, v138, v139
	v_cvt_pk_bf16_f32 v139, v140, v141
	v_mov_b32_e32 v140, v3
	v_mov_b32_e32 v141, v3
	v_mfma_f32_16x16x32_bf16 v[130:133], v[134:137], v[84:87], v[130:133]


	s_nop 0
	v_mfma_f32_16x16x32_bf16 v[138:141], v[0:3], v[138:141], 0


	s_nop 2


	s_nop 4
	v_cvt_pk_bf16_f32 v146, -v138, -v139


	v_cvt_pk_bf16_f32 v147, -v140, -v141
	v_mfma_f32_16x16x32_bf16 v[196:199], v[96:99], v[188:191], 0


	v_cvt_pk_bf16_f32 v192, v36, v37
	v_mfma_f32_16x16x32_bf16 v[130:133], v[144:147], v[108:111], v[130:133]
	v_cvt_pk_bf16_f32 v193, v38, v39
	v_cvt_pk_bf16_f32 v194, v48, v49
	v_cvt_pk_bf16_f32 v195, v50, v51
	v_mov_b32_e32 v150, v3
	v_mov_b32_e32 v151, v3
	s_nop 2
	v_cvt_pk_bf16_f32 v130, v130, v131
	v_cvt_pk_bf16_f32 v131, v132, v133
	global_store_dwordx2 v[180:181], v[130:131], off


	v_mfma_f32_16x16x32_bf16 v[196:199], v[88:91], v[192:195], v[196:199]


	s_waitcnt lgkmcnt(10)
	v_mfma_f32_16x16x32_bf16 v[196:199], v[120:123], v[148:151], v[196:199]


	s_nop 2
	s_nop 4
	v_cvt_pk_bf16_f32 v196, v196, v197
	v_cvt_pk_bf16_f32 v197, v198, v199
	v_mov_b32_e32 v198, v3
	v_mov_b32_e32 v199, v3
	v_mfma_f32_16x16x32_bf16 v[188:191], v[188:191], v[92:95], 0


	s_nop 0
	v_mfma_f32_16x16x32_bf16 v[196:199], v[0:3], v[196:199], 0


	v_mov_b32_e32 v130, v3
	v_mfma_f32_16x16x32_bf16 v[188:191], v[192:195], v[84:87], v[188:191]
	v_mov_b32_e32 v131, v3
	s_nop 2


	s_nop 1
	v_cvt_pk_bf16_f32 v150, -v196, -v197


	v_cvt_pk_bf16_f32 v151, -v198, -v199


	s_nop 1
	v_mfma_f32_16x16x32_bf16 v[188:191], v[148:151], v[108:111], v[188:191]


	s_waitcnt lgkmcnt(3)
	v_mfma_f32_16x16x32_bf16 v[4:7], v[124:127], v[148:151], v[4:7]
	ds_read_b128 v[140:143], v236 offset:25856
	ds_read_b128 v[136:139], v236 offset:25920
	s_nop 0
	s_nop 2
	v_cvt_pk_bf16_f32 v188, v188, v189
	v_cvt_pk_bf16_f32 v189, v190, v191
	global_store_dwordx2 v[180:181], v[188:189], off offset:32
	s_waitcnt lgkmcnt(4)
	v_mfma_f32_16x16x32_bf16 v[20:23], v[116:119], v[148:151], v[20:23]


	s_waitcnt lgkmcnt(3)
	v_mfma_f32_16x16x32_bf16 v[36:39], v[112:115], v[148:151], v[36:39]


	s_waitcnt lgkmcnt(2)
	v_mfma_f32_16x16x32_bf16 v[48:51], v[104:107], v[148:151], v[48:51]
	v_cvt_pk_bf16_f32 v148, v8, v9
	v_cvt_pk_bf16_f32 v149, v10, v11
	v_cvt_pk_bf16_f32 v150, v24, v25
	v_cvt_pk_bf16_f32 v151, v26, v27
	v_cvt_pk_bf16_f32 v188, v40, v41
	v_cvt_pk_bf16_f32 v189, v42, v43
	v_mfma_f32_16x16x32_bf16 v[192:195], v[96:99], v[148:151], 0
	v_cvt_pk_bf16_f32 v190, v52, v53
	v_cvt_pk_bf16_f32 v191, v54, v55

	v_mfma_f32_16x16x32_bf16 v[148:151], v[148:151], v[92:95], 0
	ds_read_b128 v[132:135], v236 offset:25984
	s_waitcnt lgkmcnt(2)
	v_mul_f32_e32 v6, v142, v6
	v_mul_f32_e32 v7, v143, v7
	v_mul_f32_e32 v4, v140, v4
	v_mul_f32_e32 v5, v141, v5
	v_mfma_f32_16x16x32_bf16 v[192:195], v[88:91], v[188:191], v[192:195]
	s_waitcnt lgkmcnt(1)
	v_mul_f32_e32 v22, v138, v22
	v_mul_f32_e32 v23, v139, v23
	v_mul_f32_e32 v20, v136, v20
	v_mul_f32_e32 v21, v137, v21
	v_mfma_f32_16x16x32_bf16 v[192:195], v[120:123], v[128:131], v[192:195]
	v_mfma_f32_16x16x32_bf16 v[148:151], v[188:191], v[84:87], v[148:151]
	v_mfma_f32_16x16x32_bf16 v[16:19], v[124:127], v[144:147], v[16:19]
	s_nop 5
	v_cvt_pk_bf16_f32 v192, v192, v193
	v_cvt_pk_bf16_f32 v193, v194, v195
	v_mov_b32_e32 v194, v3
	v_mov_b32_e32 v195, v3
	v_mfma_f32_16x16x32_bf16 v[28:31], v[116:119], v[144:147], v[28:31]
	v_mul_f32_e64 v18, v18, v142
	v_mul_f32_e64 v19, v19, v143
	v_mul_f32_e32 v16, v16, v140
	v_mul_f32_e32 v17, v17, v141
	v_mfma_f32_16x16x32_bf16 v[192:195], v[0:3], v[192:195], 0
	v_mfma_f32_16x16x32_bf16 v[32:35], v[112:115], v[144:147], v[32:35]
	s_nop 2
	v_mul_f32_e64 v30, v30, v138
	v_mul_f32_e64 v31, v31, v139
	s_nop 1


	v_cvt_pk_bf16_f32 v130, -v192, -v193


	v_cvt_pk_bf16_f32 v131, -v194, -v195
	v_mov_b32_e32 v103, v3
	v_mfma_f32_16x16x32_bf16 v[56:59], v[104:107], v[144:147], v[56:59]
	ds_read_b128 v[144:147], v236 offset:26048
	v_mul_f32_e32 v28, v28, v136
	v_mul_f32_e32 v29, v29, v137
	s_waitcnt lgkmcnt(1)
	v_mul_f32_e32 v34, v34, v134
	v_mul_f32_e32 v35, v35, v135
	v_mfma_f32_16x16x32_bf16 v[148:151], v[128:131], v[108:111], v[148:151]
	v_mul_f32_e64 v32, v32, v132
	v_mul_f32_e64 v33, v33, v133
	s_waitcnt lgkmcnt(0)
	v_mul_f32_e32 v58, v58, v146
	v_mul_f32_e32 v59, v59, v147
	v_mul_f32_e32 v56, v56, v144
	v_mul_f32_e32 v57, v57, v145
	v_mfma_f32_16x16x32_bf16 v[8:11], v[124:127], v[128:131], v[8:11]
	v_mul_f32_e64 v38, v134, v38
	v_mul_f32_e64 v39, v135, v39
	v_cvt_pk_bf16_f32 v148, v148, v149
	v_cvt_pk_bf16_f32 v149, v150, v151
	global_store_dwordx2 v[180:181], v[148:149], off offset:64

	v_mfma_f32_16x16x32_bf16 v[24:27], v[116:119], v[128:131], v[24:27]


	v_mfma_f32_16x16x32_bf16 v[40:43], v[112:115], v[128:131], v[40:43]


	v_cvt_pk_bf16_f32 v148, v44, v45
	v_mfma_f32_16x16x32_bf16 v[52:55], v[104:107], v[128:131], v[52:55]
	v_cvt_pk_bf16_f32 v128, v12, v13
	v_cvt_pk_bf16_f32 v129, v14, v15
	v_cvt_pk_bf16_f32 v130, v60, v61
	v_cvt_pk_bf16_f32 v131, v62, v63
	v_cvt_pk_bf16_f32 v149, v46, v47
	v_cvt_pk_bf16_f32 v150, v64, v65
	v_mfma_f32_16x16x32_bf16 v[96:99], v[96:99], v[128:131], 0
	v_cvt_pk_bf16_f32 v151, v66, v67

	v_mov_b32_e32 v102, v3
	s_nop 0
	v_mfma_f32_16x16x32_bf16 v[88:91], v[88:91], v[148:151], v[96:99]
	v_mul_f32_e64 v36, v132, v36
	v_mul_f32_e64 v37, v133, v37
	v_mul_f32_e32 v50, v146, v50
	v_mul_f32_e32 v51, v147, v51
	v_mul_f32_e32 v48, v144, v48
	v_mul_f32_e32 v49, v145, v49
	v_mfma_f32_16x16x32_bf16 v[88:91], v[120:123], v[100:103], v[88:91]
	v_mul_f32_e64 v10, v142, v10
	v_mul_f32_e64 v11, v143, v11
	v_mul_f32_e32 v8, v140, v8
	v_mul_f32_e32 v9, v141, v9
	v_mul_f32_e32 v26, v138, v26
	v_mul_f32_e32 v27, v139, v27
	v_mul_f32_e32 v24, v136, v24
	v_mul_f32_e32 v25, v137, v25
	v_mul_f32_e32 v42, v134, v42
	v_mul_f32_e32 v43, v135, v43

	v_cvt_pk_bf16_f32 v88, v88, v89
	v_cvt_pk_bf16_f32 v89, v90, v91
	v_mov_b32_e32 v90, v3
	v_mov_b32_e32 v91, v3
	v_mul_f32_e32 v40, v132, v40
	v_mul_f32_e32 v41, v133, v41
	v_mul_f32_e32 v54, v146, v54
	v_mul_f32_e32 v55, v147, v55
	v_mfma_f32_16x16x32_bf16 v[88:91], v[0:3], v[88:91], 0
	v_mul_f32_e64 v52, v144, v52
	v_mul_f32_e64 v53, v145, v53
	s_nop 5


	v_cvt_pk_bf16_f32 v102, -v88, -v89
	v_xor_b32_e32 v0, 0x80000000, v90
	v_xor_b32_e32 v1, 0x80000000, v91
	v_mfma_f32_16x16x32_bf16 v[88:91], v[128:131], v[92:95], 0
	v_cvt_pk_bf16_f32 v103, v0, v1
	v_mfma_f32_16x16x32_bf16 v[84:87], v[148:151], v[84:87], v[88:91]
	s_nop 0
	v_mfma_f32_16x16x32_bf16 v[84:87], v[100:103], v[108:111], v[84:87]
	v_mfma_f32_16x16x32_bf16 v[12:15], v[124:127], v[100:103], v[12:15]
	v_mfma_f32_16x16x32_bf16 v[60:63], v[116:119], v[100:103], v[60:63]
	s_nop 5
	v_cvt_pk_bf16_f32 v84, v84, v85
	v_cvt_pk_bf16_f32 v85, v86, v87
	global_store_dwordx2 v[180:181], v[84:85], off offset:96


	v_mfma_f32_16x16x32_bf16 v[44:47], v[112:115], v[100:103], v[44:47]


	v_mfma_f32_16x16x32_bf16 v[64:67], v[104:107], v[100:103], v[64:67]

	v_mul_f32_e32 v14, v142, v14
	v_mul_f32_e32 v15, v143, v15
	v_mul_f32_e32 v12, v140, v12
	v_mul_f32_e32 v13, v141, v13
	v_mul_f32_e32 v62, v138, v62
	v_mul_f32_e32 v63, v139, v63
	v_mul_f32_e32 v60, v136, v60
	v_mul_f32_e32 v61, v137, v61
	v_mul_f32_e32 v46, v134, v46
	v_mul_f32_e32 v47, v135, v47
	v_mul_f32_e32 v44, v132, v44
	v_mul_f32_e32 v45, v133, v45

	v_mul_f32_e32 v66, v146, v66
	v_mul_f32_e32 v67, v147, v67
	v_mul_f32_e32 v64, v144, v64
	v_mul_f32_e32 v65, v145, v65

	s_setprio 0
	s_add_i32 s55, s55, 16
	s_add_i32 s54, s54, -16
	s_waitcnt vmcnt(4)
	v_mov_b64_e32 v[86:87], v[82:83]
	s_cmpk_eq_i32 s55, 0x110
	v_mov_b64_e32 v[138:139], v[178:179]
	v_mov_b64_e32 v[136:137], v[170:171]
	v_mov_b64_e32 v[134:135], v[172:173]
	v_mov_b64_e32 v[132:133], v[176:177]
	v_mov_b64_e32 v[124:125], v[174:175]
	v_mov_b64_e32 v[182:183], v[164:165]
	v_mov_b64_e32 v[140:141], v[166:167]
	v_mov_b64_e32 v[0:1], v[168:169]
	v_mov_b64_e32 v[84:85], v[80:81]
	s_cbranch_scc1 .LBB0_527
